# same as previous but early barrier before last 3 MFMAs (k=3)
# speedup vs baseline: 1.0062x; 1.0004x over previous
; #define PG8_STAGE(bufoff, gbase, voff) do { _Pragma("unroll") for (int _i = 0; _i < 2; ++_i) \
;         __builtin_amdgcn_global_load_lds((const unsigned*)((const char*)(gbase) + (voff)[_i]), (LAS unsigned*)(lds + (bufoff) + ldsw + _i * 8192), 16, 0, 0); } while (0)
; #define PG8_LDA(dst, b, h) do { _Pragma("unroll") for (int m = 0; m < 4; ++m) _Pragma("unroll") for (int k = 0; k < 2; ++k) dst[m][k] = *(const LAS bf16x8*)(lds + PG8_SA(b, h) + aoff + m * 2048 + k * 1024); } while (0)
; #define PG8_LDB(dst, b, h) do { _Pragma("unroll") for (int n = 0; n < 2; ++n) _Pragma("unroll") for (int k = 0; k < 2; ++k) dst[n][k] = *(const LAS bf16x8*)(lds + PG8_SB(b, h) + boff + n * 2048 + k * 1024); } while (0)
; #define PG8_MMA(ai, bj, At, Bt) do { __builtin_amdgcn_s_setprio(1); _Pragma("unroll") for (int m = 0; m < 4; ++m) _Pragma("unroll") for (int n = 0; n < 2; ++n) _Pragma("unroll") for (int k = 0; k < 2; ++k) \
;         acc[ai][bj][m][n] = __builtin_amdgcn_mfma_f32_16x16x32_bf16(Bt[n][k], At[m][k], acc[ai][bj][m][n], 0, 0, 0); __builtin_amdgcn_s_setprio(0); } while (0)
; #define PG8_WAIT_V(n) asm volatile("s_waitcnt vmcnt(" #n ")" ::: "memory")
; #define PG8_WAIT_L(n) asm volatile("s_waitcnt lgkmcnt(" #n ")" ::: "memory")
; #define PG8_BAR __builtin_amdgcn_s_barrier()
; #define PG8_SCHED __builtin_amdgcn_sched_barrier(0)
; template <class Epi>
; __device__ __forceinline__ void gemm_phase(LAS unsigned char* lds, const Gemm g, const TileOrder& S, const Epi& E) {
;     ...
;             const bool last = (t == nt - 2);
;             const char* a1 = cA + (size_t)(t + 1) * kstepA;
;             const char* a2 = last ? nA : cA + (size_t)(t + 2) * kstepA; const char* b2 = last ? nB : cB + (size_t)(t + 2) * kstep;
;             const char* a3 = a2 + kstepA; const char* b3 = b2 + kstep;
;             PG8_LDB(B0, 0, 0); PG8_LDB(B1, 0, 1); PG8_SCHED; PG8_LDA(At, 0, 0); PG8_STAGE(PG8_SA(1, 1), a1 + hstepA, voffA);
;             PG8_WAIT_V(8); PG8_WAIT_L(0); PG8_BAR; PG8_MMA(0, 0, At, B0); PG8_MMA(0, 1, At, B1); PG8_BAR; PG8_SCHED;
;             PG8_LDA(At, 0, 1); PG8_STAGE(PG8_SB(0, 0), b2, voffB); PG8_STAGE(PG8_SB(0, 1), b2 + hstepB, voffB); PG8_STAGE(PG8_SA(0, 0), a2, voffA);
;             PG8_WAIT_V(8); PG8_WAIT_L(0); PG8_BAR; PG8_MMA(1, 0, At, B0); PG8_MMA(1, 1, At, B1); PG8_BAR; PG8_SCHED;
.LBB0_51:
	s_mov_b32 s6, 0x10000
	v_add_u32_e32 v0, s6, v186
	s_mov_b32 s12, 0x14000
	ds_read_b128 v[130:133], v0
	ds_read_b128 v[134:137], v0 offset:1024
	ds_read_b128 v[138:141], v0 offset:2048
	ds_read_b128 v[142:145], v0 offset:3072
	v_add_u32_e32 v0, s12, v186
	ds_read_b128 v[154:157], v0
	ds_read_b128 v[158:161], v0 offset:1024
	ds_read_b128 v[162:165], v0 offset:2048
	ds_read_b128 v[166:169], v0 offset:3072
	ds_read_b128 v[170:173], v187
	ds_read_b128 v[174:177], v187 offset:1024
	ds_read_b128 v[178:181], v187 offset:2048
	ds_read_b128 v[188:191], v187 offset:3072
	ds_read_b128 v[192:195], v187 offset:4096
	ds_read_b128 v[196:199], v187 offset:5120
	ds_read_b128 v[200:203], v187 offset:6144
	ds_read_b128 v[204:207], v187 offset:7168
	s_add_u32 s2, s28, 0xfff80080
	s_addc_u32 s3, s29, -1
	s_cmp_eq_u32 s72, 28
	s_cselect_b32 s31, s49, s3
	s_cselect_b32 s30, s68, s2
	s_cselect_b32 s3, s47, s71
	s_cselect_b32 s2, s69, s70
	s_waitcnt lgkmcnt(0)
	s_add_i32 m0, s56, 0xc000
	s_nop 0
	global_load_lds_dwordx4 v150, s[28:29]
	s_add_i32 m0, s56, 0xe000
	s_nop 0
	global_load_lds_dwordx4 v152, s[28:29]
	s_waitcnt vmcnt(8)
	s_waitcnt lgkmcnt(0)
	s_barrier
	s_setprio 1
	s_waitcnt lgkmcnt(0)
	v_mfma_f32_16x16x32_bf16 v[126:129], v[130:133], v[170:173], v[126:129]
	v_mfma_f32_16x16x32_bf16 v[118:121], v[138:141], v[170:173], v[118:121]
	v_mfma_f32_16x16x32_bf16 v[110:113], v[130:133], v[178:181], v[110:113]
	v_mfma_f32_16x16x32_bf16 v[102:105], v[138:141], v[178:181], v[102:105]
	v_mfma_f32_16x16x32_bf16 v[94:97], v[130:133], v[192:195], v[94:97]
	v_mfma_f32_16x16x32_bf16 v[86:89], v[138:141], v[192:195], v[86:89]
	v_mfma_f32_16x16x32_bf16 v[78:81], v[130:133], v[200:203], v[78:81]
	v_mfma_f32_16x16x32_bf16 v[70:73], v[138:141], v[200:203], v[70:73]
	v_mfma_f32_16x16x32_bf16 v[126:129], v[134:137], v[174:177], v[126:129]
	v_mfma_f32_16x16x32_bf16 v[118:121], v[142:145], v[174:177], v[118:121]
	v_mfma_f32_16x16x32_bf16 v[110:113], v[134:137], v[188:191], v[110:113]
	v_mfma_f32_16x16x32_bf16 v[102:105], v[142:145], v[188:191], v[102:105]
	v_mfma_f32_16x16x32_bf16 v[94:97], v[134:137], v[196:199], v[94:97]
	v_mfma_f32_16x16x32_bf16 v[86:89], v[142:145], v[196:199], v[86:89]
	v_mfma_f32_16x16x32_bf16 v[78:81], v[134:137], v[204:207], v[78:81]
	v_mfma_f32_16x16x32_bf16 v[70:73], v[142:145], v[204:207], v[70:73]
	s_setprio 0
	s_setprio 1
	v_mfma_f32_16x16x32_bf16 v[122:125], v[154:157], v[170:173], v[122:125]
	v_mfma_f32_16x16x32_bf16 v[114:117], v[162:165], v[170:173], v[114:117]
	v_mfma_f32_16x16x32_bf16 v[106:109], v[154:157], v[178:181], v[106:109]
	v_mfma_f32_16x16x32_bf16 v[98:101], v[162:165], v[178:181], v[98:101]
	v_mfma_f32_16x16x32_bf16 v[90:93], v[154:157], v[192:195], v[90:93]
	v_mfma_f32_16x16x32_bf16 v[82:85], v[162:165], v[192:195], v[82:85]
	v_mfma_f32_16x16x32_bf16 v[74:77], v[154:157], v[200:203], v[74:77]
	v_mfma_f32_16x16x32_bf16 v[66:69], v[162:165], v[200:203], v[66:69]
	v_mfma_f32_16x16x32_bf16 v[122:125], v[158:161], v[174:177], v[122:125]
	v_mfma_f32_16x16x32_bf16 v[114:117], v[166:169], v[174:177], v[114:117]
	v_mfma_f32_16x16x32_bf16 v[106:109], v[158:161], v[188:191], v[106:109]
	v_mfma_f32_16x16x32_bf16 v[98:101], v[166:169], v[188:191], v[98:101]
	v_mfma_f32_16x16x32_bf16 v[90:93], v[158:161], v[196:199], v[90:93]
	s_setprio 2
	s_barrier
	v_mfma_f32_16x16x32_bf16 v[82:85], v[166:169], v[196:199], v[82:85]
	v_mfma_f32_16x16x32_bf16 v[74:77], v[158:161], v[204:207], v[74:77]
	v_mfma_f32_16x16x32_bf16 v[66:69], v[166:169], v[204:207], v[66:69]
	s_setprio 0
	s_add_i32 s6, s6, s55
	v_lshl_add_u64 v[182:183], s[2:3], 0, v[148:149]
	s_mov_b32 m0, s6
	ds_read_b128 v[170:173], v187 offset:16384
	ds_read_b128 v[174:177], v187 offset:17408
	ds_read_b128 v[178:181], v187 offset:18432
	ds_read_b128 v[188:191], v187 offset:19456
	ds_read_b128 v[192:195], v187 offset:20480
	ds_read_b128 v[196:199], v187 offset:21504
	ds_read_b128 v[200:203], v187 offset:22528
	ds_read_b128 v[204:207], v187 offset:23552
	global_load_lds_dwordx4 v[182:183], off
	s_add_i32 m0, s6, 0x2000
	s_add_u32 s14, s2, 0x80000
	v_lshl_add_u64 v[208:209], s[2:3], 0, v[146:147]
	s_addc_u32 s15, s3, 0
	s_add_i32 s6, s12, s55
	global_load_lds_dwordx4 v[208:209], off
	s_mov_b32 m0, s6
	v_lshl_add_u64 v[212:213], s[30:31], 0, v[146:147]
	global_load_lds_dwordx4 v148, s[14:15]
	s_add_i32 m0, s6, 0x2000
	s_nop 0
	global_load_lds_dwordx4 v146, s[14:15]
	v_lshl_add_u64 v[210:211], s[30:31], 0, v[148:149]
	s_mov_b32 m0, s56
	s_nop 0
	global_load_lds_dwordx4 v[210:211], off
	s_mov_b32 m0, s57
	s_nop 0
	global_load_lds_dwordx4 v[212:213], off
	s_waitcnt vmcnt(8)
	s_waitcnt lgkmcnt(0)
	s_barrier
; #define PG8_STAGE(bufoff, gbase, voff) do { _Pragma("unroll") for (int _i = 0; _i < 2; ++_i) \
;         __builtin_amdgcn_global_load_lds((const unsigned*)((const char*)(gbase) + (voff)[_i]), (LAS unsigned*)(lds + (bufoff) + ldsw + _i * 8192), 16, 0, 0); } while (0)
; #define PG8_LDA(dst, b, h) do { _Pragma("unroll") for (int m = 0; m < 4; ++m) _Pragma("unroll") for (int k = 0; k < 2; ++k) dst[m][k] = *(const LAS bf16x8*)(lds + PG8_SA(b, h) + aoff + m * 2048 + k * 1024); } while (0)
; #define PG8_LDB(dst, b, h) do { _Pragma("unroll") for (int n = 0; n < 2; ++n) _Pragma("unroll") for (int k = 0; k < 2; ++k) dst[n][k] = *(const LAS bf16x8*)(lds + PG8_SB(b, h) + boff + n * 2048 + k * 1024); } while (0)
; #define PG8_MMA(ai, bj, At, Bt) do { __builtin_amdgcn_s_setprio(1); _Pragma("unroll") for (int m = 0; m < 4; ++m) _Pragma("unroll") for (int n = 0; n < 2; ++n) _Pragma("unroll") for (int k = 0; k < 2; ++k) \
;         acc[ai][bj][m][n] = __builtin_amdgcn_mfma_f32_16x16x32_bf16(Bt[n][k], At[m][k], acc[ai][bj][m][n], 0, 0, 0); __builtin_amdgcn_s_setprio(0); } while (0)
; #define PG8_WAIT_V(n) asm volatile("s_waitcnt vmcnt(" #n ")" ::: "memory")
; #define PG8_WAIT_L(n) asm volatile("s_waitcnt lgkmcnt(" #n ")" ::: "memory")
; #define PG8_BAR __builtin_amdgcn_s_barrier()
; #define PG8_SCHED __builtin_amdgcn_sched_barrier(0)
; template <class Epi>
; __device__ __forceinline__ void gemm_phase(LAS unsigned char* lds, const Gemm g, const TileOrder& S, const Epi& E) {
;     ...
;             PG8_WAIT_V(8); PG8_WAIT_L(0); PG8_BAR; PG8_MMA(1, 0, At, B0); PG8_MMA(1, 1, At, B1); PG8_BAR; PG8_SCHED;
;             PG8_LDB(B0, 1, 0); PG8_LDB(B1, 1, 1); PG8_SCHED; PG8_LDA(At, 1, 0); PG8_STAGE(PG8_SA(0, 1), a2 + hstepA, voffA);
;             PG8_WAIT_V(8); PG8_WAIT_L(0); PG8_BAR; PG8_MMA(0, 0, At, B0); PG8_MMA(0, 1, At, B1); PG8_BAR; PG8_SCHED;
	s_setprio 1
	s_waitcnt lgkmcnt(0)
	v_mfma_f32_16x16x32_bf16 v[62:65], v[130:133], v[170:173], v[62:65]
	v_mfma_f32_16x16x32_bf16 v[54:57], v[138:141], v[170:173], v[54:57]
	v_mfma_f32_16x16x32_bf16 v[46:49], v[130:133], v[178:181], v[46:49]
	v_mfma_f32_16x16x32_bf16 v[38:41], v[138:141], v[178:181], v[38:41]
	v_mfma_f32_16x16x32_bf16 v[30:33], v[130:133], v[192:195], v[30:33]
	v_mfma_f32_16x16x32_bf16 v[22:25], v[138:141], v[192:195], v[22:25]
	v_mfma_f32_16x16x32_bf16 v[14:17], v[130:133], v[200:203], v[14:17]
	v_mfma_f32_16x16x32_bf16 v[6:9], v[138:141], v[200:203], v[6:9]
	v_mfma_f32_16x16x32_bf16 v[62:65], v[134:137], v[174:177], v[62:65]
	v_mfma_f32_16x16x32_bf16 v[54:57], v[142:145], v[174:177], v[54:57]
	v_mfma_f32_16x16x32_bf16 v[46:49], v[134:137], v[188:191], v[46:49]
	v_mfma_f32_16x16x32_bf16 v[38:41], v[142:145], v[188:191], v[38:41]
	v_mfma_f32_16x16x32_bf16 v[30:33], v[134:137], v[196:199], v[30:33]
	v_mfma_f32_16x16x32_bf16 v[22:25], v[142:145], v[196:199], v[22:25]
	v_mfma_f32_16x16x32_bf16 v[14:17], v[134:137], v[204:207], v[14:17]
	v_mfma_f32_16x16x32_bf16 v[6:9], v[142:145], v[204:207], v[6:9]
	s_setprio 0
	s_setprio 1
	v_mfma_f32_16x16x32_bf16 v[58:61], v[154:157], v[170:173], v[58:61]
	v_mfma_f32_16x16x32_bf16 v[50:53], v[162:165], v[170:173], v[50:53]
	v_mfma_f32_16x16x32_bf16 v[42:45], v[154:157], v[178:181], v[42:45]
	v_mfma_f32_16x16x32_bf16 v[34:37], v[162:165], v[178:181], v[34:37]
	v_mfma_f32_16x16x32_bf16 v[26:29], v[154:157], v[192:195], v[26:29]
	v_mfma_f32_16x16x32_bf16 v[18:21], v[162:165], v[192:195], v[18:21]
	v_mfma_f32_16x16x32_bf16 v[10:13], v[154:157], v[200:203], v[10:13]
	v_mfma_f32_16x16x32_bf16 v[2:5], v[162:165], v[200:203], v[2:5]
	v_mfma_f32_16x16x32_bf16 v[58:61], v[158:161], v[174:177], v[58:61]
	v_mfma_f32_16x16x32_bf16 v[50:53], v[166:169], v[174:177], v[50:53]
	v_mfma_f32_16x16x32_bf16 v[42:45], v[158:161], v[188:191], v[42:45]
	v_mfma_f32_16x16x32_bf16 v[34:37], v[166:169], v[188:191], v[34:37]
	v_mfma_f32_16x16x32_bf16 v[26:29], v[158:161], v[196:199], v[26:29]
	s_setprio 2
	s_barrier
	v_mfma_f32_16x16x32_bf16 v[18:21], v[166:169], v[196:199], v[18:21]
	v_mfma_f32_16x16x32_bf16 v[10:13], v[158:161], v[204:207], v[10:13]
	v_mfma_f32_16x16x32_bf16 v[2:5], v[166:169], v[204:207], v[2:5]
	s_setprio 0
	s_add_i32 s6, 0, 0x18000
	v_add_u32_e32 v0, s6, v186
	s_add_i32 s12, 0, 0x1c000
	ds_read_b128 v[130:133], v0
	ds_read_b128 v[134:137], v0 offset:1024
	ds_read_b128 v[138:141], v0 offset:2048
	ds_read_b128 v[142:145], v0 offset:3072
	v_add_u32_e32 v0, s12, v186
	ds_read_b128 v[154:157], v0
	ds_read_b128 v[158:161], v0 offset:1024
	ds_read_b128 v[162:165], v0 offset:2048
	ds_read_b128 v[166:169], v0 offset:3072
	s_add_u32 s14, s30, 0x80000
	s_addc_u32 s15, s31, 0
	s_mov_b32 m0, s58
	ds_read_b128 v[170:173], v187 offset:32768
	ds_read_b128 v[174:177], v187 offset:33792
	ds_read_b128 v[178:181], v187 offset:34816
	ds_read_b128 v[188:191], v187 offset:35840
	ds_read_b128 v[192:195], v187 offset:36864
	ds_read_b128 v[196:199], v187 offset:37888
	ds_read_b128 v[200:203], v187 offset:38912
	ds_read_b128 v[204:207], v187 offset:39936
	global_load_lds_dwordx4 v148, s[14:15]
	s_mov_b32 m0, s59
	s_nop 0
	global_load_lds_dwordx4 v146, s[14:15]
	s_waitcnt vmcnt(8)
	s_waitcnt lgkmcnt(0)
	s_barrier
	s_setprio 1
	s_waitcnt lgkmcnt(0)
	v_mfma_f32_16x16x32_bf16 v[126:129], v[130:133], v[170:173], v[126:129]
	v_mfma_f32_16x16x32_bf16 v[118:121], v[138:141], v[170:173], v[118:121]
	v_mfma_f32_16x16x32_bf16 v[110:113], v[130:133], v[178:181], v[110:113]
	v_mfma_f32_16x16x32_bf16 v[102:105], v[138:141], v[178:181], v[102:105]
	v_mfma_f32_16x16x32_bf16 v[94:97], v[130:133], v[192:195], v[94:97]
	v_mfma_f32_16x16x32_bf16 v[86:89], v[138:141], v[192:195], v[86:89]
	v_mfma_f32_16x16x32_bf16 v[78:81], v[130:133], v[200:203], v[78:81]
	v_mfma_f32_16x16x32_bf16 v[70:73], v[138:141], v[200:203], v[70:73]
	v_mfma_f32_16x16x32_bf16 v[126:129], v[134:137], v[174:177], v[126:129]
	v_mfma_f32_16x16x32_bf16 v[118:121], v[142:145], v[174:177], v[118:121]
	v_mfma_f32_16x16x32_bf16 v[110:113], v[134:137], v[188:191], v[110:113]
	v_mfma_f32_16x16x32_bf16 v[102:105], v[142:145], v[188:191], v[102:105]
	v_mfma_f32_16x16x32_bf16 v[94:97], v[134:137], v[196:199], v[94:97]
	v_mfma_f32_16x16x32_bf16 v[86:89], v[142:145], v[196:199], v[86:89]
	v_mfma_f32_16x16x32_bf16 v[78:81], v[134:137], v[204:207], v[78:81]
	v_mfma_f32_16x16x32_bf16 v[70:73], v[142:145], v[204:207], v[70:73]
	s_setprio 0
	s_setprio 1
	v_mfma_f32_16x16x32_bf16 v[122:125], v[154:157], v[170:173], v[122:125]
	v_mfma_f32_16x16x32_bf16 v[114:117], v[162:165], v[170:173], v[114:117]
	v_mfma_f32_16x16x32_bf16 v[106:109], v[154:157], v[178:181], v[106:109]
	v_mfma_f32_16x16x32_bf16 v[98:101], v[162:165], v[178:181], v[98:101]
	v_mfma_f32_16x16x32_bf16 v[90:93], v[154:157], v[192:195], v[90:93]
	v_mfma_f32_16x16x32_bf16 v[82:85], v[162:165], v[192:195], v[82:85]
	v_mfma_f32_16x16x32_bf16 v[74:77], v[154:157], v[200:203], v[74:77]
	v_mfma_f32_16x16x32_bf16 v[66:69], v[162:165], v[200:203], v[66:69]
	v_mfma_f32_16x16x32_bf16 v[122:125], v[158:161], v[174:177], v[122:125]
	v_mfma_f32_16x16x32_bf16 v[114:117], v[166:169], v[174:177], v[114:117]
	v_mfma_f32_16x16x32_bf16 v[106:109], v[158:161], v[188:191], v[106:109]
	v_mfma_f32_16x16x32_bf16 v[98:101], v[166:169], v[188:191], v[98:101]
	v_mfma_f32_16x16x32_bf16 v[90:93], v[158:161], v[196:199], v[90:93]
	s_setprio 2
	s_barrier
; #define PG8_STAGE(bufoff, gbase, voff) do { _Pragma("unroll") for (int _i = 0; _i < 2; ++_i) \
;         __builtin_amdgcn_global_load_lds((const unsigned*)((const char*)(gbase) + (voff)[_i]), (LAS unsigned*)(lds + (bufoff) + ldsw + _i * 8192), 16, 0, 0); } while (0)
; #define PG8_LDA(dst, b, h) do { _Pragma("unroll") for (int m = 0; m < 4; ++m) _Pragma("unroll") for (int k = 0; k < 2; ++k) dst[m][k] = *(const LAS bf16x8*)(lds + PG8_SA(b, h) + aoff + m * 2048 + k * 1024); } while (0)
; #define PG8_MMA(ai, bj, At, Bt) do { __builtin_amdgcn_s_setprio(1); _Pragma("unroll") for (int m = 0; m < 4; ++m) _Pragma("unroll") for (int n = 0; n < 2; ++n) _Pragma("unroll") for (int k = 0; k < 2; ++k) \
;         acc[ai][bj][m][n] = __builtin_amdgcn_mfma_f32_16x16x32_bf16(Bt[n][k], At[m][k], acc[ai][bj][m][n], 0, 0, 0); __builtin_amdgcn_s_setprio(0); } while (0)
; #define PG8_WAIT_V(n) asm volatile("s_waitcnt vmcnt(" #n ")" ::: "memory")
; #define PG8_WAIT_L(n) asm volatile("s_waitcnt lgkmcnt(" #n ")" ::: "memory")
; #define PG8_BAR __builtin_amdgcn_s_barrier()
; #define PG8_SCHED __builtin_amdgcn_sched_barrier(0)
; template <class Epi>
; __device__ __forceinline__ void gemm_phase(LAS unsigned char* lds, const Gemm g, const TileOrder& S, const Epi& E) {
;     ...
;             PG8_WAIT_V(8); PG8_WAIT_L(0); PG8_BAR; PG8_MMA(0, 0, At, B0); PG8_MMA(0, 1, At, B1); PG8_BAR; PG8_SCHED;
;             PG8_LDA(At, 1, 1); PG8_STAGE(PG8_SB(1, 0), b3, voffB); PG8_STAGE(PG8_SB(1, 1), b3 + hstepB, voffB); PG8_STAGE(PG8_SA(1, 0), a3, voffA);
;             PG8_WAIT_V(8); PG8_WAIT_L(0); PG8_BAR; PG8_MMA(1, 0, At, B0); PG8_MMA(1, 1, At, B1); PG8_BAR; PG8_SCHED;
;         }
;         if (wr == 0) PG8_BAR;
	v_mfma_f32_16x16x32_bf16 v[82:85], v[166:169], v[196:199], v[82:85]
	v_mfma_f32_16x16x32_bf16 v[74:77], v[158:161], v[204:207], v[74:77]
	v_mfma_f32_16x16x32_bf16 v[66:69], v[166:169], v[204:207], v[66:69]
	s_setprio 0
	s_add_i32 s6, s6, s55
	v_lshl_add_u64 v[182:183], v[182:183], 0, s[34:35]
	s_mov_b32 m0, s6
	ds_read_b128 v[170:173], v187 offset:49152
	ds_read_b128 v[174:177], v187 offset:50176
	ds_read_b128 v[178:181], v187 offset:51200
	ds_read_b128 v[188:191], v187 offset:52224
	ds_read_b128 v[192:195], v187 offset:53248
	ds_read_b128 v[196:199], v187 offset:54272
	ds_read_b128 v[200:203], v187 offset:55296
	ds_read_b128 v[204:207], v187 offset:56320
	global_load_lds_dwordx4 v[182:183], off
	s_add_i32 m0, s6, 0x2000
	s_add_u32 s2, s2, 0x80080
	v_lshl_add_u64 v[182:183], v[208:209], 0, s[34:35]
	s_addc_u32 s3, s3, 0
	s_add_i32 s6, s12, s55
	global_load_lds_dwordx4 v[182:183], off
	s_mov_b32 m0, s6
	s_nop 0
	global_load_lds_dwordx4 v148, s[2:3]
	v_lshl_add_u64 v[182:183], s[2:3], 0, v[146:147]
	s_add_i32 m0, s6, 0x2000
	s_nop 0
	global_load_lds_dwordx4 v[182:183], off
	v_lshl_add_u64 v[182:183], v[210:211], 0, s[34:35]
	s_mov_b32 m0, s61
	s_nop 0
	global_load_lds_dwordx4 v[182:183], off
	v_lshl_add_u64 v[182:183], v[212:213], 0, s[34:35]
	s_mov_b32 m0, s62
	s_nop 0
	global_load_lds_dwordx4 v[182:183], off
	s_waitcnt vmcnt(8)
	s_waitcnt lgkmcnt(0)
	s_barrier
	s_setprio 1
	s_waitcnt lgkmcnt(0)
	v_mfma_f32_16x16x32_bf16 v[62:65], v[130:133], v[170:173], v[62:65]
	v_mfma_f32_16x16x32_bf16 v[54:57], v[138:141], v[170:173], v[54:57]
	v_mfma_f32_16x16x32_bf16 v[46:49], v[130:133], v[178:181], v[46:49]
	v_mfma_f32_16x16x32_bf16 v[38:41], v[138:141], v[178:181], v[38:41]
	v_mfma_f32_16x16x32_bf16 v[30:33], v[130:133], v[192:195], v[30:33]
	v_mfma_f32_16x16x32_bf16 v[22:25], v[138:141], v[192:195], v[22:25]
	v_mfma_f32_16x16x32_bf16 v[14:17], v[130:133], v[200:203], v[14:17]
	v_mfma_f32_16x16x32_bf16 v[6:9], v[138:141], v[200:203], v[6:9]
	v_mfma_f32_16x16x32_bf16 v[62:65], v[134:137], v[174:177], v[62:65]
	v_mfma_f32_16x16x32_bf16 v[54:57], v[142:145], v[174:177], v[54:57]
	v_mfma_f32_16x16x32_bf16 v[46:49], v[134:137], v[188:191], v[46:49]
	v_mfma_f32_16x16x32_bf16 v[38:41], v[142:145], v[188:191], v[38:41]
	v_mfma_f32_16x16x32_bf16 v[30:33], v[134:137], v[196:199], v[30:33]
	v_mfma_f32_16x16x32_bf16 v[22:25], v[142:145], v[196:199], v[22:25]
	v_mfma_f32_16x16x32_bf16 v[14:17], v[134:137], v[204:207], v[14:17]
	v_mfma_f32_16x16x32_bf16 v[6:9], v[142:145], v[204:207], v[6:9]
	s_setprio 0
	s_setprio 1
	v_mfma_f32_16x16x32_bf16 v[58:61], v[154:157], v[170:173], v[58:61]
	v_mfma_f32_16x16x32_bf16 v[50:53], v[162:165], v[170:173], v[50:53]
	v_mfma_f32_16x16x32_bf16 v[42:45], v[154:157], v[178:181], v[42:45]
	v_mfma_f32_16x16x32_bf16 v[34:37], v[162:165], v[178:181], v[34:37]
	v_mfma_f32_16x16x32_bf16 v[26:29], v[154:157], v[192:195], v[26:29]
	v_mfma_f32_16x16x32_bf16 v[18:21], v[162:165], v[192:195], v[18:21]
	v_mfma_f32_16x16x32_bf16 v[10:13], v[154:157], v[200:203], v[10:13]
	v_mfma_f32_16x16x32_bf16 v[2:5], v[162:165], v[200:203], v[2:5]
	v_mfma_f32_16x16x32_bf16 v[58:61], v[158:161], v[174:177], v[58:61]
	v_mfma_f32_16x16x32_bf16 v[50:53], v[166:169], v[174:177], v[50:53]
	v_mfma_f32_16x16x32_bf16 v[42:45], v[158:161], v[188:191], v[42:45]
	v_mfma_f32_16x16x32_bf16 v[34:37], v[166:169], v[188:191], v[34:37]
	v_mfma_f32_16x16x32_bf16 v[26:29], v[158:161], v[196:199], v[26:29]
	s_setprio 2
	s_barrier
	v_mfma_f32_16x16x32_bf16 v[18:21], v[166:169], v[196:199], v[18:21]
	v_mfma_f32_16x16x32_bf16 v[10:13], v[158:161], v[204:207], v[10:13]
	v_mfma_f32_16x16x32_bf16 v[2:5], v[166:169], v[204:207], v[2:5]
	s_setprio 0
	s_add_i32 s72, s72, 2
	s_add_u32 s28, s28, 0x100
	s_addc_u32 s29, s29, 0
	s_add_u32 s70, s70, 0x100
	s_addc_u32 s71, s71, 0
	s_cmp_gt_u32 s72, 29
	s_cbranch_scc0 .LBB0_51
	s_and_b64 vcc, exec, s[44:45]
	s_cbranch_vccz .LBB0_54
	s_barrier

; #define PG8_STAGE(bufoff, gbase, voff) do { _Pragma("unroll") for (int _i = 0; _i < 2; ++_i) \
;         __builtin_amdgcn_global_load_lds((const unsigned*)((const char*)(gbase) + (voff)[_i]), (LAS unsigned*)(lds + (bufoff) + ldsw + _i * 8192), 16, 0, 0); } while (0)
; #define PG8_LDA(dst, b, h) do { _Pragma("unroll") for (int m = 0; m < 4; ++m) _Pragma("unroll") for (int k = 0; k < 2; ++k) dst[m][k] = *(const LAS bf16x8*)(lds + PG8_SA(b, h) + aoff + m * 2048 + k * 1024); } while (0)
; #define PG8_LDB(dst, b, h) do { _Pragma("unroll") for (int n = 0; n < 2; ++n) _Pragma("unroll") for (int k = 0; k < 2; ++k) dst[n][k] = *(const LAS bf16x8*)(lds + PG8_SB(b, h) + boff + n * 2048 + k * 1024); } while (0)
; #define PG8_MMA(ai, bj, At, Bt) do { __builtin_amdgcn_s_setprio(1); _Pragma("unroll") for (int m = 0; m < 4; ++m) _Pragma("unroll") for (int n = 0; n < 2; ++n) _Pragma("unroll") for (int k = 0; k < 2; ++k) \
;         acc[ai][bj][m][n] = __builtin_amdgcn_mfma_f32_16x16x32_bf16(Bt[n][k], At[m][k], acc[ai][bj][m][n], 0, 0, 0); __builtin_amdgcn_s_setprio(0); } while (0)
; #define PG8_WAIT_V(n) asm volatile("s_waitcnt vmcnt(" #n ")" ::: "memory")
; template <class Epi>
; __device__ __forceinline__ void gemm_phase(LAS unsigned char* lds, const Gemm g, const TileOrder& S, const Epi& E) {
;     ...
;             const bool last = (t == nt - 2);
;             const char* a1 = cA + (size_t)(t + 1) * kstepA;
;             const char* a2 = last ? nA : cA + (size_t)(t + 2) * kstepA; const char* b2 = last ? nB : cB + (size_t)(t + 2) * kstep;
;             const char* a3 = a2 + kstepA; const char* b3 = b2 + kstep;
;             PG8_LDB(B0, 0, 0); PG8_LDB(B1, 0, 1); PG8_SCHED; PG8_LDA(At, 0, 0); PG8_STAGE(PG8_SA(1, 1), a1 + hstepA, voffA);
;             PG8_WAIT_V(8); PG8_WAIT_L(0); PG8_BAR; PG8_MMA(0, 0, At, B0); PG8_MMA(0, 1, At, B1); PG8_BAR; PG8_SCHED;
;             PG8_LDA(At, 0, 1); PG8_STAGE(PG8_SB(0, 0), b2, voffB); PG8_STAGE(PG8_SB(0, 1), b2 + hstepB, voffB); PG8_STAGE(PG8_SA(0, 0), a2, voffA);
;             PG8_WAIT_V(8); PG8_WAIT_L(0); PG8_BAR; PG8_MMA(1, 0, At, B0); PG8_MMA(1, 1, At, B1); PG8_BAR; PG8_SCHED;
;             PG8_LDB(B0, 1, 0); PG8_LDB(B1, 1, 1); PG8_SCHED; PG8_LDA(At, 1, 0); PG8_STAGE(PG8_SA(0, 1), a2 + hstepA, voffA);
;             PG8_WAIT_V(8); PG8_WAIT_L(0); PG8_BAR; PG8_MMA(0, 0, At, B0); PG8_MMA(0, 1, At, B1); PG8_BAR; PG8_SCHED;
.LBB0_255:
	s_mov_b32 s6, 0x10000
	s_mov_b32 s14, 0x14000
	v_add_u32_e32 v134, s6, v238
	v_add_u32_e32 v158, s14, v238
	ds_read_b128 v[118:121], v134
	ds_read_b128 v[126:129], v134 offset:1024
	ds_read_b128 v[130:133], v134 offset:2048
	ds_read_b128 v[134:137], v134 offset:3072
	ds_read_b128 v[138:141], v158
	ds_read_b128 v[142:145], v158 offset:1024
	ds_read_b128 v[154:157], v158 offset:2048
	ds_read_b128 v[158:161], v158 offset:3072
	ds_read_b128 v[162:165], v239
	ds_read_b128 v[166:169], v239 offset:1024
	ds_read_b128 v[170:173], v239 offset:2048
	ds_read_b128 v[174:177], v239 offset:3072
	ds_read_b128 v[178:181], v239 offset:4096
	ds_read_b128 v[182:185], v239 offset:5120
	ds_read_b128 v[186:189], v239 offset:6144
	ds_read_b128 v[200:203], v239 offset:7168
	s_add_u32 s2, s28, 0x4000
	s_addc_u32 s3, s29, 0
	s_cmp_eq_u32 s68, 28
	s_cselect_b32 s48, s64, s2
	s_cselect_b32 s49, s43, s3
	s_cselect_b32 s30, s65, s66
	s_cselect_b32 s31, s39, s67
	s_add_u32 s2, s48, 0x8000
	s_addc_u32 s3, s49, 0
	s_add_i32 m0, s52, 0xc000
	s_nop 0
	global_load_lds_dwordx4 v196, s[28:29]
	s_add_i32 m0, s52, 0xe000
	s_nop 0
	global_load_lds_dwordx4 v198, s[28:29]
	s_waitcnt vmcnt(8)
	s_waitcnt lgkmcnt(0)
	s_barrier
	s_setprio 1
	s_waitcnt lgkmcnt(0)
	v_mfma_f32_16x16x32_bf16 v[150:153], v[118:121], v[162:165], v[150:153]
	v_mfma_f32_16x16x32_bf16 v[146:149], v[130:133], v[162:165], v[146:149]
	v_mfma_f32_16x16x32_bf16 v[110:113], v[118:121], v[170:173], v[110:113]
	v_mfma_f32_16x16x32_bf16 v[106:109], v[130:133], v[170:173], v[106:109]
	v_mfma_f32_16x16x32_bf16 v[94:97], v[118:121], v[178:181], v[94:97]
	v_mfma_f32_16x16x32_bf16 v[90:93], v[130:133], v[178:181], v[90:93]
	v_mfma_f32_16x16x32_bf16 v[78:81], v[118:121], v[186:189], v[78:81]
	v_mfma_f32_16x16x32_bf16 v[74:77], v[130:133], v[186:189], v[74:77]
	v_mfma_f32_16x16x32_bf16 v[150:153], v[126:129], v[166:169], v[150:153]
	v_mfma_f32_16x16x32_bf16 v[146:149], v[134:137], v[166:169], v[146:149]
	v_mfma_f32_16x16x32_bf16 v[110:113], v[126:129], v[174:177], v[110:113]
	v_mfma_f32_16x16x32_bf16 v[106:109], v[134:137], v[174:177], v[106:109]
	v_mfma_f32_16x16x32_bf16 v[94:97], v[126:129], v[182:185], v[94:97]
	v_mfma_f32_16x16x32_bf16 v[90:93], v[134:137], v[182:185], v[90:93]
	v_mfma_f32_16x16x32_bf16 v[78:81], v[126:129], v[200:203], v[78:81]
	v_mfma_f32_16x16x32_bf16 v[74:77], v[134:137], v[200:203], v[74:77]
	s_setprio 0
	s_setprio 1
	v_mfma_f32_16x16x32_bf16 v[122:125], v[138:141], v[162:165], v[122:125]
	v_mfma_f32_16x16x32_bf16 v[114:117], v[154:157], v[162:165], v[114:117]
	v_mfma_f32_16x16x32_bf16 v[102:105], v[138:141], v[170:173], v[102:105]
	v_mfma_f32_16x16x32_bf16 v[98:101], v[154:157], v[170:173], v[98:101]
	v_mfma_f32_16x16x32_bf16 v[86:89], v[138:141], v[178:181], v[86:89]
	v_mfma_f32_16x16x32_bf16 v[82:85], v[154:157], v[178:181], v[82:85]
	v_mfma_f32_16x16x32_bf16 v[70:73], v[138:141], v[186:189], v[70:73]
	v_mfma_f32_16x16x32_bf16 v[66:69], v[154:157], v[186:189], v[66:69]
	v_mfma_f32_16x16x32_bf16 v[122:125], v[142:145], v[166:169], v[122:125]
	v_mfma_f32_16x16x32_bf16 v[114:117], v[158:161], v[166:169], v[114:117]
	v_mfma_f32_16x16x32_bf16 v[102:105], v[142:145], v[174:177], v[102:105]
	v_mfma_f32_16x16x32_bf16 v[98:101], v[158:161], v[174:177], v[98:101]
	v_mfma_f32_16x16x32_bf16 v[86:89], v[142:145], v[182:185], v[86:89]
	s_setprio 2
	s_barrier
	v_mfma_f32_16x16x32_bf16 v[82:85], v[158:161], v[182:185], v[82:85]
	v_mfma_f32_16x16x32_bf16 v[70:73], v[142:145], v[200:203], v[70:73]
	v_mfma_f32_16x16x32_bf16 v[66:69], v[158:161], v[200:203], v[66:69]
	s_setprio 0
	s_add_i32 s6, s6, s51
	v_lshl_add_u64 v[204:205], s[30:31], 0, v[0:1]
	s_mov_b32 m0, s6
	ds_read_b128 v[162:165], v239 offset:16384
	ds_read_b128 v[166:169], v239 offset:17408
	ds_read_b128 v[170:173], v239 offset:18432
	ds_read_b128 v[174:177], v239 offset:19456
	ds_read_b128 v[178:181], v239 offset:20480
	ds_read_b128 v[182:185], v239 offset:21504
	ds_read_b128 v[186:189], v239 offset:22528
	ds_read_b128 v[200:203], v239 offset:23552
	global_load_lds_dwordx4 v[204:205], off
	s_add_i32 m0, s6, 0x2000
	s_add_u32 s12, s30, 0x80000
	v_lshl_add_u64 v[206:207], s[30:31], 0, v[190:191]
	s_addc_u32 s13, s31, 0
	s_add_i32 s6, s14, s51
	global_load_lds_dwordx4 v[206:207], off
	s_mov_b32 m0, s6
	s_nop 0
	global_load_lds_dwordx4 v0, s[12:13]
	s_add_i32 m0, s6, 0x2000
	s_nop 0
	global_load_lds_dwordx4 v190, s[12:13]
	s_mov_b32 m0, s52
	s_nop 0
	global_load_lds_dwordx4 v194, s[48:49]
	s_mov_b32 m0, s53
	s_nop 0
	global_load_lds_dwordx4 v192, s[48:49]
	s_waitcnt vmcnt(8)
	s_waitcnt lgkmcnt(0)
	s_barrier
	s_setprio 1
	s_waitcnt lgkmcnt(0)
	v_mfma_f32_16x16x32_bf16 v[62:65], v[118:121], v[162:165], v[62:65]
	v_mfma_f32_16x16x32_bf16 v[58:61], v[130:133], v[162:165], v[58:61]
	v_mfma_f32_16x16x32_bf16 v[46:49], v[118:121], v[170:173], v[46:49]
	v_mfma_f32_16x16x32_bf16 v[42:45], v[130:133], v[170:173], v[42:45]
	v_mfma_f32_16x16x32_bf16 v[30:33], v[118:121], v[178:181], v[30:33]
	v_mfma_f32_16x16x32_bf16 v[26:29], v[130:133], v[178:181], v[26:29]
	v_mfma_f32_16x16x32_bf16 v[14:17], v[118:121], v[186:189], v[14:17]
	v_mfma_f32_16x16x32_bf16 v[10:13], v[130:133], v[186:189], v[10:13]
	v_mfma_f32_16x16x32_bf16 v[62:65], v[126:129], v[166:169], v[62:65]
	v_mfma_f32_16x16x32_bf16 v[58:61], v[134:137], v[166:169], v[58:61]
	v_mfma_f32_16x16x32_bf16 v[46:49], v[126:129], v[174:177], v[46:49]
	v_mfma_f32_16x16x32_bf16 v[42:45], v[134:137], v[174:177], v[42:45]
	v_mfma_f32_16x16x32_bf16 v[30:33], v[126:129], v[182:185], v[30:33]
	v_mfma_f32_16x16x32_bf16 v[26:29], v[134:137], v[182:185], v[26:29]
	v_mfma_f32_16x16x32_bf16 v[14:17], v[126:129], v[200:203], v[14:17]
	v_mfma_f32_16x16x32_bf16 v[10:13], v[134:137], v[200:203], v[10:13]
	s_setprio 0
	s_setprio 1
	v_mfma_f32_16x16x32_bf16 v[54:57], v[138:141], v[162:165], v[54:57]
	v_mfma_f32_16x16x32_bf16 v[50:53], v[154:157], v[162:165], v[50:53]
	v_mfma_f32_16x16x32_bf16 v[38:41], v[138:141], v[170:173], v[38:41]
	v_mfma_f32_16x16x32_bf16 v[34:37], v[154:157], v[170:173], v[34:37]
	v_mfma_f32_16x16x32_bf16 v[22:25], v[138:141], v[178:181], v[22:25]
	v_mfma_f32_16x16x32_bf16 v[18:21], v[154:157], v[178:181], v[18:21]
	v_mfma_f32_16x16x32_bf16 v[6:9], v[138:141], v[186:189], v[6:9]
	v_mfma_f32_16x16x32_bf16 v[2:5], v[154:157], v[186:189], v[2:5]
	v_mfma_f32_16x16x32_bf16 v[54:57], v[142:145], v[166:169], v[54:57]
	v_mfma_f32_16x16x32_bf16 v[50:53], v[158:161], v[166:169], v[50:53]
	v_mfma_f32_16x16x32_bf16 v[38:41], v[142:145], v[174:177], v[38:41]
	v_mfma_f32_16x16x32_bf16 v[34:37], v[158:161], v[174:177], v[34:37]
	v_mfma_f32_16x16x32_bf16 v[22:25], v[142:145], v[182:185], v[22:25]
	s_setprio 2
	s_barrier
; #define PG8_STAGE(bufoff, gbase, voff) do { _Pragma("unroll") for (int _i = 0; _i < 2; ++_i) \
;         __builtin_amdgcn_global_load_lds((const unsigned*)((const char*)(gbase) + (voff)[_i]), (LAS unsigned*)(lds + (bufoff) + ldsw + _i * 8192), 16, 0, 0); } while (0)
; #define PG8_LDA(dst, b, h) do { _Pragma("unroll") for (int m = 0; m < 4; ++m) _Pragma("unroll") for (int k = 0; k < 2; ++k) dst[m][k] = *(const LAS bf16x8*)(lds + PG8_SA(b, h) + aoff + m * 2048 + k * 1024); } while (0)
; #define PG8_LDB(dst, b, h) do { _Pragma("unroll") for (int n = 0; n < 2; ++n) _Pragma("unroll") for (int k = 0; k < 2; ++k) dst[n][k] = *(const LAS bf16x8*)(lds + PG8_SB(b, h) + boff + n * 2048 + k * 1024); } while (0)
; #define PG8_MMA(ai, bj, At, Bt) do { __builtin_amdgcn_s_setprio(1); _Pragma("unroll") for (int m = 0; m < 4; ++m) _Pragma("unroll") for (int n = 0; n < 2; ++n) _Pragma("unroll") for (int k = 0; k < 2; ++k) \
;         acc[ai][bj][m][n] = __builtin_amdgcn_mfma_f32_16x16x32_bf16(Bt[n][k], At[m][k], acc[ai][bj][m][n], 0, 0, 0); __builtin_amdgcn_s_setprio(0); } while (0)
; #define PG8_WAIT_V(n) asm volatile("s_waitcnt vmcnt(" #n ")" ::: "memory")
; #define PG8_WAIT_L(n) asm volatile("s_waitcnt lgkmcnt(" #n ")" ::: "memory")
; #define PG8_BAR __builtin_amdgcn_s_barrier()
; #define PG8_SCHED __builtin_amdgcn_sched_barrier(0)
; template <class Epi>
; __device__ __forceinline__ void gemm_phase(LAS unsigned char* lds, const Gemm g, const TileOrder& S, const Epi& E) {
;     ...
;             PG8_WAIT_V(8); PG8_WAIT_L(0); PG8_BAR; PG8_MMA(1, 0, At, B0); PG8_MMA(1, 1, At, B1); PG8_BAR; PG8_SCHED;
;             PG8_LDB(B0, 1, 0); PG8_LDB(B1, 1, 1); PG8_SCHED; PG8_LDA(At, 1, 0); PG8_STAGE(PG8_SA(0, 1), a2 + hstepA, voffA);
;             PG8_WAIT_V(8); PG8_WAIT_L(0); PG8_BAR; PG8_MMA(0, 0, At, B0); PG8_MMA(0, 1, At, B1); PG8_BAR; PG8_SCHED;
	v_mfma_f32_16x16x32_bf16 v[18:21], v[158:161], v[182:185], v[18:21]
	v_mfma_f32_16x16x32_bf16 v[6:9], v[142:145], v[200:203], v[6:9]
	v_mfma_f32_16x16x32_bf16 v[2:5], v[158:161], v[200:203], v[2:5]
	s_setprio 0
	s_add_i32 s6, 0, 0x18000
	s_add_i32 s14, 0, 0x1c000
	v_add_u32_e32 v134, s6, v238
	v_add_u32_e32 v158, s14, v238
	ds_read_b128 v[118:121], v134
	ds_read_b128 v[126:129], v134 offset:1024
	ds_read_b128 v[130:133], v134 offset:2048
	ds_read_b128 v[134:137], v134 offset:3072
	ds_read_b128 v[138:141], v158
	ds_read_b128 v[142:145], v158 offset:1024
	ds_read_b128 v[154:157], v158 offset:2048
	ds_read_b128 v[158:161], v158 offset:3072
	s_add_u32 s12, s48, 0x4000
	s_addc_u32 s13, s49, 0
	s_mov_b32 m0, s54
	ds_read_b128 v[162:165], v239 offset:32768
	ds_read_b128 v[166:169], v239 offset:33792
	ds_read_b128 v[170:173], v239 offset:34816
	ds_read_b128 v[174:177], v239 offset:35840
	ds_read_b128 v[178:181], v239 offset:36864
	ds_read_b128 v[182:185], v239 offset:37888
	ds_read_b128 v[186:189], v239 offset:38912
	ds_read_b128 v[200:203], v239 offset:39936
	global_load_lds_dwordx4 v194, s[12:13]
	s_mov_b32 m0, s55
	s_nop 0
	global_load_lds_dwordx4 v192, s[12:13]
	s_waitcnt vmcnt(8)
	s_waitcnt lgkmcnt(0)
	s_barrier
	s_setprio 1
	s_waitcnt lgkmcnt(0)
	v_mfma_f32_16x16x32_bf16 v[150:153], v[118:121], v[162:165], v[150:153]
	v_mfma_f32_16x16x32_bf16 v[146:149], v[130:133], v[162:165], v[146:149]
	v_mfma_f32_16x16x32_bf16 v[110:113], v[118:121], v[170:173], v[110:113]
	v_mfma_f32_16x16x32_bf16 v[106:109], v[130:133], v[170:173], v[106:109]
	v_mfma_f32_16x16x32_bf16 v[94:97], v[118:121], v[178:181], v[94:97]
	v_mfma_f32_16x16x32_bf16 v[90:93], v[130:133], v[178:181], v[90:93]
	v_mfma_f32_16x16x32_bf16 v[78:81], v[118:121], v[186:189], v[78:81]
	v_mfma_f32_16x16x32_bf16 v[74:77], v[130:133], v[186:189], v[74:77]
	v_mfma_f32_16x16x32_bf16 v[150:153], v[126:129], v[166:169], v[150:153]
	v_mfma_f32_16x16x32_bf16 v[146:149], v[134:137], v[166:169], v[146:149]
	v_mfma_f32_16x16x32_bf16 v[110:113], v[126:129], v[174:177], v[110:113]
	v_mfma_f32_16x16x32_bf16 v[106:109], v[134:137], v[174:177], v[106:109]
	v_mfma_f32_16x16x32_bf16 v[94:97], v[126:129], v[182:185], v[94:97]
	v_mfma_f32_16x16x32_bf16 v[90:93], v[134:137], v[182:185], v[90:93]
	v_mfma_f32_16x16x32_bf16 v[78:81], v[126:129], v[200:203], v[78:81]
	v_mfma_f32_16x16x32_bf16 v[74:77], v[134:137], v[200:203], v[74:77]
	s_setprio 0
	s_setprio 1
	v_mfma_f32_16x16x32_bf16 v[122:125], v[138:141], v[162:165], v[122:125]
	v_mfma_f32_16x16x32_bf16 v[114:117], v[154:157], v[162:165], v[114:117]
	v_mfma_f32_16x16x32_bf16 v[102:105], v[138:141], v[170:173], v[102:105]
	v_mfma_f32_16x16x32_bf16 v[98:101], v[154:157], v[170:173], v[98:101]
	v_mfma_f32_16x16x32_bf16 v[86:89], v[138:141], v[178:181], v[86:89]
	v_mfma_f32_16x16x32_bf16 v[82:85], v[154:157], v[178:181], v[82:85]
	v_mfma_f32_16x16x32_bf16 v[70:73], v[138:141], v[186:189], v[70:73]
	v_mfma_f32_16x16x32_bf16 v[66:69], v[154:157], v[186:189], v[66:69]
	v_mfma_f32_16x16x32_bf16 v[122:125], v[142:145], v[166:169], v[122:125]
	v_mfma_f32_16x16x32_bf16 v[114:117], v[158:161], v[166:169], v[114:117]
	v_mfma_f32_16x16x32_bf16 v[102:105], v[142:145], v[174:177], v[102:105]
	v_mfma_f32_16x16x32_bf16 v[98:101], v[158:161], v[174:177], v[98:101]
	v_mfma_f32_16x16x32_bf16 v[86:89], v[142:145], v[182:185], v[86:89]
	s_setprio 2
	s_barrier
; #define PG8_STAGE(bufoff, gbase, voff) do { _Pragma("unroll") for (int _i = 0; _i < 2; ++_i) \
;         __builtin_amdgcn_global_load_lds((const unsigned*)((const char*)(gbase) + (voff)[_i]), (LAS unsigned*)(lds + (bufoff) + ldsw + _i * 8192), 16, 0, 0); } while (0)
; #define PG8_LDA(dst, b, h) do { _Pragma("unroll") for (int m = 0; m < 4; ++m) _Pragma("unroll") for (int k = 0; k < 2; ++k) dst[m][k] = *(const LAS bf16x8*)(lds + PG8_SA(b, h) + aoff + m * 2048 + k * 1024); } while (0)
; #define PG8_MMA(ai, bj, At, Bt) do { __builtin_amdgcn_s_setprio(1); _Pragma("unroll") for (int m = 0; m < 4; ++m) _Pragma("unroll") for (int n = 0; n < 2; ++n) _Pragma("unroll") for (int k = 0; k < 2; ++k) \
;         acc[ai][bj][m][n] = __builtin_amdgcn_mfma_f32_16x16x32_bf16(Bt[n][k], At[m][k], acc[ai][bj][m][n], 0, 0, 0); __builtin_amdgcn_s_setprio(0); } while (0)
; #define PG8_WAIT_V(n) asm volatile("s_waitcnt vmcnt(" #n ")" ::: "memory")
; #define PG8_WAIT_L(n) asm volatile("s_waitcnt lgkmcnt(" #n ")" ::: "memory")
; #define PG8_BAR __builtin_amdgcn_s_barrier()
; #define PG8_SCHED __builtin_amdgcn_sched_barrier(0)
; template <class Epi>
; __device__ __forceinline__ void gemm_phase(LAS unsigned char* lds, const Gemm g, const TileOrder& S, const Epi& E) {
;     ...
;             PG8_WAIT_V(8); PG8_WAIT_L(0); PG8_BAR; PG8_MMA(0, 0, At, B0); PG8_MMA(0, 1, At, B1); PG8_BAR; PG8_SCHED;
;             PG8_LDA(At, 1, 1); PG8_STAGE(PG8_SB(1, 0), b3, voffB); PG8_STAGE(PG8_SB(1, 1), b3 + hstepB, voffB); PG8_STAGE(PG8_SA(1, 0), a3, voffA);
;             PG8_WAIT_V(8); PG8_WAIT_L(0); PG8_BAR; PG8_MMA(1, 0, At, B0); PG8_MMA(1, 1, At, B1); PG8_BAR; PG8_SCHED;
;         }
;         if (wr == 0) PG8_BAR;
	v_mfma_f32_16x16x32_bf16 v[82:85], v[158:161], v[182:185], v[82:85]
	v_mfma_f32_16x16x32_bf16 v[70:73], v[142:145], v[200:203], v[70:73]
	v_mfma_f32_16x16x32_bf16 v[66:69], v[158:161], v[200:203], v[66:69]
	s_setprio 0
	s_add_i32 s6, s6, s51
	v_lshl_add_u64 v[204:205], v[204:205], 0, s[34:35]
	s_mov_b32 m0, s6
	ds_read_b128 v[162:165], v239 offset:49152
	ds_read_b128 v[166:169], v239 offset:50176
	ds_read_b128 v[170:173], v239 offset:51200
	ds_read_b128 v[174:177], v239 offset:52224
	ds_read_b128 v[178:181], v239 offset:53248
	ds_read_b128 v[182:185], v239 offset:54272
	ds_read_b128 v[186:189], v239 offset:55296
	ds_read_b128 v[200:203], v239 offset:56320
	global_load_lds_dwordx4 v[204:205], off
	s_add_i32 m0, s6, 0x2000
	s_add_u32 s12, s30, 0x80080
	v_lshl_add_u64 v[204:205], v[206:207], 0, s[34:35]
	s_addc_u32 s13, s31, 0
	s_add_i32 s6, s14, s51
	global_load_lds_dwordx4 v[204:205], off
	s_mov_b32 m0, s6
	s_nop 0
	global_load_lds_dwordx4 v0, s[12:13]
	s_add_i32 m0, s6, 0x2000
	s_nop 0
	global_load_lds_dwordx4 v190, s[12:13]
	s_mov_b32 m0, s60
	s_nop 0
	global_load_lds_dwordx4 v194, s[2:3]
	s_mov_b32 m0, s61
	s_nop 0
	global_load_lds_dwordx4 v192, s[2:3]
	s_waitcnt vmcnt(8)
	s_waitcnt lgkmcnt(0)
	s_barrier
	s_setprio 1
	s_waitcnt lgkmcnt(0)
	v_mfma_f32_16x16x32_bf16 v[62:65], v[118:121], v[162:165], v[62:65]
	v_mfma_f32_16x16x32_bf16 v[58:61], v[130:133], v[162:165], v[58:61]
	v_mfma_f32_16x16x32_bf16 v[46:49], v[118:121], v[170:173], v[46:49]
	v_mfma_f32_16x16x32_bf16 v[42:45], v[130:133], v[170:173], v[42:45]
	v_mfma_f32_16x16x32_bf16 v[30:33], v[118:121], v[178:181], v[30:33]
	v_mfma_f32_16x16x32_bf16 v[26:29], v[130:133], v[178:181], v[26:29]
	v_mfma_f32_16x16x32_bf16 v[14:17], v[118:121], v[186:189], v[14:17]
	v_mfma_f32_16x16x32_bf16 v[10:13], v[130:133], v[186:189], v[10:13]
	v_mfma_f32_16x16x32_bf16 v[62:65], v[126:129], v[166:169], v[62:65]
	v_mfma_f32_16x16x32_bf16 v[58:61], v[134:137], v[166:169], v[58:61]
	v_mfma_f32_16x16x32_bf16 v[46:49], v[126:129], v[174:177], v[46:49]
	v_mfma_f32_16x16x32_bf16 v[42:45], v[134:137], v[174:177], v[42:45]
	v_mfma_f32_16x16x32_bf16 v[30:33], v[126:129], v[182:185], v[30:33]
	v_mfma_f32_16x16x32_bf16 v[26:29], v[134:137], v[182:185], v[26:29]
	v_mfma_f32_16x16x32_bf16 v[14:17], v[126:129], v[200:203], v[14:17]
	v_mfma_f32_16x16x32_bf16 v[10:13], v[134:137], v[200:203], v[10:13]
	s_setprio 0
	s_setprio 1
	v_mfma_f32_16x16x32_bf16 v[54:57], v[138:141], v[162:165], v[54:57]
	v_mfma_f32_16x16x32_bf16 v[50:53], v[154:157], v[162:165], v[50:53]
	v_mfma_f32_16x16x32_bf16 v[38:41], v[138:141], v[170:173], v[38:41]
	v_mfma_f32_16x16x32_bf16 v[34:37], v[154:157], v[170:173], v[34:37]
	v_mfma_f32_16x16x32_bf16 v[22:25], v[138:141], v[178:181], v[22:25]
	v_mfma_f32_16x16x32_bf16 v[18:21], v[154:157], v[178:181], v[18:21]
	v_mfma_f32_16x16x32_bf16 v[6:9], v[138:141], v[186:189], v[6:9]
	v_mfma_f32_16x16x32_bf16 v[2:5], v[154:157], v[186:189], v[2:5]
	v_mfma_f32_16x16x32_bf16 v[54:57], v[142:145], v[166:169], v[54:57]
	v_mfma_f32_16x16x32_bf16 v[50:53], v[158:161], v[166:169], v[50:53]
	v_mfma_f32_16x16x32_bf16 v[38:41], v[142:145], v[174:177], v[38:41]
	v_mfma_f32_16x16x32_bf16 v[34:37], v[158:161], v[174:177], v[34:37]
	v_mfma_f32_16x16x32_bf16 v[22:25], v[142:145], v[182:185], v[22:25]
	s_setprio 2
	s_barrier
	v_mfma_f32_16x16x32_bf16 v[18:21], v[158:161], v[182:185], v[18:21]
	v_mfma_f32_16x16x32_bf16 v[6:9], v[142:145], v[200:203], v[6:9]
	v_mfma_f32_16x16x32_bf16 v[2:5], v[158:161], v[200:203], v[2:5]
	s_setprio 0
	s_add_i32 s68, s68, 2
	s_add_u32 s66, s66, 0x100
	s_addc_u32 s67, s67, 0
	s_add_u32 s28, s28, 0x10000
	s_addc_u32 s29, s29, 0
	s_cmp_gt_u32 s68, 29
	s_cbranch_scc0 .LBB0_255
	s_and_b64 vcc, exec, s[36:37]
	s_cbranch_vccz .LBB0_258
	s_barrier

; #define PG8_STAGE(bufoff, gbase, voff) do { _Pragma("unroll") for (int _i = 0; _i < 2; ++_i) \
;         __builtin_amdgcn_global_load_lds((const unsigned*)((const char*)(gbase) + (voff)[_i]), (LAS unsigned*)(lds + (bufoff) + ldsw + _i * 8192), 16, 0, 0); } while (0)
; #define PG8_LDA(dst, b, h) do { _Pragma("unroll") for (int m = 0; m < 4; ++m) _Pragma("unroll") for (int k = 0; k < 2; ++k) dst[m][k] = *(const LAS bf16x8*)(lds + PG8_SA(b, h) + aoff + m * 2048 + k * 1024); } while (0)
; #define PG8_LDB(dst, b, h) do { _Pragma("unroll") for (int n = 0; n < 2; ++n) _Pragma("unroll") for (int k = 0; k < 2; ++k) dst[n][k] = *(const LAS bf16x8*)(lds + PG8_SB(b, h) + boff + n * 2048 + k * 1024); } while (0)
; #define PG8_MMA(ai, bj, At, Bt) do { __builtin_amdgcn_s_setprio(1); _Pragma("unroll") for (int m = 0; m < 4; ++m) _Pragma("unroll") for (int n = 0; n < 2; ++n) _Pragma("unroll") for (int k = 0; k < 2; ++k) \
;         acc[ai][bj][m][n] = __builtin_amdgcn_mfma_f32_16x16x32_bf16(Bt[n][k], At[m][k], acc[ai][bj][m][n], 0, 0, 0); __builtin_amdgcn_s_setprio(0); } while (0)
; #define PG8_WAIT_V(n) asm volatile("s_waitcnt vmcnt(" #n ")" ::: "memory")
; #define PG8_WAIT_L(n) asm volatile("s_waitcnt lgkmcnt(" #n ")" ::: "memory")
; #define PG8_BAR __builtin_amdgcn_s_barrier()
; #define PG8_SCHED __builtin_amdgcn_sched_barrier(0)
; template <class Epi>
; __device__ __forceinline__ void gemm_phase(LAS unsigned char* lds, const Gemm g, const TileOrder& S, const Epi& E) {
;     ...
;             const bool last = (t == nt - 2);
;             const char* a1 = cA + (size_t)(t + 1) * kstepA;
;             const char* a2 = last ? nA : cA + (size_t)(t + 2) * kstepA; const char* b2 = last ? nB : cB + (size_t)(t + 2) * kstep;
;             const char* a3 = a2 + kstepA; const char* b3 = b2 + kstep;
;             PG8_LDB(B0, 0, 0); PG8_LDB(B1, 0, 1); PG8_SCHED; PG8_LDA(At, 0, 0); PG8_STAGE(PG8_SA(1, 1), a1 + hstepA, voffA);
;             PG8_WAIT_V(8); PG8_WAIT_L(0); PG8_BAR; PG8_MMA(0, 0, At, B0); PG8_MMA(0, 1, At, B1); PG8_BAR; PG8_SCHED;
;             PG8_LDA(At, 0, 1); PG8_STAGE(PG8_SB(0, 0), b2, voffB); PG8_STAGE(PG8_SB(0, 1), b2 + hstepB, voffB); PG8_STAGE(PG8_SA(0, 0), a2, voffA);
.LBB0_457:
	s_mov_b32 s6, 0x10000
	s_mov_b32 s12, 0x14000
	v_add_u32_e32 v156, s6, v142
	v_add_u32_e32 v172, s12, v142
	ds_read_b128 v[144:147], v156
	ds_read_b128 v[148:151], v156 offset:1024
	ds_read_b128 v[152:155], v156 offset:2048
	ds_read_b128 v[156:159], v156 offset:3072
	ds_read_b128 v[160:163], v172
	ds_read_b128 v[164:167], v172 offset:1024
	ds_read_b128 v[168:171], v172 offset:2048
	ds_read_b128 v[172:175], v172 offset:3072
	ds_read_b128 v[176:179], v143
	ds_read_b128 v[180:183], v143 offset:1024
	ds_read_b128 v[184:187], v143 offset:2048
	ds_read_b128 v[188:191], v143 offset:3072
	ds_read_b128 v[192:195], v143 offset:4096
	ds_read_b128 v[196:199], v143 offset:5120
	ds_read_b128 v[200:203], v143 offset:6144
	ds_read_b128 v[204:207], v143 offset:7168
	s_add_u32 s2, s44, 0x100
	s_addc_u32 s3, s45, 0
	s_cmp_eq_u32 s60, 4
	s_cselect_b32 s47, s39, s3
	s_cselect_b32 s46, s38, s2
	s_cselect_b32 s5, s29, s59
	s_cselect_b32 s4, s57, s58
	s_add_i32 m0, s26, 0xc000
	s_nop 0
	global_load_lds_dwordx4 v136, s[44:45]
	s_add_i32 m0, s26, 0xe000
	s_nop 0
	global_load_lds_dwordx4 v138, s[44:45]
	s_waitcnt vmcnt(8)
	s_waitcnt lgkmcnt(0)
	s_barrier
	s_setprio 1
	s_waitcnt lgkmcnt(0)
	v_mfma_f32_16x16x32_bf16 v[126:129], v[144:147], v[176:179], v[126:129]
	v_mfma_f32_16x16x32_bf16 v[122:125], v[152:155], v[176:179], v[122:125]
	v_mfma_f32_16x16x32_bf16 v[118:121], v[144:147], v[184:187], v[118:121]
	v_mfma_f32_16x16x32_bf16 v[114:117], v[152:155], v[184:187], v[114:117]
	v_mfma_f32_16x16x32_bf16 v[106:109], v[144:147], v[192:195], v[106:109]
	v_mfma_f32_16x16x32_bf16 v[98:101], v[152:155], v[192:195], v[98:101]
	v_mfma_f32_16x16x32_bf16 v[90:93], v[144:147], v[200:203], v[90:93]
	v_mfma_f32_16x16x32_bf16 v[82:85], v[152:155], v[200:203], v[82:85]
	v_mfma_f32_16x16x32_bf16 v[126:129], v[148:151], v[180:183], v[126:129]
	v_mfma_f32_16x16x32_bf16 v[122:125], v[156:159], v[180:183], v[122:125]
	v_mfma_f32_16x16x32_bf16 v[118:121], v[148:151], v[188:191], v[118:121]
	v_mfma_f32_16x16x32_bf16 v[114:117], v[156:159], v[188:191], v[114:117]
	v_mfma_f32_16x16x32_bf16 v[106:109], v[148:151], v[196:199], v[106:109]
	v_mfma_f32_16x16x32_bf16 v[98:101], v[156:159], v[196:199], v[98:101]
	v_mfma_f32_16x16x32_bf16 v[90:93], v[148:151], v[204:207], v[90:93]
	v_mfma_f32_16x16x32_bf16 v[82:85], v[156:159], v[204:207], v[82:85]
	s_setprio 0
	s_setprio 1
	v_mfma_f32_16x16x32_bf16 v[110:113], v[160:163], v[176:179], v[110:113]
	v_mfma_f32_16x16x32_bf16 v[102:105], v[168:171], v[176:179], v[102:105]
	v_mfma_f32_16x16x32_bf16 v[94:97], v[160:163], v[184:187], v[94:97]
	v_mfma_f32_16x16x32_bf16 v[86:89], v[168:171], v[184:187], v[86:89]
	v_mfma_f32_16x16x32_bf16 v[78:81], v[160:163], v[192:195], v[78:81]
	v_mfma_f32_16x16x32_bf16 v[74:77], v[168:171], v[192:195], v[74:77]
	v_mfma_f32_16x16x32_bf16 v[70:73], v[160:163], v[200:203], v[70:73]
	v_mfma_f32_16x16x32_bf16 v[66:69], v[168:171], v[200:203], v[66:69]
	v_mfma_f32_16x16x32_bf16 v[110:113], v[164:167], v[180:183], v[110:113]
	v_mfma_f32_16x16x32_bf16 v[102:105], v[172:175], v[180:183], v[102:105]
	v_mfma_f32_16x16x32_bf16 v[94:97], v[164:167], v[188:191], v[94:97]
	v_mfma_f32_16x16x32_bf16 v[86:89], v[172:175], v[188:191], v[86:89]
	v_mfma_f32_16x16x32_bf16 v[78:81], v[164:167], v[196:199], v[78:81]
	s_setprio 2
	s_barrier
	v_mfma_f32_16x16x32_bf16 v[74:77], v[172:175], v[196:199], v[74:77]
	v_mfma_f32_16x16x32_bf16 v[70:73], v[164:167], v[204:207], v[70:73]
	v_mfma_f32_16x16x32_bf16 v[66:69], v[172:175], v[204:207], v[66:69]
	s_setprio 0
	s_add_i32 s6, s6, s25
	v_lshl_add_u64 v[208:209], s[4:5], 0, v[0:1]
	s_mov_b32 m0, s6
	ds_read_b128 v[176:179], v143 offset:16384
	ds_read_b128 v[180:183], v143 offset:17408
	ds_read_b128 v[184:187], v143 offset:18432
	ds_read_b128 v[188:191], v143 offset:19456
	ds_read_b128 v[192:195], v143 offset:20480
	ds_read_b128 v[196:199], v143 offset:21504
	ds_read_b128 v[200:203], v143 offset:22528
	ds_read_b128 v[204:207], v143 offset:23552
	global_load_lds_dwordx4 v[208:209], off
	s_add_i32 m0, s6, 0x2000
	s_add_u32 s14, s4, 0x20000
	v_lshl_add_u64 v[210:211], s[4:5], 0, v[130:131]
	s_addc_u32 s15, s5, 0
	s_add_i32 s6, s12, s25
	global_load_lds_dwordx4 v[210:211], off
	s_mov_b32 m0, s6
	v_lshl_add_u64 v[214:215], s[46:47], 0, v[132:133]
	global_load_lds_dwordx4 v0, s[14:15]
	s_add_i32 m0, s6, 0x2000
	s_nop 0
	global_load_lds_dwordx4 v130, s[14:15]
	v_lshl_add_u64 v[212:213], s[46:47], 0, v[134:135]
	s_mov_b32 m0, s26
	s_nop 0
	global_load_lds_dwordx4 v[212:213], off
	s_mov_b32 m0, s48
	s_nop 0
	global_load_lds_dwordx4 v[214:215], off
	s_waitcnt vmcnt(8)
	s_waitcnt lgkmcnt(0)
	s_barrier
; #define PG8_STAGE(bufoff, gbase, voff) do { _Pragma("unroll") for (int _i = 0; _i < 2; ++_i) \
;         __builtin_amdgcn_global_load_lds((const unsigned*)((const char*)(gbase) + (voff)[_i]), (LAS unsigned*)(lds + (bufoff) + ldsw + _i * 8192), 16, 0, 0); } while (0)
; #define PG8_LDA(dst, b, h) do { _Pragma("unroll") for (int m = 0; m < 4; ++m) _Pragma("unroll") for (int k = 0; k < 2; ++k) dst[m][k] = *(const LAS bf16x8*)(lds + PG8_SA(b, h) + aoff + m * 2048 + k * 1024); } while (0)
; #define PG8_LDB(dst, b, h) do { _Pragma("unroll") for (int n = 0; n < 2; ++n) _Pragma("unroll") for (int k = 0; k < 2; ++k) dst[n][k] = *(const LAS bf16x8*)(lds + PG8_SB(b, h) + boff + n * 2048 + k * 1024); } while (0)
; #define PG8_MMA(ai, bj, At, Bt) do { __builtin_amdgcn_s_setprio(1); _Pragma("unroll") for (int m = 0; m < 4; ++m) _Pragma("unroll") for (int n = 0; n < 2; ++n) _Pragma("unroll") for (int k = 0; k < 2; ++k) \
;         acc[ai][bj][m][n] = __builtin_amdgcn_mfma_f32_16x16x32_bf16(Bt[n][k], At[m][k], acc[ai][bj][m][n], 0, 0, 0); __builtin_amdgcn_s_setprio(0); } while (0)
; #define PG8_WAIT_V(n) asm volatile("s_waitcnt vmcnt(" #n ")" ::: "memory")
; #define PG8_WAIT_L(n) asm volatile("s_waitcnt lgkmcnt(" #n ")" ::: "memory")
; #define PG8_BAR __builtin_amdgcn_s_barrier()
; #define PG8_SCHED __builtin_amdgcn_sched_barrier(0)
; template <class Epi>
; __device__ __forceinline__ void gemm_phase(LAS unsigned char* lds, const Gemm g, const TileOrder& S, const Epi& E) {
;     ...
;             PG8_WAIT_V(8); PG8_WAIT_L(0); PG8_BAR; PG8_MMA(1, 0, At, B0); PG8_MMA(1, 1, At, B1); PG8_BAR; PG8_SCHED;
;             PG8_LDB(B0, 1, 0); PG8_LDB(B1, 1, 1); PG8_SCHED; PG8_LDA(At, 1, 0); PG8_STAGE(PG8_SA(0, 1), a2 + hstepA, voffA);
;             PG8_WAIT_V(8); PG8_WAIT_L(0); PG8_BAR; PG8_MMA(0, 0, At, B0); PG8_MMA(0, 1, At, B1); PG8_BAR; PG8_SCHED;
	s_setprio 1
	s_waitcnt lgkmcnt(0)
	v_mfma_f32_16x16x32_bf16 v[62:65], v[144:147], v[176:179], v[62:65]
	v_mfma_f32_16x16x32_bf16 v[58:61], v[152:155], v[176:179], v[58:61]
	v_mfma_f32_16x16x32_bf16 v[54:57], v[144:147], v[184:187], v[54:57]
	v_mfma_f32_16x16x32_bf16 v[50:53], v[152:155], v[184:187], v[50:53]
	v_mfma_f32_16x16x32_bf16 v[38:41], v[144:147], v[192:195], v[38:41]
	v_mfma_f32_16x16x32_bf16 v[34:37], v[152:155], v[192:195], v[34:37]
	v_mfma_f32_16x16x32_bf16 v[22:25], v[144:147], v[200:203], v[22:25]
	v_mfma_f32_16x16x32_bf16 v[18:21], v[152:155], v[200:203], v[18:21]
	v_mfma_f32_16x16x32_bf16 v[62:65], v[148:151], v[180:183], v[62:65]
	v_mfma_f32_16x16x32_bf16 v[58:61], v[156:159], v[180:183], v[58:61]
	v_mfma_f32_16x16x32_bf16 v[54:57], v[148:151], v[188:191], v[54:57]
	v_mfma_f32_16x16x32_bf16 v[50:53], v[156:159], v[188:191], v[50:53]
	v_mfma_f32_16x16x32_bf16 v[38:41], v[148:151], v[196:199], v[38:41]
	v_mfma_f32_16x16x32_bf16 v[34:37], v[156:159], v[196:199], v[34:37]
	v_mfma_f32_16x16x32_bf16 v[22:25], v[148:151], v[204:207], v[22:25]
	v_mfma_f32_16x16x32_bf16 v[18:21], v[156:159], v[204:207], v[18:21]
	s_setprio 0
	s_setprio 1
	v_mfma_f32_16x16x32_bf16 v[46:49], v[160:163], v[176:179], v[46:49]
	v_mfma_f32_16x16x32_bf16 v[42:45], v[168:171], v[176:179], v[42:45]
	v_mfma_f32_16x16x32_bf16 v[30:33], v[160:163], v[184:187], v[30:33]
	v_mfma_f32_16x16x32_bf16 v[26:29], v[168:171], v[184:187], v[26:29]
	v_mfma_f32_16x16x32_bf16 v[14:17], v[160:163], v[192:195], v[14:17]
	v_mfma_f32_16x16x32_bf16 v[10:13], v[168:171], v[192:195], v[10:13]
	v_mfma_f32_16x16x32_bf16 v[6:9], v[160:163], v[200:203], v[6:9]
	v_mfma_f32_16x16x32_bf16 v[2:5], v[168:171], v[200:203], v[2:5]
	v_mfma_f32_16x16x32_bf16 v[46:49], v[164:167], v[180:183], v[46:49]
	v_mfma_f32_16x16x32_bf16 v[42:45], v[172:175], v[180:183], v[42:45]
	v_mfma_f32_16x16x32_bf16 v[30:33], v[164:167], v[188:191], v[30:33]
	v_mfma_f32_16x16x32_bf16 v[26:29], v[172:175], v[188:191], v[26:29]
	v_mfma_f32_16x16x32_bf16 v[14:17], v[164:167], v[196:199], v[14:17]
	s_setprio 2
	s_barrier
	v_mfma_f32_16x16x32_bf16 v[10:13], v[172:175], v[196:199], v[10:13]
	v_mfma_f32_16x16x32_bf16 v[6:9], v[164:167], v[204:207], v[6:9]
	v_mfma_f32_16x16x32_bf16 v[2:5], v[172:175], v[204:207], v[2:5]
	s_setprio 0
	s_add_i32 s6, 0, 0x18000
	s_add_i32 s12, 0, 0x1c000
	v_add_u32_e32 v156, s6, v142
	v_add_u32_e32 v172, s12, v142
	ds_read_b128 v[144:147], v156
	ds_read_b128 v[148:151], v156 offset:1024
	ds_read_b128 v[152:155], v156 offset:2048
	ds_read_b128 v[156:159], v156 offset:3072
	ds_read_b128 v[160:163], v172
	ds_read_b128 v[164:167], v172 offset:1024
	ds_read_b128 v[168:171], v172 offset:2048
	ds_read_b128 v[172:175], v172 offset:3072
	s_add_u32 s14, s46, 0x30000
	s_addc_u32 s15, s47, 0
	s_mov_b32 m0, s49
	ds_read_b128 v[176:179], v143 offset:32768
	ds_read_b128 v[180:183], v143 offset:33792
	ds_read_b128 v[184:187], v143 offset:34816
	ds_read_b128 v[188:191], v143 offset:35840
	ds_read_b128 v[192:195], v143 offset:36864
	ds_read_b128 v[196:199], v143 offset:37888
	ds_read_b128 v[200:203], v143 offset:38912
	ds_read_b128 v[204:207], v143 offset:39936
	global_load_lds_dwordx4 v134, s[14:15]
	s_mov_b32 m0, s50
	s_nop 0
	global_load_lds_dwordx4 v132, s[14:15]
	s_waitcnt vmcnt(8)
	s_waitcnt lgkmcnt(0)
	s_barrier
	s_setprio 1
	s_waitcnt lgkmcnt(0)
	v_mfma_f32_16x16x32_bf16 v[126:129], v[144:147], v[176:179], v[126:129]
	v_mfma_f32_16x16x32_bf16 v[122:125], v[152:155], v[176:179], v[122:125]
	v_mfma_f32_16x16x32_bf16 v[118:121], v[144:147], v[184:187], v[118:121]
	v_mfma_f32_16x16x32_bf16 v[114:117], v[152:155], v[184:187], v[114:117]
	v_mfma_f32_16x16x32_bf16 v[106:109], v[144:147], v[192:195], v[106:109]
	v_mfma_f32_16x16x32_bf16 v[98:101], v[152:155], v[192:195], v[98:101]
	v_mfma_f32_16x16x32_bf16 v[90:93], v[144:147], v[200:203], v[90:93]
	v_mfma_f32_16x16x32_bf16 v[82:85], v[152:155], v[200:203], v[82:85]
	v_mfma_f32_16x16x32_bf16 v[126:129], v[148:151], v[180:183], v[126:129]
	v_mfma_f32_16x16x32_bf16 v[122:125], v[156:159], v[180:183], v[122:125]
	v_mfma_f32_16x16x32_bf16 v[118:121], v[148:151], v[188:191], v[118:121]
	v_mfma_f32_16x16x32_bf16 v[114:117], v[156:159], v[188:191], v[114:117]
	v_mfma_f32_16x16x32_bf16 v[106:109], v[148:151], v[196:199], v[106:109]
	v_mfma_f32_16x16x32_bf16 v[98:101], v[156:159], v[196:199], v[98:101]
	v_mfma_f32_16x16x32_bf16 v[90:93], v[148:151], v[204:207], v[90:93]
	v_mfma_f32_16x16x32_bf16 v[82:85], v[156:159], v[204:207], v[82:85]
	s_setprio 0
	s_setprio 1
	v_mfma_f32_16x16x32_bf16 v[110:113], v[160:163], v[176:179], v[110:113]
	v_mfma_f32_16x16x32_bf16 v[102:105], v[168:171], v[176:179], v[102:105]
	v_mfma_f32_16x16x32_bf16 v[94:97], v[160:163], v[184:187], v[94:97]
	v_mfma_f32_16x16x32_bf16 v[86:89], v[168:171], v[184:187], v[86:89]
	v_mfma_f32_16x16x32_bf16 v[78:81], v[160:163], v[192:195], v[78:81]
	v_mfma_f32_16x16x32_bf16 v[74:77], v[168:171], v[192:195], v[74:77]
	v_mfma_f32_16x16x32_bf16 v[70:73], v[160:163], v[200:203], v[70:73]
	v_mfma_f32_16x16x32_bf16 v[66:69], v[168:171], v[200:203], v[66:69]
	v_mfma_f32_16x16x32_bf16 v[110:113], v[164:167], v[180:183], v[110:113]
	v_mfma_f32_16x16x32_bf16 v[102:105], v[172:175], v[180:183], v[102:105]
	v_mfma_f32_16x16x32_bf16 v[94:97], v[164:167], v[188:191], v[94:97]
	v_mfma_f32_16x16x32_bf16 v[86:89], v[172:175], v[188:191], v[86:89]
	v_mfma_f32_16x16x32_bf16 v[78:81], v[164:167], v[196:199], v[78:81]
	s_setprio 2
	s_barrier
; #define PG8_STAGE(bufoff, gbase, voff) do { _Pragma("unroll") for (int _i = 0; _i < 2; ++_i) \
;         __builtin_amdgcn_global_load_lds((const unsigned*)((const char*)(gbase) + (voff)[_i]), (LAS unsigned*)(lds + (bufoff) + ldsw + _i * 8192), 16, 0, 0); } while (0)
; #define PG8_LDA(dst, b, h) do { _Pragma("unroll") for (int m = 0; m < 4; ++m) _Pragma("unroll") for (int k = 0; k < 2; ++k) dst[m][k] = *(const LAS bf16x8*)(lds + PG8_SA(b, h) + aoff + m * 2048 + k * 1024); } while (0)
; #define PG8_LDB(dst, b, h) do { _Pragma("unroll") for (int n = 0; n < 2; ++n) _Pragma("unroll") for (int k = 0; k < 2; ++k) dst[n][k] = *(const LAS bf16x8*)(lds + PG8_SB(b, h) + boff + n * 2048 + k * 1024); } while (0)
; #define PG8_MMA(ai, bj, At, Bt) do { __builtin_amdgcn_s_setprio(1); _Pragma("unroll") for (int m = 0; m < 4; ++m) _Pragma("unroll") for (int n = 0; n < 2; ++n) _Pragma("unroll") for (int k = 0; k < 2; ++k) \
;         acc[ai][bj][m][n] = __builtin_amdgcn_mfma_f32_16x16x32_bf16(Bt[n][k], At[m][k], acc[ai][bj][m][n], 0, 0, 0); __builtin_amdgcn_s_setprio(0); } while (0)
; #define PG8_WAIT_V(n) asm volatile("s_waitcnt vmcnt(" #n ")" ::: "memory")
; #define PG8_WAIT_L(n) asm volatile("s_waitcnt lgkmcnt(" #n ")" ::: "memory")
; #define PG8_BAR __builtin_amdgcn_s_barrier()
; #define PG8_SCHED __builtin_amdgcn_sched_barrier(0)
; template <class Epi>
; __device__ __forceinline__ void gemm_phase(LAS unsigned char* lds, const Gemm g, const TileOrder& S, const Epi& E) {
;     ...
;             PG8_LDB(B0, 1, 0); PG8_LDB(B1, 1, 1); PG8_SCHED; PG8_LDA(At, 1, 0); PG8_STAGE(PG8_SA(0, 1), a2 + hstepA, voffA);
;             PG8_WAIT_V(8); PG8_WAIT_L(0); PG8_BAR; PG8_MMA(0, 0, At, B0); PG8_MMA(0, 1, At, B1); PG8_BAR; PG8_SCHED;
;             PG8_LDA(At, 1, 1); PG8_STAGE(PG8_SB(1, 0), b3, voffB); PG8_STAGE(PG8_SB(1, 1), b3 + hstepB, voffB); PG8_STAGE(PG8_SA(1, 0), a3, voffA);
;             PG8_WAIT_V(8); PG8_WAIT_L(0); PG8_BAR; PG8_MMA(1, 0, At, B0); PG8_MMA(1, 1, At, B1); PG8_BAR; PG8_SCHED;
;         }
;         if (wr == 0) PG8_BAR;
	v_mfma_f32_16x16x32_bf16 v[74:77], v[172:175], v[196:199], v[74:77]
	v_mfma_f32_16x16x32_bf16 v[70:73], v[164:167], v[204:207], v[70:73]
	v_mfma_f32_16x16x32_bf16 v[66:69], v[172:175], v[204:207], v[66:69]
	s_setprio 0
	s_add_i32 s6, s6, s25
	v_lshl_add_u64 v[208:209], v[208:209], 0, s[34:35]
	s_mov_b32 m0, s6
	ds_read_b128 v[176:179], v143 offset:49152
	ds_read_b128 v[180:183], v143 offset:50176
	ds_read_b128 v[184:187], v143 offset:51200
	ds_read_b128 v[188:191], v143 offset:52224
	ds_read_b128 v[192:195], v143 offset:53248
	ds_read_b128 v[196:199], v143 offset:54272
	ds_read_b128 v[200:203], v143 offset:55296
	ds_read_b128 v[204:207], v143 offset:56320
	global_load_lds_dwordx4 v[208:209], off
	s_add_i32 m0, s6, 0x2000
	s_add_u32 s4, s4, 0x20080
	v_lshl_add_u64 v[208:209], v[210:211], 0, s[34:35]
	s_addc_u32 s5, s5, 0
	s_add_i32 s6, s12, s25
	global_load_lds_dwordx4 v[208:209], off
	s_mov_b32 m0, s6
	s_nop 0
	global_load_lds_dwordx4 v0, s[4:5]
	v_lshl_add_u64 v[208:209], s[4:5], 0, v[130:131]
	s_add_i32 m0, s6, 0x2000
	s_nop 0
	global_load_lds_dwordx4 v[208:209], off
	v_lshl_add_u64 v[208:209], v[212:213], 0, s[34:35]
	s_mov_b32 m0, s51
	s_nop 0
	global_load_lds_dwordx4 v[208:209], off
	v_lshl_add_u64 v[208:209], v[214:215], 0, s[34:35]
	s_mov_b32 m0, s52
	s_nop 0
	global_load_lds_dwordx4 v[208:209], off
	s_waitcnt vmcnt(8)
	s_waitcnt lgkmcnt(0)
	s_barrier
	s_setprio 1
	s_waitcnt lgkmcnt(0)
	v_mfma_f32_16x16x32_bf16 v[62:65], v[144:147], v[176:179], v[62:65]
	v_mfma_f32_16x16x32_bf16 v[58:61], v[152:155], v[176:179], v[58:61]
	v_mfma_f32_16x16x32_bf16 v[54:57], v[144:147], v[184:187], v[54:57]
	v_mfma_f32_16x16x32_bf16 v[50:53], v[152:155], v[184:187], v[50:53]
	v_mfma_f32_16x16x32_bf16 v[38:41], v[144:147], v[192:195], v[38:41]
	v_mfma_f32_16x16x32_bf16 v[34:37], v[152:155], v[192:195], v[34:37]
	v_mfma_f32_16x16x32_bf16 v[22:25], v[144:147], v[200:203], v[22:25]
	v_mfma_f32_16x16x32_bf16 v[18:21], v[152:155], v[200:203], v[18:21]
	v_mfma_f32_16x16x32_bf16 v[62:65], v[148:151], v[180:183], v[62:65]
	v_mfma_f32_16x16x32_bf16 v[58:61], v[156:159], v[180:183], v[58:61]
	v_mfma_f32_16x16x32_bf16 v[54:57], v[148:151], v[188:191], v[54:57]
	v_mfma_f32_16x16x32_bf16 v[50:53], v[156:159], v[188:191], v[50:53]
	v_mfma_f32_16x16x32_bf16 v[38:41], v[148:151], v[196:199], v[38:41]
	v_mfma_f32_16x16x32_bf16 v[34:37], v[156:159], v[196:199], v[34:37]
	v_mfma_f32_16x16x32_bf16 v[22:25], v[148:151], v[204:207], v[22:25]
	v_mfma_f32_16x16x32_bf16 v[18:21], v[156:159], v[204:207], v[18:21]
	s_setprio 0
	s_setprio 1
	v_mfma_f32_16x16x32_bf16 v[46:49], v[160:163], v[176:179], v[46:49]
	v_mfma_f32_16x16x32_bf16 v[42:45], v[168:171], v[176:179], v[42:45]
	v_mfma_f32_16x16x32_bf16 v[30:33], v[160:163], v[184:187], v[30:33]
	v_mfma_f32_16x16x32_bf16 v[26:29], v[168:171], v[184:187], v[26:29]
	v_mfma_f32_16x16x32_bf16 v[14:17], v[160:163], v[192:195], v[14:17]
	v_mfma_f32_16x16x32_bf16 v[10:13], v[168:171], v[192:195], v[10:13]
	v_mfma_f32_16x16x32_bf16 v[6:9], v[160:163], v[200:203], v[6:9]
	v_mfma_f32_16x16x32_bf16 v[2:5], v[168:171], v[200:203], v[2:5]
	v_mfma_f32_16x16x32_bf16 v[46:49], v[164:167], v[180:183], v[46:49]
	v_mfma_f32_16x16x32_bf16 v[42:45], v[172:175], v[180:183], v[42:45]
	v_mfma_f32_16x16x32_bf16 v[30:33], v[164:167], v[188:191], v[30:33]
	v_mfma_f32_16x16x32_bf16 v[26:29], v[172:175], v[188:191], v[26:29]
	v_mfma_f32_16x16x32_bf16 v[14:17], v[164:167], v[196:199], v[14:17]
	s_setprio 2
	s_barrier
	v_mfma_f32_16x16x32_bf16 v[10:13], v[172:175], v[196:199], v[10:13]
	v_mfma_f32_16x16x32_bf16 v[6:9], v[164:167], v[204:207], v[6:9]
	v_mfma_f32_16x16x32_bf16 v[2:5], v[172:175], v[204:207], v[2:5]
	s_setprio 0
	s_add_i32 s60, s60, 2
	s_add_u32 s58, s58, 0x100
	s_addc_u32 s59, s59, 0
	s_cmp_gt_u32 s60, 5
	s_mov_b64 s[44:45], s[2:3]
	s_cbranch_scc0 .LBB0_457
	s_and_b64 vcc, exec, s[36:37]
	s_cbranch_vccz .LBB0_460
	s_barrier

; #define PG8_STAGE(bufoff, gbase, voff) do { _Pragma("unroll") for (int _i = 0; _i < 2; ++_i) \
;         __builtin_amdgcn_global_load_lds((const unsigned*)((const char*)(gbase) + (voff)[_i]), (LAS unsigned*)(lds + (bufoff) + ldsw + _i * 8192), 16, 0, 0); } while (0)
; #define PG8_LDA(dst, b, h) do { _Pragma("unroll") for (int m = 0; m < 4; ++m) _Pragma("unroll") for (int k = 0; k < 2; ++k) dst[m][k] = *(const LAS bf16x8*)(lds + PG8_SA(b, h) + aoff + m * 2048 + k * 1024); } while (0)
; #define PG8_LDB(dst, b, h) do { _Pragma("unroll") for (int n = 0; n < 2; ++n) _Pragma("unroll") for (int k = 0; k < 2; ++k) dst[n][k] = *(const LAS bf16x8*)(lds + PG8_SB(b, h) + boff + n * 2048 + k * 1024); } while (0)
; #define PG8_MMA(ai, bj, At, Bt) do { __builtin_amdgcn_s_setprio(1); _Pragma("unroll") for (int m = 0; m < 4; ++m) _Pragma("unroll") for (int n = 0; n < 2; ++n) _Pragma("unroll") for (int k = 0; k < 2; ++k) \
;         acc[ai][bj][m][n] = __builtin_amdgcn_mfma_f32_16x16x32_bf16(Bt[n][k], At[m][k], acc[ai][bj][m][n], 0, 0, 0); __builtin_amdgcn_s_setprio(0); } while (0)
; #define PG8_WAIT_V(n) asm volatile("s_waitcnt vmcnt(" #n ")" ::: "memory")
; #define PG8_WAIT_L(n) asm volatile("s_waitcnt lgkmcnt(" #n ")" ::: "memory")
; #define PG8_BAR __builtin_amdgcn_s_barrier()
; #define PG8_SCHED __builtin_amdgcn_sched_barrier(0)
; template <class Epi>
; __device__ __forceinline__ void gemm_phase(LAS unsigned char* lds, const Gemm g, const TileOrder& S, const Epi& E) {
;     ...
;         for (int t = 0; t < nt; t += 2) {
;             const bool last = (t == nt - 2);
;             const char* a1 = cA + (size_t)(t + 1) * kstepA;
;             const char* a2 = last ? nA : cA + (size_t)(t + 2) * kstepA; const char* b2 = last ? nB : cB + (size_t)(t + 2) * kstep;
;             const char* a3 = a2 + kstepA; const char* b3 = b2 + kstep;
;             PG8_LDB(B0, 0, 0); PG8_LDB(B1, 0, 1); PG8_SCHED; PG8_LDA(At, 0, 0); PG8_STAGE(PG8_SA(1, 1), a1 + hstepA, voffA);
;             PG8_WAIT_V(8); PG8_WAIT_L(0); PG8_BAR; PG8_MMA(0, 0, At, B0); PG8_MMA(0, 1, At, B1); PG8_BAR; PG8_SCHED;
;             PG8_LDA(At, 0, 1); PG8_STAGE(PG8_SB(0, 0), b2, voffB); PG8_STAGE(PG8_SB(0, 1), b2 + hstepB, voffB); PG8_STAGE(PG8_SA(0, 0), a2, voffA);
;             PG8_WAIT_V(8); PG8_WAIT_L(0); PG8_BAR; PG8_MMA(1, 0, At, B0); PG8_MMA(1, 1, At, B1); PG8_BAR; PG8_SCHED;
.LBB0_596:
	s_mov_b32 s6, 0x10000
	s_mov_b32 s12, 0x14000
	v_add_u32_e32 v58, s6, v224
	v_add_u32_e32 v102, s12, v224
	ds_read_b128 v[42:45], v58
	ds_read_b128 v[46:49], v58 offset:1024
	ds_read_b128 v[50:53], v58 offset:2048
	ds_read_b128 v[58:61], v58 offset:3072
	ds_read_b128 v[74:77], v102
	ds_read_b128 v[82:85], v102 offset:1024
	ds_read_b128 v[94:97], v102 offset:2048
	ds_read_b128 v[102:105], v102 offset:3072
	ds_read_b128 v[114:117], v225
	ds_read_b128 v[126:129], v225 offset:1024
	ds_read_b128 v[138:141], v225 offset:2048
	ds_read_b128 v[150:153], v225 offset:3072
	ds_read_b128 v[162:165], v225 offset:4096
	ds_read_b128 v[174:177], v225 offset:5120
	ds_read_b128 v[186:189], v225 offset:6144
	ds_read_b128 v[190:193], v225 offset:7168
	s_add_u32 s2, s28, 0x100
	s_addc_u32 s3, s29, 0
	s_cmp_eq_u32 s62, 8
	s_cselect_b32 s47, s1, s3
	s_cselect_b32 s46, s0, s2
	s_cselect_b32 s31, s45, s61
	s_cselect_b32 s30, s44, s60
	s_add_i32 m0, s26, 0xc000
	s_nop 0
	global_load_lds_dwordx4 v214, s[28:29]
	s_add_i32 m0, s26, 0xe000
	s_nop 0
	global_load_lds_dwordx4 v216, s[28:29]
	s_waitcnt vmcnt(8)
	s_waitcnt lgkmcnt(0)
	s_barrier
	s_setprio 1
	s_waitcnt lgkmcnt(0)
	v_mfma_f32_16x16x32_bf16 v[182:185], v[42:45], v[114:117], v[182:185]
	v_mfma_f32_16x16x32_bf16 v[178:181], v[50:53], v[114:117], v[178:181]
	v_mfma_f32_16x16x32_bf16 v[158:161], v[42:45], v[138:141], v[158:161]
	v_mfma_f32_16x16x32_bf16 v[154:157], v[50:53], v[138:141], v[154:157]
	v_mfma_f32_16x16x32_bf16 v[134:137], v[42:45], v[162:165], v[134:137]
	v_mfma_f32_16x16x32_bf16 v[130:133], v[50:53], v[162:165], v[130:133]
	v_mfma_f32_16x16x32_bf16 v[110:113], v[42:45], v[186:189], v[110:113]
	v_mfma_f32_16x16x32_bf16 v[106:109], v[50:53], v[186:189], v[106:109]
	v_mfma_f32_16x16x32_bf16 v[182:185], v[46:49], v[126:129], v[182:185]
	v_mfma_f32_16x16x32_bf16 v[178:181], v[58:61], v[126:129], v[178:181]
	v_mfma_f32_16x16x32_bf16 v[158:161], v[46:49], v[150:153], v[158:161]
	v_mfma_f32_16x16x32_bf16 v[154:157], v[58:61], v[150:153], v[154:157]
	v_mfma_f32_16x16x32_bf16 v[134:137], v[46:49], v[174:177], v[134:137]
	v_mfma_f32_16x16x32_bf16 v[130:133], v[58:61], v[174:177], v[130:133]
	v_mfma_f32_16x16x32_bf16 v[110:113], v[46:49], v[190:193], v[110:113]
	v_mfma_f32_16x16x32_bf16 v[106:109], v[58:61], v[190:193], v[106:109]
	s_setprio 0
	s_setprio 1
	v_mfma_f32_16x16x32_bf16 v[170:173], v[74:77], v[114:117], v[170:173]
	v_mfma_f32_16x16x32_bf16 v[114:117], v[94:97], v[114:117], v[166:169]
	v_mfma_f32_16x16x32_bf16 v[122:125], v[74:77], v[162:165], v[122:125]
	v_mfma_f32_16x16x32_bf16 v[118:121], v[94:97], v[162:165], v[118:121]
	v_mfma_f32_16x16x32_bf16 v[98:101], v[74:77], v[186:189], v[98:101]
	v_mfma_f32_16x16x32_bf16 v[90:93], v[94:97], v[186:189], v[90:93]
	v_mfma_f32_16x16x32_bf16 v[170:173], v[82:85], v[126:129], v[170:173]
	v_mfma_f32_16x16x32_bf16 v[114:117], v[102:105], v[126:129], v[114:117]
	v_mfma_f32_16x16x32_bf16 v[126:129], v[74:77], v[138:141], v[146:149]
	v_mfma_f32_16x16x32_bf16 v[138:141], v[94:97], v[138:141], v[142:145]
	v_mfma_f32_16x16x32_bf16 v[122:125], v[82:85], v[174:177], v[122:125]
	v_mfma_f32_16x16x32_bf16 v[118:121], v[102:105], v[174:177], v[118:121]
	v_mfma_f32_16x16x32_bf16 v[98:101], v[82:85], v[190:193], v[98:101]
	s_setprio 2
	s_barrier
	v_mfma_f32_16x16x32_bf16 v[90:93], v[102:105], v[190:193], v[90:93]
	v_mfma_f32_16x16x32_bf16 v[126:129], v[82:85], v[150:153], v[126:129]
	v_mfma_f32_16x16x32_bf16 v[138:141], v[102:105], v[150:153], v[138:141]
	s_setprio 0
	s_add_i32 s6, s6, s25
	v_lshl_add_u64 v[198:199], s[30:31], 0, v[0:1]
	s_mov_b32 m0, s6
	ds_read_b128 v[142:145], v225 offset:16384
	ds_read_b128 v[146:149], v225 offset:17408
	ds_read_b128 v[150:153], v225 offset:18432
	ds_read_b128 v[162:165], v225 offset:19456
	ds_read_b128 v[166:169], v225 offset:20480
	ds_read_b128 v[174:177], v225 offset:21504
	ds_read_b128 v[186:189], v225 offset:22528
	ds_read_b128 v[190:193], v225 offset:23552
	global_load_lds_dwordx4 v[198:199], off
	s_add_i32 m0, s6, 0x2000
	s_add_u32 s14, s30, 0x30000
	v_lshl_add_u64 v[200:201], s[30:31], 0, v[208:209]
	s_addc_u32 s15, s31, 0
	s_add_i32 s6, s12, s25
	global_load_lds_dwordx4 v[200:201], off
	s_mov_b32 m0, s6
	v_lshl_add_u64 v[202:203], s[46:47], 0, v[212:213]
	global_load_lds_dwordx4 v0, s[14:15]
	v_lshl_add_u64 v[194:195], s[14:15], 0, v[208:209]
	s_add_i32 m0, s6, 0x2000
	v_lshl_add_u64 v[204:205], s[46:47], 0, v[210:211]
	global_load_lds_dwordx4 v[194:195], off
	s_mov_b32 m0, s26
	s_nop 0
	global_load_lds_dwordx4 v[202:203], off
	s_mov_b32 m0, s48
	s_nop 0
	global_load_lds_dwordx4 v[204:205], off
	s_waitcnt vmcnt(8)
	s_waitcnt lgkmcnt(0)
	s_barrier
; #define PG8_STAGE(bufoff, gbase, voff) do { _Pragma("unroll") for (int _i = 0; _i < 2; ++_i) \
;         __builtin_amdgcn_global_load_lds((const unsigned*)((const char*)(gbase) + (voff)[_i]), (LAS unsigned*)(lds + (bufoff) + ldsw + _i * 8192), 16, 0, 0); } while (0)
; #define PG8_LDA(dst, b, h) do { _Pragma("unroll") for (int m = 0; m < 4; ++m) _Pragma("unroll") for (int k = 0; k < 2; ++k) dst[m][k] = *(const LAS bf16x8*)(lds + PG8_SA(b, h) + aoff + m * 2048 + k * 1024); } while (0)
; #define PG8_LDB(dst, b, h) do { _Pragma("unroll") for (int n = 0; n < 2; ++n) _Pragma("unroll") for (int k = 0; k < 2; ++k) dst[n][k] = *(const LAS bf16x8*)(lds + PG8_SB(b, h) + boff + n * 2048 + k * 1024); } while (0)
; #define PG8_MMA(ai, bj, At, Bt) do { __builtin_amdgcn_s_setprio(1); _Pragma("unroll") for (int m = 0; m < 4; ++m) _Pragma("unroll") for (int n = 0; n < 2; ++n) _Pragma("unroll") for (int k = 0; k < 2; ++k) \
;         acc[ai][bj][m][n] = __builtin_amdgcn_mfma_f32_16x16x32_bf16(Bt[n][k], At[m][k], acc[ai][bj][m][n], 0, 0, 0); __builtin_amdgcn_s_setprio(0); } while (0)
; #define PG8_WAIT_V(n) asm volatile("s_waitcnt vmcnt(" #n ")" ::: "memory")
; #define PG8_WAIT_L(n) asm volatile("s_waitcnt lgkmcnt(" #n ")" ::: "memory")
; #define PG8_BAR __builtin_amdgcn_s_barrier()
; #define PG8_SCHED __builtin_amdgcn_sched_barrier(0)
; template <class Epi>
; __device__ __forceinline__ void gemm_phase(LAS unsigned char* lds, const Gemm g, const TileOrder& S, const Epi& E) {
;     ...
;             PG8_WAIT_V(8); PG8_WAIT_L(0); PG8_BAR; PG8_MMA(1, 0, At, B0); PG8_MMA(1, 1, At, B1); PG8_BAR; PG8_SCHED;
;             PG8_LDB(B0, 1, 0); PG8_LDB(B1, 1, 1); PG8_SCHED; PG8_LDA(At, 1, 0); PG8_STAGE(PG8_SA(0, 1), a2 + hstepA, voffA);
;             PG8_WAIT_V(8); PG8_WAIT_L(0); PG8_BAR; PG8_MMA(0, 0, At, B0); PG8_MMA(0, 1, At, B1); PG8_BAR; PG8_SCHED;
	s_setprio 1
	s_waitcnt lgkmcnt(0)
	v_mfma_f32_16x16x32_bf16 v[86:89], v[42:45], v[142:145], v[86:89]
	v_mfma_f32_16x16x32_bf16 v[78:81], v[50:53], v[142:145], v[78:81]
	v_mfma_f32_16x16x32_bf16 v[62:65], v[42:45], v[150:153], v[62:65]
	v_mfma_f32_16x16x32_bf16 v[54:57], v[50:53], v[150:153], v[54:57]
	v_mfma_f32_16x16x32_bf16 v[30:33], v[42:45], v[166:169], v[30:33]
	v_mfma_f32_16x16x32_bf16 v[26:29], v[50:53], v[166:169], v[26:29]
	v_mfma_f32_16x16x32_bf16 v[14:17], v[42:45], v[186:189], v[14:17]
	v_mfma_f32_16x16x32_bf16 v[10:13], v[50:53], v[186:189], v[10:13]
	v_mfma_f32_16x16x32_bf16 v[86:89], v[46:49], v[146:149], v[86:89]
	v_mfma_f32_16x16x32_bf16 v[78:81], v[58:61], v[146:149], v[78:81]
	v_mfma_f32_16x16x32_bf16 v[62:65], v[46:49], v[162:165], v[62:65]
	v_mfma_f32_16x16x32_bf16 v[54:57], v[58:61], v[162:165], v[54:57]
	v_mfma_f32_16x16x32_bf16 v[30:33], v[46:49], v[174:177], v[30:33]
	v_mfma_f32_16x16x32_bf16 v[26:29], v[58:61], v[174:177], v[26:29]
	v_mfma_f32_16x16x32_bf16 v[14:17], v[46:49], v[190:193], v[14:17]
	v_mfma_f32_16x16x32_bf16 v[10:13], v[58:61], v[190:193], v[10:13]
	s_setprio 0
	s_setprio 1
	v_mfma_f32_16x16x32_bf16 v[38:41], v[74:77], v[150:153], v[38:41]
	v_mfma_f32_16x16x32_bf16 v[34:37], v[94:97], v[150:153], v[34:37]
	v_mfma_f32_16x16x32_bf16 v[22:25], v[74:77], v[166:169], v[22:25]
	v_mfma_f32_16x16x32_bf16 v[18:21], v[94:97], v[166:169], v[18:21]
	v_mfma_f32_16x16x32_bf16 v[6:9], v[74:77], v[186:189], v[6:9]
	v_mfma_f32_16x16x32_bf16 v[2:5], v[94:97], v[186:189], v[2:5]
	v_mfma_f32_16x16x32_bf16 v[42:45], v[74:77], v[142:145], v[70:73]
	v_mfma_f32_16x16x32_bf16 v[46:49], v[94:97], v[142:145], v[66:69]
	v_mfma_f32_16x16x32_bf16 v[38:41], v[82:85], v[162:165], v[38:41]
	v_mfma_f32_16x16x32_bf16 v[34:37], v[102:105], v[162:165], v[34:37]
	v_mfma_f32_16x16x32_bf16 v[22:25], v[82:85], v[174:177], v[22:25]
	v_mfma_f32_16x16x32_bf16 v[18:21], v[102:105], v[174:177], v[18:21]
	v_mfma_f32_16x16x32_bf16 v[6:9], v[82:85], v[190:193], v[6:9]
	s_setprio 2
	s_barrier
	v_mfma_f32_16x16x32_bf16 v[2:5], v[102:105], v[190:193], v[2:5]
	v_mfma_f32_16x16x32_bf16 v[42:45], v[82:85], v[146:149], v[42:45]
	v_mfma_f32_16x16x32_bf16 v[46:49], v[102:105], v[146:149], v[46:49]
	s_setprio 0
	s_add_i32 s6, 0, 0x18000
	s_add_i32 s12, 0, 0x1c000
	v_add_u32_e32 v70, s6, v224
	v_add_u32_e32 v102, s12, v224
	ds_read_b128 v[50:53], v70
	ds_read_b128 v[58:61], v70 offset:1024
	ds_read_b128 v[66:69], v70 offset:2048
	ds_read_b128 v[70:73], v70 offset:3072
	ds_read_b128 v[74:77], v102
	ds_read_b128 v[82:85], v102 offset:1024
	ds_read_b128 v[94:97], v102 offset:2048
	ds_read_b128 v[102:105], v102 offset:3072
	s_add_u32 s14, s46, 0x30000
	s_addc_u32 s15, s47, 0
	s_mov_b32 m0, s49
	ds_read_b128 v[142:145], v225 offset:32768
	ds_read_b128 v[146:149], v225 offset:33792
	ds_read_b128 v[150:153], v225 offset:34816
	ds_read_b128 v[162:165], v225 offset:35840
	ds_read_b128 v[174:177], v225 offset:36864
	ds_read_b128 v[186:189], v225 offset:37888
	ds_read_b128 v[190:193], v225 offset:38912
	ds_read_b128 v[194:197], v225 offset:39936
	global_load_lds_dwordx4 v212, s[14:15]
	s_mov_b32 m0, s50
	s_nop 0
	global_load_lds_dwordx4 v210, s[14:15]
	s_waitcnt vmcnt(8)
	s_waitcnt lgkmcnt(0)
	s_barrier
	s_setprio 1
	s_waitcnt lgkmcnt(0)
	v_mfma_f32_16x16x32_bf16 v[166:169], v[50:53], v[142:145], v[182:185]
	v_mfma_f32_16x16x32_bf16 v[182:185], v[58:61], v[146:149], v[166:169]
	v_mfma_f32_16x16x32_bf16 v[166:169], v[66:69], v[142:145], v[178:181]
	v_mfma_f32_16x16x32_bf16 v[158:161], v[50:53], v[150:153], v[158:161]
	v_mfma_f32_16x16x32_bf16 v[154:157], v[66:69], v[150:153], v[154:157]
	v_mfma_f32_16x16x32_bf16 v[134:137], v[50:53], v[174:177], v[134:137]
	v_mfma_f32_16x16x32_bf16 v[130:133], v[66:69], v[174:177], v[130:133]
	v_mfma_f32_16x16x32_bf16 v[110:113], v[50:53], v[190:193], v[110:113]
	v_mfma_f32_16x16x32_bf16 v[106:109], v[66:69], v[190:193], v[106:109]
	v_mfma_f32_16x16x32_bf16 v[178:181], v[70:73], v[146:149], v[166:169]
	v_mfma_f32_16x16x32_bf16 v[158:161], v[58:61], v[162:165], v[158:161]
	v_mfma_f32_16x16x32_bf16 v[154:157], v[70:73], v[162:165], v[154:157]
	v_mfma_f32_16x16x32_bf16 v[134:137], v[58:61], v[186:189], v[134:137]
	v_mfma_f32_16x16x32_bf16 v[130:133], v[70:73], v[186:189], v[130:133]
	v_mfma_f32_16x16x32_bf16 v[110:113], v[58:61], v[194:197], v[110:113]
	v_mfma_f32_16x16x32_bf16 v[106:109], v[70:73], v[194:197], v[106:109]
	s_setprio 0
	s_setprio 1
	v_mfma_f32_16x16x32_bf16 v[166:169], v[74:77], v[142:145], v[170:173]
	v_mfma_f32_16x16x32_bf16 v[114:117], v[94:97], v[142:145], v[114:117]
	v_mfma_f32_16x16x32_bf16 v[170:173], v[82:85], v[146:149], v[166:169]
	v_mfma_f32_16x16x32_bf16 v[166:169], v[102:105], v[146:149], v[114:117]
	v_mfma_f32_16x16x32_bf16 v[114:117], v[74:77], v[150:153], v[126:129]
	v_mfma_f32_16x16x32_bf16 v[146:149], v[82:85], v[162:165], v[114:117]
	v_mfma_f32_16x16x32_bf16 v[114:117], v[94:97], v[150:153], v[138:141]
	v_mfma_f32_16x16x32_bf16 v[142:145], v[102:105], v[162:165], v[114:117]
	v_mfma_f32_16x16x32_bf16 v[114:117], v[74:77], v[174:177], v[122:125]
	v_mfma_f32_16x16x32_bf16 v[122:125], v[82:85], v[186:189], v[114:117]
	v_mfma_f32_16x16x32_bf16 v[114:117], v[94:97], v[174:177], v[118:121]
	v_mfma_f32_16x16x32_bf16 v[98:101], v[74:77], v[190:193], v[98:101]
	v_mfma_f32_16x16x32_bf16 v[90:93], v[94:97], v[190:193], v[90:93]
	s_setprio 2
	s_barrier
; #define PG8_STAGE(bufoff, gbase, voff) do { _Pragma("unroll") for (int _i = 0; _i < 2; ++_i) \
;         __builtin_amdgcn_global_load_lds((const unsigned*)((const char*)(gbase) + (voff)[_i]), (LAS unsigned*)(lds + (bufoff) + ldsw + _i * 8192), 16, 0, 0); } while (0)
; #define PG8_LDA(dst, b, h) do { _Pragma("unroll") for (int m = 0; m < 4; ++m) _Pragma("unroll") for (int k = 0; k < 2; ++k) dst[m][k] = *(const LAS bf16x8*)(lds + PG8_SA(b, h) + aoff + m * 2048 + k * 1024); } while (0)
; #define PG8_MMA(ai, bj, At, Bt) do { __builtin_amdgcn_s_setprio(1); _Pragma("unroll") for (int m = 0; m < 4; ++m) _Pragma("unroll") for (int n = 0; n < 2; ++n) _Pragma("unroll") for (int k = 0; k < 2; ++k) \
;         acc[ai][bj][m][n] = __builtin_amdgcn_mfma_f32_16x16x32_bf16(Bt[n][k], At[m][k], acc[ai][bj][m][n], 0, 0, 0); __builtin_amdgcn_s_setprio(0); } while (0)
; #define PG8_WAIT_V(n) asm volatile("s_waitcnt vmcnt(" #n ")" ::: "memory")
; #define PG8_WAIT_L(n) asm volatile("s_waitcnt lgkmcnt(" #n ")" ::: "memory")
; #define PG8_BAR __builtin_amdgcn_s_barrier()
; #define PG8_SCHED __builtin_amdgcn_sched_barrier(0)
; template <class Epi>
; __device__ __forceinline__ void gemm_phase(LAS unsigned char* lds, const Gemm g, const TileOrder& S, const Epi& E) {
;     ...
;             PG8_WAIT_V(8); PG8_WAIT_L(0); PG8_BAR; PG8_MMA(0, 0, At, B0); PG8_MMA(0, 1, At, B1); PG8_BAR; PG8_SCHED;
;             PG8_LDA(At, 1, 1); PG8_STAGE(PG8_SB(1, 0), b3, voffB); PG8_STAGE(PG8_SB(1, 1), b3 + hstepB, voffB); PG8_STAGE(PG8_SA(1, 0), a3, voffA);
;             PG8_WAIT_V(8); PG8_WAIT_L(0); PG8_BAR; PG8_MMA(1, 0, At, B0); PG8_MMA(1, 1, At, B1); PG8_BAR; PG8_SCHED;
;         }
;         if (wr == 0) PG8_BAR;
	v_mfma_f32_16x16x32_bf16 v[118:121], v[102:105], v[186:189], v[114:117]
	v_mfma_f32_16x16x32_bf16 v[98:101], v[82:85], v[194:197], v[98:101]
	v_mfma_f32_16x16x32_bf16 v[90:93], v[102:105], v[194:197], v[90:93]
	s_setprio 0
	s_add_i32 s6, s6, s25
	v_lshl_add_u64 v[194:195], v[198:199], 0, s[34:35]
	s_mov_b32 m0, s6
	ds_read_b128 v[114:117], v225 offset:49152
	ds_read_b128 v[126:129], v225 offset:50176
	ds_read_b128 v[138:141], v225 offset:51200
	ds_read_b128 v[150:153], v225 offset:52224
	ds_read_b128 v[162:165], v225 offset:53248
	ds_read_b128 v[174:177], v225 offset:54272
	ds_read_b128 v[186:189], v225 offset:55296
	ds_read_b128 v[190:193], v225 offset:56320
	global_load_lds_dwordx4 v[194:195], off
	s_add_i32 m0, s6, 0x2000
	s_add_u32 s14, s30, 0x30080
	v_lshl_add_u64 v[194:195], v[200:201], 0, s[34:35]
	s_addc_u32 s15, s31, 0
	s_add_i32 s6, s12, s25
	global_load_lds_dwordx4 v[194:195], off
	s_mov_b32 m0, s6
	s_nop 0
	global_load_lds_dwordx4 v0, s[14:15]
	v_lshl_add_u64 v[194:195], s[14:15], 0, v[208:209]
	s_add_i32 m0, s6, 0x2000
	s_nop 0
	global_load_lds_dwordx4 v[194:195], off
	v_lshl_add_u64 v[194:195], v[202:203], 0, s[34:35]
	s_mov_b32 m0, s51
	s_nop 0
	global_load_lds_dwordx4 v[194:195], off
	v_lshl_add_u64 v[194:195], v[204:205], 0, s[34:35]
	s_mov_b32 m0, s52
	s_nop 0
	global_load_lds_dwordx4 v[194:195], off
	s_waitcnt vmcnt(8)
	s_waitcnt lgkmcnt(0)
	s_barrier
	s_setprio 1
	s_waitcnt lgkmcnt(0)
	v_mfma_f32_16x16x32_bf16 v[86:89], v[50:53], v[114:117], v[86:89]
	v_mfma_f32_16x16x32_bf16 v[78:81], v[66:69], v[114:117], v[78:81]
	v_mfma_f32_16x16x32_bf16 v[62:65], v[50:53], v[138:141], v[62:65]
	v_mfma_f32_16x16x32_bf16 v[54:57], v[66:69], v[138:141], v[54:57]
	v_mfma_f32_16x16x32_bf16 v[30:33], v[50:53], v[162:165], v[30:33]
	v_mfma_f32_16x16x32_bf16 v[26:29], v[66:69], v[162:165], v[26:29]
	v_mfma_f32_16x16x32_bf16 v[14:17], v[50:53], v[186:189], v[14:17]
	v_mfma_f32_16x16x32_bf16 v[10:13], v[66:69], v[186:189], v[10:13]
	v_mfma_f32_16x16x32_bf16 v[86:89], v[58:61], v[126:129], v[86:89]
	v_mfma_f32_16x16x32_bf16 v[78:81], v[70:73], v[126:129], v[78:81]
	v_mfma_f32_16x16x32_bf16 v[62:65], v[58:61], v[150:153], v[62:65]
	v_mfma_f32_16x16x32_bf16 v[54:57], v[70:73], v[150:153], v[54:57]
	v_mfma_f32_16x16x32_bf16 v[30:33], v[58:61], v[174:177], v[30:33]
	v_mfma_f32_16x16x32_bf16 v[26:29], v[70:73], v[174:177], v[26:29]
	v_mfma_f32_16x16x32_bf16 v[14:17], v[58:61], v[190:193], v[14:17]
	v_mfma_f32_16x16x32_bf16 v[10:13], v[70:73], v[190:193], v[10:13]
	s_setprio 0
	s_setprio 1
	v_mfma_f32_16x16x32_bf16 v[42:45], v[74:77], v[114:117], v[42:45]
	v_mfma_f32_16x16x32_bf16 v[70:73], v[82:85], v[126:129], v[42:45]
	v_mfma_f32_16x16x32_bf16 v[42:45], v[94:97], v[114:117], v[46:49]
	v_mfma_f32_16x16x32_bf16 v[38:41], v[74:77], v[138:141], v[38:41]
	v_mfma_f32_16x16x32_bf16 v[34:37], v[94:97], v[138:141], v[34:37]
	v_mfma_f32_16x16x32_bf16 v[22:25], v[74:77], v[162:165], v[22:25]
	v_mfma_f32_16x16x32_bf16 v[18:21], v[94:97], v[162:165], v[18:21]
	v_mfma_f32_16x16x32_bf16 v[6:9], v[74:77], v[186:189], v[6:9]
	v_mfma_f32_16x16x32_bf16 v[2:5], v[94:97], v[186:189], v[2:5]
	v_mfma_f32_16x16x32_bf16 v[66:69], v[102:105], v[126:129], v[42:45]
	v_mfma_f32_16x16x32_bf16 v[38:41], v[82:85], v[150:153], v[38:41]
	v_mfma_f32_16x16x32_bf16 v[34:37], v[102:105], v[150:153], v[34:37]
	v_mfma_f32_16x16x32_bf16 v[22:25], v[82:85], v[174:177], v[22:25]
	s_setprio 2
	s_barrier
	v_mfma_f32_16x16x32_bf16 v[18:21], v[102:105], v[174:177], v[18:21]
	v_mfma_f32_16x16x32_bf16 v[6:9], v[82:85], v[190:193], v[6:9]
	v_mfma_f32_16x16x32_bf16 v[2:5], v[102:105], v[190:193], v[2:5]
	s_setprio 0
	s_add_i32 s62, s62, 2
	s_add_u32 s60, s60, 0x100
	s_addc_u32 s61, s61, 0
	s_cmp_gt_u32 s62, 9
	s_mov_b64 s[28:29], s[2:3]
	s_cbranch_scc0 .LBB0_596
	s_and_b64 vcc, exec, s[42:43]
	s_cbranch_vccz .LBB0_599
	s_barrier

; #define PG8_STAGE(bufoff, gbase, voff) do { _Pragma("unroll") for (int _i = 0; _i < 2; ++_i) \
;         __builtin_amdgcn_global_load_lds((const unsigned*)((const char*)(gbase) + (voff)[_i]), (LAS unsigned*)(lds + (bufoff) + ldsw + _i * 8192), 16, 0, 0); } while (0)
; #define PG8_LDA(dst, b, h) do { _Pragma("unroll") for (int m = 0; m < 4; ++m) _Pragma("unroll") for (int k = 0; k < 2; ++k) dst[m][k] = *(const LAS bf16x8*)(lds + PG8_SA(b, h) + aoff + m * 2048 + k * 1024); } while (0)
; #define PG8_LDB(dst, b, h) do { _Pragma("unroll") for (int n = 0; n < 2; ++n) _Pragma("unroll") for (int k = 0; k < 2; ++k) dst[n][k] = *(const LAS bf16x8*)(lds + PG8_SB(b, h) + boff + n * 2048 + k * 1024); } while (0)
; #define PG8_MMA(ai, bj, At, Bt) do { __builtin_amdgcn_s_setprio(1); _Pragma("unroll") for (int m = 0; m < 4; ++m) _Pragma("unroll") for (int n = 0; n < 2; ++n) _Pragma("unroll") for (int k = 0; k < 2; ++k) \
;         acc[ai][bj][m][n] = __builtin_amdgcn_mfma_f32_16x16x32_bf16(Bt[n][k], At[m][k], acc[ai][bj][m][n], 0, 0, 0); __builtin_amdgcn_s_setprio(0); } while (0)
; #define PG8_WAIT_V(n) asm volatile("s_waitcnt vmcnt(" #n ")" ::: "memory")
; #define PG8_WAIT_L(n) asm volatile("s_waitcnt lgkmcnt(" #n ")" ::: "memory")
; #define PG8_BAR __builtin_amdgcn_s_barrier()
; #define PG8_SCHED __builtin_amdgcn_sched_barrier(0)
; template <class Epi>
; __device__ __forceinline__ void gemm_phase(LAS unsigned char* lds, const Gemm g, const TileOrder& S, const Epi& E) {
;     ...
;         for (int t = 0; t < nt; t += 2) {
;             const bool last = (t == nt - 2);
;             const char* a1 = cA + (size_t)(t + 1) * kstepA;
;             const char* a2 = last ? nA : cA + (size_t)(t + 2) * kstepA; const char* b2 = last ? nB : cB + (size_t)(t + 2) * kstep;
;             const char* a3 = a2 + kstepA; const char* b3 = b2 + kstep;
;             PG8_LDB(B0, 0, 0); PG8_LDB(B1, 0, 1); PG8_SCHED; PG8_LDA(At, 0, 0); PG8_STAGE(PG8_SA(1, 1), a1 + hstepA, voffA);
;             PG8_WAIT_V(8); PG8_WAIT_L(0); PG8_BAR; PG8_MMA(0, 0, At, B0); PG8_MMA(0, 1, At, B1); PG8_BAR; PG8_SCHED;
;             PG8_LDA(At, 0, 1); PG8_STAGE(PG8_SB(0, 0), b2, voffB); PG8_STAGE(PG8_SB(0, 1), b2 + hstepB, voffB); PG8_STAGE(PG8_SA(0, 0), a2, voffA);
;             PG8_WAIT_V(8); PG8_WAIT_L(0); PG8_BAR; PG8_MMA(1, 0, At, B0); PG8_MMA(1, 1, At, B1); PG8_BAR; PG8_SCHED;
.LBB0_668:
	s_mov_b32 s6, 0x10000
	s_mov_b32 s12, 0x14000
	v_add_u32_e32 v142, s6, v184
	v_add_u32_e32 v168, s12, v184
	ds_read_b128 v[130:133], v142
	ds_read_b128 v[134:137], v142 offset:1024
	ds_read_b128 v[138:141], v142 offset:2048
	ds_read_b128 v[142:145], v142 offset:3072
	ds_read_b128 v[146:149], v168
	ds_read_b128 v[150:153], v168 offset:1024
	ds_read_b128 v[164:167], v168 offset:2048
	ds_read_b128 v[168:171], v168 offset:3072
	ds_read_b128 v[172:175], v185
	ds_read_b128 v[176:179], v185 offset:1024
	ds_read_b128 v[186:189], v185 offset:2048
	ds_read_b128 v[190:193], v185 offset:3072
	ds_read_b128 v[194:197], v185 offset:4096
	ds_read_b128 v[198:201], v185 offset:5120
	ds_read_b128 v[202:205], v185 offset:6144
	ds_read_b128 v[206:209], v185 offset:7168
	s_add_u32 s2, s4, 0xfff80080
	s_addc_u32 s3, s5, -1
	s_cmp_eq_u32 s66, 28
	s_cselect_b32 s29, s45, s3
	s_cselect_b32 s28, s62, s2
	s_cselect_b32 s3, s43, s65
	s_cselect_b32 s2, s63, s64
	s_add_i32 m0, s50, 0xc000
	s_nop 0
	global_load_lds_dwordx4 v160, s[4:5]
	s_add_i32 m0, s50, 0xe000
	s_nop 0
	global_load_lds_dwordx4 v162, s[4:5]
	s_waitcnt vmcnt(8)
	s_waitcnt lgkmcnt(0)
	s_barrier
	s_setprio 1
	s_waitcnt lgkmcnt(0)
	v_mfma_f32_16x16x32_bf16 v[122:125], v[130:133], v[172:175], v[122:125]
	v_mfma_f32_16x16x32_bf16 v[118:121], v[138:141], v[172:175], v[118:121]
	v_mfma_f32_16x16x32_bf16 v[110:113], v[130:133], v[186:189], v[110:113]
	v_mfma_f32_16x16x32_bf16 v[102:105], v[138:141], v[186:189], v[102:105]
	v_mfma_f32_16x16x32_bf16 v[94:97], v[130:133], v[194:197], v[94:97]
	v_mfma_f32_16x16x32_bf16 v[86:89], v[138:141], v[194:197], v[86:89]
	v_mfma_f32_16x16x32_bf16 v[78:81], v[130:133], v[202:205], v[78:81]
	v_mfma_f32_16x16x32_bf16 v[70:73], v[138:141], v[202:205], v[70:73]
	v_mfma_f32_16x16x32_bf16 v[122:125], v[134:137], v[176:179], v[122:125]
	v_mfma_f32_16x16x32_bf16 v[118:121], v[142:145], v[176:179], v[118:121]
	v_mfma_f32_16x16x32_bf16 v[110:113], v[134:137], v[190:193], v[110:113]
	v_mfma_f32_16x16x32_bf16 v[102:105], v[142:145], v[190:193], v[102:105]
	v_mfma_f32_16x16x32_bf16 v[94:97], v[134:137], v[198:201], v[94:97]
	v_mfma_f32_16x16x32_bf16 v[86:89], v[142:145], v[198:201], v[86:89]
	v_mfma_f32_16x16x32_bf16 v[78:81], v[134:137], v[206:209], v[78:81]
	v_mfma_f32_16x16x32_bf16 v[70:73], v[142:145], v[206:209], v[70:73]
	s_setprio 0
	s_setprio 1
	v_mfma_f32_16x16x32_bf16 v[114:117], v[146:149], v[172:175], v[114:117]
	v_mfma_f32_16x16x32_bf16 v[126:129], v[164:167], v[172:175], v[126:129]
	v_mfma_f32_16x16x32_bf16 v[106:109], v[146:149], v[186:189], v[106:109]
	v_mfma_f32_16x16x32_bf16 v[98:101], v[164:167], v[186:189], v[98:101]
	v_mfma_f32_16x16x32_bf16 v[90:93], v[146:149], v[194:197], v[90:93]
	v_mfma_f32_16x16x32_bf16 v[82:85], v[164:167], v[194:197], v[82:85]
	v_mfma_f32_16x16x32_bf16 v[74:77], v[146:149], v[202:205], v[74:77]
	v_mfma_f32_16x16x32_bf16 v[66:69], v[164:167], v[202:205], v[66:69]
	v_mfma_f32_16x16x32_bf16 v[114:117], v[150:153], v[176:179], v[114:117]
	v_mfma_f32_16x16x32_bf16 v[126:129], v[168:171], v[176:179], v[126:129]
	v_mfma_f32_16x16x32_bf16 v[106:109], v[150:153], v[190:193], v[106:109]
	v_mfma_f32_16x16x32_bf16 v[98:101], v[168:171], v[190:193], v[98:101]
	v_mfma_f32_16x16x32_bf16 v[90:93], v[150:153], v[198:201], v[90:93]
	s_setprio 2
	s_barrier
	v_mfma_f32_16x16x32_bf16 v[82:85], v[168:171], v[198:201], v[82:85]
	v_mfma_f32_16x16x32_bf16 v[74:77], v[150:153], v[206:209], v[74:77]
	v_mfma_f32_16x16x32_bf16 v[66:69], v[168:171], v[206:209], v[66:69]
	s_setprio 0
	s_add_i32 s6, s6, s31
	v_lshl_add_u64 v[180:181], s[2:3], 0, v[0:1]
	s_mov_b32 m0, s6
	ds_read_b128 v[172:175], v185 offset:16384
	ds_read_b128 v[176:179], v185 offset:17408
	ds_read_b128 v[186:189], v185 offset:18432
	ds_read_b128 v[190:193], v185 offset:19456
	ds_read_b128 v[194:197], v185 offset:20480
	ds_read_b128 v[198:201], v185 offset:21504
	ds_read_b128 v[202:205], v185 offset:22528
	ds_read_b128 v[206:209], v185 offset:23552
	global_load_lds_dwordx4 v[180:181], off
	s_add_i32 m0, s6, 0x2000
	s_add_u32 s14, s2, 0x80000
	v_lshl_add_u64 v[210:211], s[2:3], 0, v[154:155]
	s_addc_u32 s15, s3, 0
	s_add_i32 s6, s12, s31
	global_load_lds_dwordx4 v[210:211], off
	s_mov_b32 m0, s6
	v_lshl_add_u64 v[214:215], s[28:29], 0, v[156:157]
	global_load_lds_dwordx4 v0, s[14:15]
	s_add_i32 m0, s6, 0x2000
	s_nop 0
	global_load_lds_dwordx4 v154, s[14:15]
	v_lshl_add_u64 v[212:213], s[28:29], 0, v[158:159]
	s_mov_b32 m0, s50
	s_nop 0
	global_load_lds_dwordx4 v[212:213], off
	s_mov_b32 m0, s51
	s_nop 0
	global_load_lds_dwordx4 v[214:215], off
	s_waitcnt vmcnt(8)
	s_waitcnt lgkmcnt(0)
	s_barrier
; #define PG8_STAGE(bufoff, gbase, voff) do { _Pragma("unroll") for (int _i = 0; _i < 2; ++_i) \
;         __builtin_amdgcn_global_load_lds((const unsigned*)((const char*)(gbase) + (voff)[_i]), (LAS unsigned*)(lds + (bufoff) + ldsw + _i * 8192), 16, 0, 0); } while (0)
; #define PG8_LDA(dst, b, h) do { _Pragma("unroll") for (int m = 0; m < 4; ++m) _Pragma("unroll") for (int k = 0; k < 2; ++k) dst[m][k] = *(const LAS bf16x8*)(lds + PG8_SA(b, h) + aoff + m * 2048 + k * 1024); } while (0)
; #define PG8_LDB(dst, b, h) do { _Pragma("unroll") for (int n = 0; n < 2; ++n) _Pragma("unroll") for (int k = 0; k < 2; ++k) dst[n][k] = *(const LAS bf16x8*)(lds + PG8_SB(b, h) + boff + n * 2048 + k * 1024); } while (0)
; #define PG8_MMA(ai, bj, At, Bt) do { __builtin_amdgcn_s_setprio(1); _Pragma("unroll") for (int m = 0; m < 4; ++m) _Pragma("unroll") for (int n = 0; n < 2; ++n) _Pragma("unroll") for (int k = 0; k < 2; ++k) \
;         acc[ai][bj][m][n] = __builtin_amdgcn_mfma_f32_16x16x32_bf16(Bt[n][k], At[m][k], acc[ai][bj][m][n], 0, 0, 0); __builtin_amdgcn_s_setprio(0); } while (0)
; #define PG8_WAIT_V(n) asm volatile("s_waitcnt vmcnt(" #n ")" ::: "memory")
; #define PG8_WAIT_L(n) asm volatile("s_waitcnt lgkmcnt(" #n ")" ::: "memory")
; #define PG8_BAR __builtin_amdgcn_s_barrier()
; #define PG8_SCHED __builtin_amdgcn_sched_barrier(0)
; template <class Epi>
; __device__ __forceinline__ void gemm_phase(LAS unsigned char* lds, const Gemm g, const TileOrder& S, const Epi& E) {
;     ...
;             PG8_WAIT_V(8); PG8_WAIT_L(0); PG8_BAR; PG8_MMA(1, 0, At, B0); PG8_MMA(1, 1, At, B1); PG8_BAR; PG8_SCHED;
;             PG8_LDB(B0, 1, 0); PG8_LDB(B1, 1, 1); PG8_SCHED; PG8_LDA(At, 1, 0); PG8_STAGE(PG8_SA(0, 1), a2 + hstepA, voffA);
;             PG8_WAIT_V(8); PG8_WAIT_L(0); PG8_BAR; PG8_MMA(0, 0, At, B0); PG8_MMA(0, 1, At, B1); PG8_BAR; PG8_SCHED;
	s_setprio 1
	s_waitcnt lgkmcnt(0)
	v_mfma_f32_16x16x32_bf16 v[62:65], v[130:133], v[172:175], v[62:65]
	v_mfma_f32_16x16x32_bf16 v[54:57], v[138:141], v[172:175], v[54:57]
	v_mfma_f32_16x16x32_bf16 v[46:49], v[130:133], v[186:189], v[46:49]
	v_mfma_f32_16x16x32_bf16 v[38:41], v[138:141], v[186:189], v[38:41]
	v_mfma_f32_16x16x32_bf16 v[30:33], v[130:133], v[194:197], v[30:33]
	v_mfma_f32_16x16x32_bf16 v[22:25], v[138:141], v[194:197], v[22:25]
	v_mfma_f32_16x16x32_bf16 v[14:17], v[130:133], v[202:205], v[14:17]
	v_mfma_f32_16x16x32_bf16 v[6:9], v[138:141], v[202:205], v[6:9]
	v_mfma_f32_16x16x32_bf16 v[62:65], v[134:137], v[176:179], v[62:65]
	v_mfma_f32_16x16x32_bf16 v[54:57], v[142:145], v[176:179], v[54:57]
	v_mfma_f32_16x16x32_bf16 v[46:49], v[134:137], v[190:193], v[46:49]
	v_mfma_f32_16x16x32_bf16 v[38:41], v[142:145], v[190:193], v[38:41]
	v_mfma_f32_16x16x32_bf16 v[30:33], v[134:137], v[198:201], v[30:33]
	v_mfma_f32_16x16x32_bf16 v[22:25], v[142:145], v[198:201], v[22:25]
	v_mfma_f32_16x16x32_bf16 v[14:17], v[134:137], v[206:209], v[14:17]
	v_mfma_f32_16x16x32_bf16 v[6:9], v[142:145], v[206:209], v[6:9]
	s_setprio 0
	s_setprio 1
	v_mfma_f32_16x16x32_bf16 v[58:61], v[146:149], v[172:175], v[58:61]
	v_mfma_f32_16x16x32_bf16 v[50:53], v[164:167], v[172:175], v[50:53]
	v_mfma_f32_16x16x32_bf16 v[42:45], v[146:149], v[186:189], v[42:45]
	v_mfma_f32_16x16x32_bf16 v[34:37], v[164:167], v[186:189], v[34:37]
	v_mfma_f32_16x16x32_bf16 v[26:29], v[146:149], v[194:197], v[26:29]
	v_mfma_f32_16x16x32_bf16 v[18:21], v[164:167], v[194:197], v[18:21]
	v_mfma_f32_16x16x32_bf16 v[10:13], v[146:149], v[202:205], v[10:13]
	v_mfma_f32_16x16x32_bf16 v[2:5], v[164:167], v[202:205], v[2:5]
	v_mfma_f32_16x16x32_bf16 v[58:61], v[150:153], v[176:179], v[58:61]
	v_mfma_f32_16x16x32_bf16 v[50:53], v[168:171], v[176:179], v[50:53]
	v_mfma_f32_16x16x32_bf16 v[42:45], v[150:153], v[190:193], v[42:45]
	v_mfma_f32_16x16x32_bf16 v[34:37], v[168:171], v[190:193], v[34:37]
	v_mfma_f32_16x16x32_bf16 v[26:29], v[150:153], v[198:201], v[26:29]
	s_setprio 2
	s_barrier
	v_mfma_f32_16x16x32_bf16 v[18:21], v[168:171], v[198:201], v[18:21]
	v_mfma_f32_16x16x32_bf16 v[10:13], v[150:153], v[206:209], v[10:13]
	v_mfma_f32_16x16x32_bf16 v[2:5], v[168:171], v[206:209], v[2:5]
	s_setprio 0
	s_add_i32 s6, 0, 0x18000
	s_add_i32 s12, 0, 0x1c000
	v_add_u32_e32 v142, s6, v184
	v_add_u32_e32 v168, s12, v184
	ds_read_b128 v[130:133], v142
	ds_read_b128 v[134:137], v142 offset:1024
	ds_read_b128 v[138:141], v142 offset:2048
	ds_read_b128 v[142:145], v142 offset:3072
	ds_read_b128 v[146:149], v168
	ds_read_b128 v[150:153], v168 offset:1024
	ds_read_b128 v[164:167], v168 offset:2048
	ds_read_b128 v[168:171], v168 offset:3072
	s_add_u32 s14, s28, 0x80000
	s_addc_u32 s15, s29, 0
	s_mov_b32 m0, s52
	ds_read_b128 v[172:175], v185 offset:32768
	ds_read_b128 v[176:179], v185 offset:33792
	ds_read_b128 v[186:189], v185 offset:34816
	ds_read_b128 v[190:193], v185 offset:35840
	ds_read_b128 v[194:197], v185 offset:36864
	ds_read_b128 v[198:201], v185 offset:37888
	ds_read_b128 v[202:205], v185 offset:38912
	ds_read_b128 v[206:209], v185 offset:39936
	global_load_lds_dwordx4 v158, s[14:15]
	s_mov_b32 m0, s53
	s_nop 0
	global_load_lds_dwordx4 v156, s[14:15]
	s_waitcnt vmcnt(8)
	s_waitcnt lgkmcnt(0)
	s_barrier
	s_setprio 1
	s_waitcnt lgkmcnt(0)
	v_mfma_f32_16x16x32_bf16 v[122:125], v[130:133], v[172:175], v[122:125]
	v_mfma_f32_16x16x32_bf16 v[118:121], v[138:141], v[172:175], v[118:121]
	v_mfma_f32_16x16x32_bf16 v[110:113], v[130:133], v[186:189], v[110:113]
	v_mfma_f32_16x16x32_bf16 v[102:105], v[138:141], v[186:189], v[102:105]
	v_mfma_f32_16x16x32_bf16 v[94:97], v[130:133], v[194:197], v[94:97]
	v_mfma_f32_16x16x32_bf16 v[86:89], v[138:141], v[194:197], v[86:89]
	v_mfma_f32_16x16x32_bf16 v[78:81], v[130:133], v[202:205], v[78:81]
	v_mfma_f32_16x16x32_bf16 v[70:73], v[138:141], v[202:205], v[70:73]
	v_mfma_f32_16x16x32_bf16 v[122:125], v[134:137], v[176:179], v[122:125]
	v_mfma_f32_16x16x32_bf16 v[118:121], v[142:145], v[176:179], v[118:121]
	v_mfma_f32_16x16x32_bf16 v[110:113], v[134:137], v[190:193], v[110:113]
	v_mfma_f32_16x16x32_bf16 v[102:105], v[142:145], v[190:193], v[102:105]
	v_mfma_f32_16x16x32_bf16 v[94:97], v[134:137], v[198:201], v[94:97]
	v_mfma_f32_16x16x32_bf16 v[86:89], v[142:145], v[198:201], v[86:89]
	v_mfma_f32_16x16x32_bf16 v[78:81], v[134:137], v[206:209], v[78:81]
	v_mfma_f32_16x16x32_bf16 v[70:73], v[142:145], v[206:209], v[70:73]
	s_setprio 0
	s_setprio 1
	v_mfma_f32_16x16x32_bf16 v[114:117], v[146:149], v[172:175], v[114:117]
	v_mfma_f32_16x16x32_bf16 v[126:129], v[164:167], v[172:175], v[126:129]
	v_mfma_f32_16x16x32_bf16 v[106:109], v[146:149], v[186:189], v[106:109]
	v_mfma_f32_16x16x32_bf16 v[98:101], v[164:167], v[186:189], v[98:101]
	v_mfma_f32_16x16x32_bf16 v[90:93], v[146:149], v[194:197], v[90:93]
	v_mfma_f32_16x16x32_bf16 v[82:85], v[164:167], v[194:197], v[82:85]
	v_mfma_f32_16x16x32_bf16 v[74:77], v[146:149], v[202:205], v[74:77]
	v_mfma_f32_16x16x32_bf16 v[66:69], v[164:167], v[202:205], v[66:69]
	v_mfma_f32_16x16x32_bf16 v[114:117], v[150:153], v[176:179], v[114:117]
	v_mfma_f32_16x16x32_bf16 v[126:129], v[168:171], v[176:179], v[126:129]
	v_mfma_f32_16x16x32_bf16 v[106:109], v[150:153], v[190:193], v[106:109]
	v_mfma_f32_16x16x32_bf16 v[98:101], v[168:171], v[190:193], v[98:101]
	v_mfma_f32_16x16x32_bf16 v[90:93], v[150:153], v[198:201], v[90:93]
	s_setprio 2
	s_barrier
; #define PG8_STAGE(bufoff, gbase, voff) do { _Pragma("unroll") for (int _i = 0; _i < 2; ++_i) \
;         __builtin_amdgcn_global_load_lds((const unsigned*)((const char*)(gbase) + (voff)[_i]), (LAS unsigned*)(lds + (bufoff) + ldsw + _i * 8192), 16, 0, 0); } while (0)
; #define PG8_LDA(dst, b, h) do { _Pragma("unroll") for (int m = 0; m < 4; ++m) _Pragma("unroll") for (int k = 0; k < 2; ++k) dst[m][k] = *(const LAS bf16x8*)(lds + PG8_SA(b, h) + aoff + m * 2048 + k * 1024); } while (0)
; #define PG8_MMA(ai, bj, At, Bt) do { __builtin_amdgcn_s_setprio(1); _Pragma("unroll") for (int m = 0; m < 4; ++m) _Pragma("unroll") for (int n = 0; n < 2; ++n) _Pragma("unroll") for (int k = 0; k < 2; ++k) \
;         acc[ai][bj][m][n] = __builtin_amdgcn_mfma_f32_16x16x32_bf16(Bt[n][k], At[m][k], acc[ai][bj][m][n], 0, 0, 0); __builtin_amdgcn_s_setprio(0); } while (0)
; #define PG8_WAIT_V(n) asm volatile("s_waitcnt vmcnt(" #n ")" ::: "memory")
; #define PG8_WAIT_L(n) asm volatile("s_waitcnt lgkmcnt(" #n ")" ::: "memory")
; #define PG8_BAR __builtin_amdgcn_s_barrier()
; #define PG8_SCHED __builtin_amdgcn_sched_barrier(0)
; template <class Epi>
; __device__ __forceinline__ void gemm_phase(LAS unsigned char* lds, const Gemm g, const TileOrder& S, const Epi& E) {
;     ...
;             PG8_WAIT_V(8); PG8_WAIT_L(0); PG8_BAR; PG8_MMA(0, 0, At, B0); PG8_MMA(0, 1, At, B1); PG8_BAR; PG8_SCHED;
;             PG8_LDA(At, 1, 1); PG8_STAGE(PG8_SB(1, 0), b3, voffB); PG8_STAGE(PG8_SB(1, 1), b3 + hstepB, voffB); PG8_STAGE(PG8_SA(1, 0), a3, voffA);
;             PG8_WAIT_V(8); PG8_WAIT_L(0); PG8_BAR; PG8_MMA(1, 0, At, B0); PG8_MMA(1, 1, At, B1); PG8_BAR; PG8_SCHED;
;         }
;         if (wr == 0) PG8_BAR;
	v_mfma_f32_16x16x32_bf16 v[82:85], v[168:171], v[198:201], v[82:85]
	v_mfma_f32_16x16x32_bf16 v[74:77], v[150:153], v[206:209], v[74:77]
	v_mfma_f32_16x16x32_bf16 v[66:69], v[168:171], v[206:209], v[66:69]
	s_setprio 0
	s_add_i32 s6, s6, s31
	v_lshl_add_u64 v[180:181], v[180:181], 0, s[34:35]
	s_mov_b32 m0, s6
	ds_read_b128 v[172:175], v185 offset:49152
	ds_read_b128 v[176:179], v185 offset:50176
	ds_read_b128 v[186:189], v185 offset:51200
	ds_read_b128 v[190:193], v185 offset:52224
	ds_read_b128 v[194:197], v185 offset:53248
	ds_read_b128 v[198:201], v185 offset:54272
	ds_read_b128 v[202:205], v185 offset:55296
	ds_read_b128 v[206:209], v185 offset:56320
	global_load_lds_dwordx4 v[180:181], off
	s_add_i32 m0, s6, 0x2000
	s_add_u32 s2, s2, 0x80080
	v_lshl_add_u64 v[180:181], v[210:211], 0, s[34:35]
	s_addc_u32 s3, s3, 0
	s_add_i32 s6, s12, s31
	global_load_lds_dwordx4 v[180:181], off
	s_mov_b32 m0, s6
	s_nop 0
	global_load_lds_dwordx4 v0, s[2:3]
	v_lshl_add_u64 v[180:181], s[2:3], 0, v[154:155]
	s_add_i32 m0, s6, 0x2000
	s_nop 0
	global_load_lds_dwordx4 v[180:181], off
	v_lshl_add_u64 v[180:181], v[212:213], 0, s[34:35]
	s_mov_b32 m0, s58
	s_nop 0
	global_load_lds_dwordx4 v[180:181], off
	v_lshl_add_u64 v[180:181], v[214:215], 0, s[34:35]
	s_mov_b32 m0, s59
	s_nop 0
	global_load_lds_dwordx4 v[180:181], off
	s_waitcnt vmcnt(8)
	s_waitcnt lgkmcnt(0)
	s_barrier
	s_setprio 1
	s_waitcnt lgkmcnt(0)
	v_mfma_f32_16x16x32_bf16 v[62:65], v[130:133], v[172:175], v[62:65]
	v_mfma_f32_16x16x32_bf16 v[54:57], v[138:141], v[172:175], v[54:57]
	v_mfma_f32_16x16x32_bf16 v[46:49], v[130:133], v[186:189], v[46:49]
	v_mfma_f32_16x16x32_bf16 v[38:41], v[138:141], v[186:189], v[38:41]
	v_mfma_f32_16x16x32_bf16 v[30:33], v[130:133], v[194:197], v[30:33]
	v_mfma_f32_16x16x32_bf16 v[22:25], v[138:141], v[194:197], v[22:25]
	v_mfma_f32_16x16x32_bf16 v[14:17], v[130:133], v[202:205], v[14:17]
	v_mfma_f32_16x16x32_bf16 v[6:9], v[138:141], v[202:205], v[6:9]
	v_mfma_f32_16x16x32_bf16 v[62:65], v[134:137], v[176:179], v[62:65]
	v_mfma_f32_16x16x32_bf16 v[54:57], v[142:145], v[176:179], v[54:57]
	v_mfma_f32_16x16x32_bf16 v[46:49], v[134:137], v[190:193], v[46:49]
	v_mfma_f32_16x16x32_bf16 v[38:41], v[142:145], v[190:193], v[38:41]
	v_mfma_f32_16x16x32_bf16 v[30:33], v[134:137], v[198:201], v[30:33]
	v_mfma_f32_16x16x32_bf16 v[22:25], v[142:145], v[198:201], v[22:25]
	v_mfma_f32_16x16x32_bf16 v[14:17], v[134:137], v[206:209], v[14:17]
	v_mfma_f32_16x16x32_bf16 v[6:9], v[142:145], v[206:209], v[6:9]
	s_setprio 0
	s_setprio 1
	v_mfma_f32_16x16x32_bf16 v[58:61], v[146:149], v[172:175], v[58:61]
	v_mfma_f32_16x16x32_bf16 v[50:53], v[164:167], v[172:175], v[50:53]
	v_mfma_f32_16x16x32_bf16 v[42:45], v[146:149], v[186:189], v[42:45]
	v_mfma_f32_16x16x32_bf16 v[34:37], v[164:167], v[186:189], v[34:37]
	v_mfma_f32_16x16x32_bf16 v[26:29], v[146:149], v[194:197], v[26:29]
	v_mfma_f32_16x16x32_bf16 v[18:21], v[164:167], v[194:197], v[18:21]
	v_mfma_f32_16x16x32_bf16 v[10:13], v[146:149], v[202:205], v[10:13]
	v_mfma_f32_16x16x32_bf16 v[2:5], v[164:167], v[202:205], v[2:5]
	v_mfma_f32_16x16x32_bf16 v[58:61], v[150:153], v[176:179], v[58:61]
	v_mfma_f32_16x16x32_bf16 v[50:53], v[168:171], v[176:179], v[50:53]
	v_mfma_f32_16x16x32_bf16 v[42:45], v[150:153], v[190:193], v[42:45]
	v_mfma_f32_16x16x32_bf16 v[34:37], v[168:171], v[190:193], v[34:37]
	v_mfma_f32_16x16x32_bf16 v[26:29], v[150:153], v[198:201], v[26:29]
	s_setprio 2
	s_barrier
	v_mfma_f32_16x16x32_bf16 v[18:21], v[168:171], v[198:201], v[18:21]
	v_mfma_f32_16x16x32_bf16 v[10:13], v[150:153], v[206:209], v[10:13]
	v_mfma_f32_16x16x32_bf16 v[2:5], v[168:171], v[206:209], v[2:5]
	s_setprio 0
	s_add_i32 s66, s66, 2
	s_add_u32 s4, s4, 0x100
	s_addc_u32 s5, s5, 0
	s_add_u32 s64, s64, 0x100
	s_addc_u32 s65, s65, 0
	s_cmp_gt_u32 s66, 29
	s_cbranch_scc0 .LBB0_668
	s_and_b64 vcc, exec, s[38:39]
	s_cbranch_vccz .LBB0_671
	s_barrier

; #define PG8_STAGE(bufoff, gbase, voff) do { _Pragma("unroll") for (int _i = 0; _i < 2; ++_i) \
;         __builtin_amdgcn_global_load_lds((const unsigned*)((const char*)(gbase) + (voff)[_i]), (LAS unsigned*)(lds + (bufoff) + ldsw + _i * 8192), 16, 0, 0); } while (0)
; #define PG8_LDA(dst, b, h) do { _Pragma("unroll") for (int m = 0; m < 4; ++m) _Pragma("unroll") for (int k = 0; k < 2; ++k) dst[m][k] = *(const LAS bf16x8*)(lds + PG8_SA(b, h) + aoff + m * 2048 + k * 1024); } while (0)
; #define PG8_LDB(dst, b, h) do { _Pragma("unroll") for (int n = 0; n < 2; ++n) _Pragma("unroll") for (int k = 0; k < 2; ++k) dst[n][k] = *(const LAS bf16x8*)(lds + PG8_SB(b, h) + boff + n * 2048 + k * 1024); } while (0)
; #define PG8_MMA(ai, bj, At, Bt) do { __builtin_amdgcn_s_setprio(1); _Pragma("unroll") for (int m = 0; m < 4; ++m) _Pragma("unroll") for (int n = 0; n < 2; ++n) _Pragma("unroll") for (int k = 0; k < 2; ++k) \
;         acc[ai][bj][m][n] = __builtin_amdgcn_mfma_f32_16x16x32_bf16(Bt[n][k], At[m][k], acc[ai][bj][m][n], 0, 0, 0); __builtin_amdgcn_s_setprio(0); } while (0)
; #define PG8_WAIT_V(n) asm volatile("s_waitcnt vmcnt(" #n ")" ::: "memory")
; #define PG8_WAIT_L(n) asm volatile("s_waitcnt lgkmcnt(" #n ")" ::: "memory")
; #define PG8_BAR __builtin_amdgcn_s_barrier()
; #define PG8_SCHED __builtin_amdgcn_sched_barrier(0)
; template <class Epi>
; __device__ __forceinline__ void gemm_phase(LAS unsigned char* lds, const Gemm g, const TileOrder& S, const Epi& E) {
;     ...
;         for (int t = 0; t < nt; t += 2) {
;             const bool last = (t == nt - 2);
;             const char* a1 = cA + (size_t)(t + 1) * kstepA;
;             const char* a2 = last ? nA : cA + (size_t)(t + 2) * kstepA; const char* b2 = last ? nB : cB + (size_t)(t + 2) * kstep;
;             const char* a3 = a2 + kstepA; const char* b3 = b2 + kstep;
;             PG8_LDB(B0, 0, 0); PG8_LDB(B1, 0, 1); PG8_SCHED; PG8_LDA(At, 0, 0); PG8_STAGE(PG8_SA(1, 1), a1 + hstepA, voffA);
;             PG8_WAIT_V(8); PG8_WAIT_L(0); PG8_BAR; PG8_MMA(0, 0, At, B0); PG8_MMA(0, 1, At, B1); PG8_BAR; PG8_SCHED;
;             PG8_LDA(At, 0, 1); PG8_STAGE(PG8_SB(0, 0), b2, voffB); PG8_STAGE(PG8_SB(0, 1), b2 + hstepB, voffB); PG8_STAGE(PG8_SA(0, 0), a2, voffA);
;             PG8_WAIT_V(8); PG8_WAIT_L(0); PG8_BAR; PG8_MMA(1, 0, At, B0); PG8_MMA(1, 1, At, B1); PG8_BAR; PG8_SCHED;
.LBB0_757:
	s_mov_b32 s6, 0x10000
	v_add_u32_e32 v0, s6, v154
	s_mov_b32 s14, 0x14000
	ds_read_b128 v[142:145], v0
	ds_read_b128 v[146:149], v0 offset:1024
	ds_read_b128 v[156:159], v0 offset:2048
	ds_read_b128 v[160:163], v0 offset:3072
	v_add_u32_e32 v0, s14, v154
	ds_read_b128 v[164:167], v0
	ds_read_b128 v[168:171], v0 offset:1024
	ds_read_b128 v[172:175], v0 offset:2048
	ds_read_b128 v[176:179], v0 offset:3072
	ds_read_b128 v[180:183], v155
	ds_read_b128 v[184:187], v155 offset:1024
	ds_read_b128 v[188:191], v155 offset:2048
	ds_read_b128 v[192:195], v155 offset:3072
	ds_read_b128 v[196:199], v155 offset:4096
	ds_read_b128 v[200:203], v155 offset:5120
	ds_read_b128 v[204:207], v155 offset:6144
	ds_read_b128 v[208:211], v155 offset:7168
	s_add_u32 s2, s28, 0xfff80080
	s_addc_u32 s3, s29, -1
	s_cmp_eq_u32 s72, 28
	s_cselect_b32 s31, s47, s3
	s_cselect_b32 s30, s51, s2
	s_cselect_b32 s3, s49, s71
	s_cselect_b32 s2, s69, s70
	s_add_i32 m0, s59, 0xc000
	s_nop 0
	global_load_lds_dwordx4 v138, s[28:29]
	s_add_i32 m0, s59, 0xe000
	s_nop 0
	global_load_lds_dwordx4 v140, s[28:29]
	s_waitcnt vmcnt(8)
	s_waitcnt lgkmcnt(0)
	s_barrier
	s_setprio 1
	s_waitcnt lgkmcnt(0)
	v_mfma_f32_16x16x32_bf16 v[126:129], v[142:145], v[180:183], v[126:129]
	v_mfma_f32_16x16x32_bf16 v[122:125], v[156:159], v[180:183], v[122:125]
	v_mfma_f32_16x16x32_bf16 v[110:113], v[142:145], v[188:191], v[110:113]
	v_mfma_f32_16x16x32_bf16 v[106:109], v[156:159], v[188:191], v[106:109]
	v_mfma_f32_16x16x32_bf16 v[94:97], v[142:145], v[196:199], v[94:97]
	v_mfma_f32_16x16x32_bf16 v[90:93], v[156:159], v[196:199], v[90:93]
	v_mfma_f32_16x16x32_bf16 v[78:81], v[142:145], v[204:207], v[78:81]
	v_mfma_f32_16x16x32_bf16 v[74:77], v[156:159], v[204:207], v[74:77]
	v_mfma_f32_16x16x32_bf16 v[126:129], v[146:149], v[184:187], v[126:129]
	v_mfma_f32_16x16x32_bf16 v[122:125], v[160:163], v[184:187], v[122:125]
	v_mfma_f32_16x16x32_bf16 v[110:113], v[146:149], v[192:195], v[110:113]
	v_mfma_f32_16x16x32_bf16 v[106:109], v[160:163], v[192:195], v[106:109]
	v_mfma_f32_16x16x32_bf16 v[94:97], v[146:149], v[200:203], v[94:97]
	v_mfma_f32_16x16x32_bf16 v[90:93], v[160:163], v[200:203], v[90:93]
	v_mfma_f32_16x16x32_bf16 v[78:81], v[146:149], v[208:211], v[78:81]
	v_mfma_f32_16x16x32_bf16 v[74:77], v[160:163], v[208:211], v[74:77]
	s_setprio 0
	s_setprio 1
	v_mfma_f32_16x16x32_bf16 v[118:121], v[164:167], v[180:183], v[118:121]
	v_mfma_f32_16x16x32_bf16 v[114:117], v[172:175], v[180:183], v[114:117]
	v_mfma_f32_16x16x32_bf16 v[102:105], v[164:167], v[188:191], v[102:105]
	v_mfma_f32_16x16x32_bf16 v[98:101], v[172:175], v[188:191], v[98:101]
	v_mfma_f32_16x16x32_bf16 v[86:89], v[164:167], v[196:199], v[86:89]
	v_mfma_f32_16x16x32_bf16 v[82:85], v[172:175], v[196:199], v[82:85]
	v_mfma_f32_16x16x32_bf16 v[70:73], v[164:167], v[204:207], v[70:73]
	v_mfma_f32_16x16x32_bf16 v[66:69], v[172:175], v[204:207], v[66:69]
	v_mfma_f32_16x16x32_bf16 v[118:121], v[168:171], v[184:187], v[118:121]
	v_mfma_f32_16x16x32_bf16 v[114:117], v[176:179], v[184:187], v[114:117]
	v_mfma_f32_16x16x32_bf16 v[102:105], v[168:171], v[192:195], v[102:105]
	v_mfma_f32_16x16x32_bf16 v[98:101], v[176:179], v[192:195], v[98:101]
	v_mfma_f32_16x16x32_bf16 v[86:89], v[168:171], v[200:203], v[86:89]
	s_setprio 2
	s_barrier
	v_mfma_f32_16x16x32_bf16 v[82:85], v[176:179], v[200:203], v[82:85]
	v_mfma_f32_16x16x32_bf16 v[70:73], v[168:171], v[208:211], v[70:73]
	v_mfma_f32_16x16x32_bf16 v[66:69], v[176:179], v[208:211], v[66:69]
	s_setprio 0
	s_add_i32 s6, s6, s58
	v_lshl_add_u64 v[150:151], s[2:3], 0, v[134:135]
	s_mov_b32 m0, s6
	ds_read_b128 v[180:183], v155 offset:16384
	ds_read_b128 v[184:187], v155 offset:17408
	ds_read_b128 v[188:191], v155 offset:18432
	ds_read_b128 v[192:195], v155 offset:19456
	ds_read_b128 v[196:199], v155 offset:20480
	ds_read_b128 v[200:203], v155 offset:21504
	ds_read_b128 v[204:207], v155 offset:22528
	ds_read_b128 v[208:211], v155 offset:23552
	global_load_lds_dwordx4 v[150:151], off
	s_add_i32 m0, s6, 0x2000
	s_add_u32 s12, s2, 0x80000
	v_lshl_add_u64 v[212:213], s[2:3], 0, v[130:131]
	s_addc_u32 s13, s3, 0
	s_add_i32 s6, s14, s58
	global_load_lds_dwordx4 v[212:213], off
	s_mov_b32 m0, s6
	v_lshl_add_u64 v[216:217], s[30:31], 0, v[132:133]
	global_load_lds_dwordx4 v134, s[12:13]
	s_add_i32 m0, s6, 0x2000
	s_nop 0
	global_load_lds_dwordx4 v130, s[12:13]
	v_lshl_add_u64 v[214:215], s[30:31], 0, v[136:137]
	s_mov_b32 m0, s59
	s_nop 0
	global_load_lds_dwordx4 v[214:215], off
	s_mov_b32 m0, s60
	s_nop 0
	global_load_lds_dwordx4 v[216:217], off
	s_waitcnt vmcnt(8)
	s_waitcnt lgkmcnt(0)
	s_barrier
; #define PG8_STAGE(bufoff, gbase, voff) do { _Pragma("unroll") for (int _i = 0; _i < 2; ++_i) \
;         __builtin_amdgcn_global_load_lds((const unsigned*)((const char*)(gbase) + (voff)[_i]), (LAS unsigned*)(lds + (bufoff) + ldsw + _i * 8192), 16, 0, 0); } while (0)
; #define PG8_LDA(dst, b, h) do { _Pragma("unroll") for (int m = 0; m < 4; ++m) _Pragma("unroll") for (int k = 0; k < 2; ++k) dst[m][k] = *(const LAS bf16x8*)(lds + PG8_SA(b, h) + aoff + m * 2048 + k * 1024); } while (0)
; #define PG8_LDB(dst, b, h) do { _Pragma("unroll") for (int n = 0; n < 2; ++n) _Pragma("unroll") for (int k = 0; k < 2; ++k) dst[n][k] = *(const LAS bf16x8*)(lds + PG8_SB(b, h) + boff + n * 2048 + k * 1024); } while (0)
; #define PG8_MMA(ai, bj, At, Bt) do { __builtin_amdgcn_s_setprio(1); _Pragma("unroll") for (int m = 0; m < 4; ++m) _Pragma("unroll") for (int n = 0; n < 2; ++n) _Pragma("unroll") for (int k = 0; k < 2; ++k) \
;         acc[ai][bj][m][n] = __builtin_amdgcn_mfma_f32_16x16x32_bf16(Bt[n][k], At[m][k], acc[ai][bj][m][n], 0, 0, 0); __builtin_amdgcn_s_setprio(0); } while (0)
; #define PG8_WAIT_V(n) asm volatile("s_waitcnt vmcnt(" #n ")" ::: "memory")
; #define PG8_WAIT_L(n) asm volatile("s_waitcnt lgkmcnt(" #n ")" ::: "memory")
; #define PG8_BAR __builtin_amdgcn_s_barrier()
; #define PG8_SCHED __builtin_amdgcn_sched_barrier(0)
; template <class Epi>
; __device__ __forceinline__ void gemm_phase(LAS unsigned char* lds, const Gemm g, const TileOrder& S, const Epi& E) {
;     ...
;             PG8_WAIT_V(8); PG8_WAIT_L(0); PG8_BAR; PG8_MMA(1, 0, At, B0); PG8_MMA(1, 1, At, B1); PG8_BAR; PG8_SCHED;
;             PG8_LDB(B0, 1, 0); PG8_LDB(B1, 1, 1); PG8_SCHED; PG8_LDA(At, 1, 0); PG8_STAGE(PG8_SA(0, 1), a2 + hstepA, voffA);
;             PG8_WAIT_V(8); PG8_WAIT_L(0); PG8_BAR; PG8_MMA(0, 0, At, B0); PG8_MMA(0, 1, At, B1); PG8_BAR; PG8_SCHED;
	s_setprio 1
	s_waitcnt lgkmcnt(0)
	v_mfma_f32_16x16x32_bf16 v[62:65], v[142:145], v[180:183], v[62:65]
	v_mfma_f32_16x16x32_bf16 v[58:61], v[156:159], v[180:183], v[58:61]
	v_mfma_f32_16x16x32_bf16 v[46:49], v[142:145], v[188:191], v[46:49]
	v_mfma_f32_16x16x32_bf16 v[42:45], v[156:159], v[188:191], v[42:45]
	v_mfma_f32_16x16x32_bf16 v[30:33], v[142:145], v[196:199], v[30:33]
	v_mfma_f32_16x16x32_bf16 v[26:29], v[156:159], v[196:199], v[26:29]
	v_mfma_f32_16x16x32_bf16 v[14:17], v[142:145], v[204:207], v[14:17]
	v_mfma_f32_16x16x32_bf16 v[10:13], v[156:159], v[204:207], v[10:13]
	v_mfma_f32_16x16x32_bf16 v[62:65], v[146:149], v[184:187], v[62:65]
	v_mfma_f32_16x16x32_bf16 v[58:61], v[160:163], v[184:187], v[58:61]
	v_mfma_f32_16x16x32_bf16 v[46:49], v[146:149], v[192:195], v[46:49]
	v_mfma_f32_16x16x32_bf16 v[42:45], v[160:163], v[192:195], v[42:45]
	v_mfma_f32_16x16x32_bf16 v[30:33], v[146:149], v[200:203], v[30:33]
	v_mfma_f32_16x16x32_bf16 v[26:29], v[160:163], v[200:203], v[26:29]
	v_mfma_f32_16x16x32_bf16 v[14:17], v[146:149], v[208:211], v[14:17]
	v_mfma_f32_16x16x32_bf16 v[10:13], v[160:163], v[208:211], v[10:13]
	s_setprio 0
	s_setprio 1
	v_mfma_f32_16x16x32_bf16 v[54:57], v[164:167], v[180:183], v[54:57]
	v_mfma_f32_16x16x32_bf16 v[50:53], v[172:175], v[180:183], v[50:53]
	v_mfma_f32_16x16x32_bf16 v[38:41], v[164:167], v[188:191], v[38:41]
	v_mfma_f32_16x16x32_bf16 v[34:37], v[172:175], v[188:191], v[34:37]
	v_mfma_f32_16x16x32_bf16 v[22:25], v[164:167], v[196:199], v[22:25]
	v_mfma_f32_16x16x32_bf16 v[18:21], v[172:175], v[196:199], v[18:21]
	v_mfma_f32_16x16x32_bf16 v[6:9], v[164:167], v[204:207], v[6:9]
	v_mfma_f32_16x16x32_bf16 v[2:5], v[172:175], v[204:207], v[2:5]
	v_mfma_f32_16x16x32_bf16 v[54:57], v[168:171], v[184:187], v[54:57]
	v_mfma_f32_16x16x32_bf16 v[50:53], v[176:179], v[184:187], v[50:53]
	v_mfma_f32_16x16x32_bf16 v[38:41], v[168:171], v[192:195], v[38:41]
	v_mfma_f32_16x16x32_bf16 v[34:37], v[176:179], v[192:195], v[34:37]
	v_mfma_f32_16x16x32_bf16 v[22:25], v[168:171], v[200:203], v[22:25]
	s_setprio 2
	s_barrier
	v_mfma_f32_16x16x32_bf16 v[18:21], v[176:179], v[200:203], v[18:21]
	v_mfma_f32_16x16x32_bf16 v[6:9], v[168:171], v[208:211], v[6:9]
	v_mfma_f32_16x16x32_bf16 v[2:5], v[176:179], v[208:211], v[2:5]
	s_setprio 0
	s_add_i32 s6, 0, 0x18000
	v_add_u32_e32 v0, s6, v154
	s_add_i32 s14, 0, 0x1c000
	ds_read_b128 v[142:145], v0
	ds_read_b128 v[146:149], v0 offset:1024
	ds_read_b128 v[156:159], v0 offset:2048
	ds_read_b128 v[160:163], v0 offset:3072
	v_add_u32_e32 v0, s14, v154
	ds_read_b128 v[164:167], v0
	ds_read_b128 v[168:171], v0 offset:1024
	ds_read_b128 v[172:175], v0 offset:2048
	ds_read_b128 v[176:179], v0 offset:3072
	s_add_u32 s12, s30, 0x80000
	s_addc_u32 s13, s31, 0
	s_mov_b32 m0, s61
	ds_read_b128 v[180:183], v155 offset:32768
	ds_read_b128 v[184:187], v155 offset:33792
	ds_read_b128 v[188:191], v155 offset:34816
	ds_read_b128 v[192:195], v155 offset:35840
	ds_read_b128 v[196:199], v155 offset:36864
	ds_read_b128 v[200:203], v155 offset:37888
	ds_read_b128 v[204:207], v155 offset:38912
	ds_read_b128 v[208:211], v155 offset:39936
	global_load_lds_dwordx4 v136, s[12:13]
	s_mov_b32 m0, s62
	s_nop 0
	global_load_lds_dwordx4 v132, s[12:13]
	s_waitcnt vmcnt(8)
	s_waitcnt lgkmcnt(0)
	s_barrier
	s_setprio 1
	s_waitcnt lgkmcnt(0)
	v_mfma_f32_16x16x32_bf16 v[126:129], v[142:145], v[180:183], v[126:129]
	v_mfma_f32_16x16x32_bf16 v[122:125], v[156:159], v[180:183], v[122:125]
	v_mfma_f32_16x16x32_bf16 v[110:113], v[142:145], v[188:191], v[110:113]
	v_mfma_f32_16x16x32_bf16 v[106:109], v[156:159], v[188:191], v[106:109]
	v_mfma_f32_16x16x32_bf16 v[94:97], v[142:145], v[196:199], v[94:97]
	v_mfma_f32_16x16x32_bf16 v[90:93], v[156:159], v[196:199], v[90:93]
	v_mfma_f32_16x16x32_bf16 v[78:81], v[142:145], v[204:207], v[78:81]
	v_mfma_f32_16x16x32_bf16 v[74:77], v[156:159], v[204:207], v[74:77]
	v_mfma_f32_16x16x32_bf16 v[126:129], v[146:149], v[184:187], v[126:129]
	v_mfma_f32_16x16x32_bf16 v[122:125], v[160:163], v[184:187], v[122:125]
	v_mfma_f32_16x16x32_bf16 v[110:113], v[146:149], v[192:195], v[110:113]
	v_mfma_f32_16x16x32_bf16 v[106:109], v[160:163], v[192:195], v[106:109]
	v_mfma_f32_16x16x32_bf16 v[94:97], v[146:149], v[200:203], v[94:97]
	v_mfma_f32_16x16x32_bf16 v[90:93], v[160:163], v[200:203], v[90:93]
	v_mfma_f32_16x16x32_bf16 v[78:81], v[146:149], v[208:211], v[78:81]
	v_mfma_f32_16x16x32_bf16 v[74:77], v[160:163], v[208:211], v[74:77]
	s_setprio 0
	s_setprio 1
	v_mfma_f32_16x16x32_bf16 v[118:121], v[164:167], v[180:183], v[118:121]
	v_mfma_f32_16x16x32_bf16 v[114:117], v[172:175], v[180:183], v[114:117]
	v_mfma_f32_16x16x32_bf16 v[102:105], v[164:167], v[188:191], v[102:105]
	v_mfma_f32_16x16x32_bf16 v[98:101], v[172:175], v[188:191], v[98:101]
	v_mfma_f32_16x16x32_bf16 v[86:89], v[164:167], v[196:199], v[86:89]
	v_mfma_f32_16x16x32_bf16 v[82:85], v[172:175], v[196:199], v[82:85]
	v_mfma_f32_16x16x32_bf16 v[70:73], v[164:167], v[204:207], v[70:73]
	v_mfma_f32_16x16x32_bf16 v[66:69], v[172:175], v[204:207], v[66:69]
	v_mfma_f32_16x16x32_bf16 v[118:121], v[168:171], v[184:187], v[118:121]
	v_mfma_f32_16x16x32_bf16 v[114:117], v[176:179], v[184:187], v[114:117]
	v_mfma_f32_16x16x32_bf16 v[102:105], v[168:171], v[192:195], v[102:105]
	v_mfma_f32_16x16x32_bf16 v[98:101], v[176:179], v[192:195], v[98:101]
	v_mfma_f32_16x16x32_bf16 v[86:89], v[168:171], v[200:203], v[86:89]
	s_setprio 2
	s_barrier
; #define PG8_STAGE(bufoff, gbase, voff) do { _Pragma("unroll") for (int _i = 0; _i < 2; ++_i) \
;         __builtin_amdgcn_global_load_lds((const unsigned*)((const char*)(gbase) + (voff)[_i]), (LAS unsigned*)(lds + (bufoff) + ldsw + _i * 8192), 16, 0, 0); } while (0)
; #define PG8_LDA(dst, b, h) do { _Pragma("unroll") for (int m = 0; m < 4; ++m) _Pragma("unroll") for (int k = 0; k < 2; ++k) dst[m][k] = *(const LAS bf16x8*)(lds + PG8_SA(b, h) + aoff + m * 2048 + k * 1024); } while (0)
; #define PG8_MMA(ai, bj, At, Bt) do { __builtin_amdgcn_s_setprio(1); _Pragma("unroll") for (int m = 0; m < 4; ++m) _Pragma("unroll") for (int n = 0; n < 2; ++n) _Pragma("unroll") for (int k = 0; k < 2; ++k) \
;         acc[ai][bj][m][n] = __builtin_amdgcn_mfma_f32_16x16x32_bf16(Bt[n][k], At[m][k], acc[ai][bj][m][n], 0, 0, 0); __builtin_amdgcn_s_setprio(0); } while (0)
; #define PG8_WAIT_V(n) asm volatile("s_waitcnt vmcnt(" #n ")" ::: "memory")
; #define PG8_WAIT_L(n) asm volatile("s_waitcnt lgkmcnt(" #n ")" ::: "memory")
; #define PG8_BAR __builtin_amdgcn_s_barrier()
; #define PG8_SCHED __builtin_amdgcn_sched_barrier(0)
; template <class Epi>
; __device__ __forceinline__ void gemm_phase(LAS unsigned char* lds, const Gemm g, const TileOrder& S, const Epi& E) {
;     ...
;             PG8_WAIT_V(8); PG8_WAIT_L(0); PG8_BAR; PG8_MMA(0, 0, At, B0); PG8_MMA(0, 1, At, B1); PG8_BAR; PG8_SCHED;
;             PG8_LDA(At, 1, 1); PG8_STAGE(PG8_SB(1, 0), b3, voffB); PG8_STAGE(PG8_SB(1, 1), b3 + hstepB, voffB); PG8_STAGE(PG8_SA(1, 0), a3, voffA);
;             PG8_WAIT_V(8); PG8_WAIT_L(0); PG8_BAR; PG8_MMA(1, 0, At, B0); PG8_MMA(1, 1, At, B1); PG8_BAR; PG8_SCHED;
;         }
;         if (wr == 0) PG8_BAR;
	v_mfma_f32_16x16x32_bf16 v[82:85], v[176:179], v[200:203], v[82:85]
	v_mfma_f32_16x16x32_bf16 v[70:73], v[168:171], v[208:211], v[70:73]
	v_mfma_f32_16x16x32_bf16 v[66:69], v[176:179], v[208:211], v[66:69]
	s_setprio 0
	s_add_i32 s6, s6, s58
	v_lshl_add_u64 v[150:151], v[150:151], 0, s[34:35]
	s_mov_b32 m0, s6
	ds_read_b128 v[180:183], v155 offset:49152
	ds_read_b128 v[184:187], v155 offset:50176
	ds_read_b128 v[188:191], v155 offset:51200
	ds_read_b128 v[192:195], v155 offset:52224
	ds_read_b128 v[196:199], v155 offset:53248
	ds_read_b128 v[200:203], v155 offset:54272
	ds_read_b128 v[204:207], v155 offset:55296
	ds_read_b128 v[208:211], v155 offset:56320
	global_load_lds_dwordx4 v[150:151], off
	s_add_i32 m0, s6, 0x2000
	s_add_u32 s2, s2, 0x80080
	v_lshl_add_u64 v[150:151], v[212:213], 0, s[34:35]
	s_addc_u32 s3, s3, 0
	s_add_i32 s6, s14, s58
	global_load_lds_dwordx4 v[150:151], off
	s_mov_b32 m0, s6
	s_nop 0
	global_load_lds_dwordx4 v134, s[2:3]
	v_lshl_add_u64 v[150:151], s[2:3], 0, v[130:131]
	s_add_i32 m0, s6, 0x2000
	s_nop 0
	global_load_lds_dwordx4 v[150:151], off
	v_lshl_add_u64 v[150:151], v[214:215], 0, s[34:35]
	s_mov_b32 m0, s63
	s_nop 0
	global_load_lds_dwordx4 v[150:151], off
	v_lshl_add_u64 v[150:151], v[216:217], 0, s[34:35]
	s_mov_b32 m0, s64
	s_nop 0
	global_load_lds_dwordx4 v[150:151], off
	s_waitcnt vmcnt(8)
	s_waitcnt lgkmcnt(0)
	s_barrier
	s_setprio 1
	s_waitcnt lgkmcnt(0)
	v_mfma_f32_16x16x32_bf16 v[62:65], v[142:145], v[180:183], v[62:65]
	v_mfma_f32_16x16x32_bf16 v[58:61], v[156:159], v[180:183], v[58:61]
	v_mfma_f32_16x16x32_bf16 v[46:49], v[142:145], v[188:191], v[46:49]
	v_mfma_f32_16x16x32_bf16 v[42:45], v[156:159], v[188:191], v[42:45]
	v_mfma_f32_16x16x32_bf16 v[30:33], v[142:145], v[196:199], v[30:33]
	v_mfma_f32_16x16x32_bf16 v[26:29], v[156:159], v[196:199], v[26:29]
	v_mfma_f32_16x16x32_bf16 v[14:17], v[142:145], v[204:207], v[14:17]
	v_mfma_f32_16x16x32_bf16 v[10:13], v[156:159], v[204:207], v[10:13]
	v_mfma_f32_16x16x32_bf16 v[62:65], v[146:149], v[184:187], v[62:65]
	v_mfma_f32_16x16x32_bf16 v[58:61], v[160:163], v[184:187], v[58:61]
	v_mfma_f32_16x16x32_bf16 v[46:49], v[146:149], v[192:195], v[46:49]
	v_mfma_f32_16x16x32_bf16 v[42:45], v[160:163], v[192:195], v[42:45]
	v_mfma_f32_16x16x32_bf16 v[30:33], v[146:149], v[200:203], v[30:33]
	v_mfma_f32_16x16x32_bf16 v[26:29], v[160:163], v[200:203], v[26:29]
	v_mfma_f32_16x16x32_bf16 v[14:17], v[146:149], v[208:211], v[14:17]
	v_mfma_f32_16x16x32_bf16 v[10:13], v[160:163], v[208:211], v[10:13]
	s_setprio 0
	s_setprio 1
	v_mfma_f32_16x16x32_bf16 v[54:57], v[164:167], v[180:183], v[54:57]
	v_mfma_f32_16x16x32_bf16 v[50:53], v[172:175], v[180:183], v[50:53]
	v_mfma_f32_16x16x32_bf16 v[38:41], v[164:167], v[188:191], v[38:41]
	v_mfma_f32_16x16x32_bf16 v[34:37], v[172:175], v[188:191], v[34:37]
	v_mfma_f32_16x16x32_bf16 v[22:25], v[164:167], v[196:199], v[22:25]
	v_mfma_f32_16x16x32_bf16 v[18:21], v[172:175], v[196:199], v[18:21]
	v_mfma_f32_16x16x32_bf16 v[6:9], v[164:167], v[204:207], v[6:9]
	v_mfma_f32_16x16x32_bf16 v[2:5], v[172:175], v[204:207], v[2:5]
	v_mfma_f32_16x16x32_bf16 v[54:57], v[168:171], v[184:187], v[54:57]
	v_mfma_f32_16x16x32_bf16 v[50:53], v[176:179], v[184:187], v[50:53]
	v_mfma_f32_16x16x32_bf16 v[38:41], v[168:171], v[192:195], v[38:41]
	v_mfma_f32_16x16x32_bf16 v[34:37], v[176:179], v[192:195], v[34:37]
	v_mfma_f32_16x16x32_bf16 v[22:25], v[168:171], v[200:203], v[22:25]
	s_setprio 2
	s_barrier
	v_mfma_f32_16x16x32_bf16 v[18:21], v[176:179], v[200:203], v[18:21]
	v_mfma_f32_16x16x32_bf16 v[6:9], v[168:171], v[208:211], v[6:9]
	v_mfma_f32_16x16x32_bf16 v[2:5], v[176:179], v[208:211], v[2:5]
	s_setprio 0
	s_add_i32 s72, s72, 2
	s_add_u32 s28, s28, 0x100
	s_addc_u32 s29, s29, 0
	s_add_u32 s70, s70, 0x100
	s_addc_u32 s71, s71, 0
	s_cmp_gt_u32 s72, 29
	s_cbranch_scc0 .LBB0_757
	s_and_b64 vcc, exec, s[42:43]
	s_cbranch_vccz .LBB0_760
	s_barrier

; #define PG8_STAGE(bufoff, gbase, voff) do { _Pragma("unroll") for (int _i = 0; _i < 2; ++_i) \
;         __builtin_amdgcn_global_load_lds((const unsigned*)((const char*)(gbase) + (voff)[_i]), (LAS unsigned*)(lds + (bufoff) + ldsw + _i * 8192), 16, 0, 0); } while (0)
; #define PG8_LDA(dst, b, h) do { _Pragma("unroll") for (int m = 0; m < 4; ++m) _Pragma("unroll") for (int k = 0; k < 2; ++k) dst[m][k] = *(const LAS bf16x8*)(lds + PG8_SA(b, h) + aoff + m * 2048 + k * 1024); } while (0)
; #define PG8_LDB(dst, b, h) do { _Pragma("unroll") for (int n = 0; n < 2; ++n) _Pragma("unroll") for (int k = 0; k < 2; ++k) dst[n][k] = *(const LAS bf16x8*)(lds + PG8_SB(b, h) + boff + n * 2048 + k * 1024); } while (0)
; #define PG8_MMA(ai, bj, At, Bt) do { __builtin_amdgcn_s_setprio(1); _Pragma("unroll") for (int m = 0; m < 4; ++m) _Pragma("unroll") for (int n = 0; n < 2; ++n) _Pragma("unroll") for (int k = 0; k < 2; ++k) \
;         acc[ai][bj][m][n] = __builtin_amdgcn_mfma_f32_16x16x32_bf16(Bt[n][k], At[m][k], acc[ai][bj][m][n], 0, 0, 0); __builtin_amdgcn_s_setprio(0); } while (0)
; #define PG8_WAIT_V(n) asm volatile("s_waitcnt vmcnt(" #n ")" ::: "memory")
; #define PG8_WAIT_L(n) asm volatile("s_waitcnt lgkmcnt(" #n ")" ::: "memory")
; #define PG8_BAR __builtin_amdgcn_s_barrier()
; #define PG8_SCHED __builtin_amdgcn_sched_barrier(0)
; template <class Epi>
; __device__ __forceinline__ void gemm_phase(LAS unsigned char* lds, const Gemm g, const TileOrder& S, const Epi& E) {
;     ...
;         for (int t = 0; t < nt; t += 2) {
;             const bool last = (t == nt - 2);
;             const char* a1 = cA + (size_t)(t + 1) * kstepA;
;             const char* a2 = last ? nA : cA + (size_t)(t + 2) * kstepA; const char* b2 = last ? nB : cB + (size_t)(t + 2) * kstep;
;             const char* a3 = a2 + kstepA; const char* b3 = b2 + kstep;
;             PG8_LDB(B0, 0, 0); PG8_LDB(B1, 0, 1); PG8_SCHED; PG8_LDA(At, 0, 0); PG8_STAGE(PG8_SA(1, 1), a1 + hstepA, voffA);
;             PG8_WAIT_V(8); PG8_WAIT_L(0); PG8_BAR; PG8_MMA(0, 0, At, B0); PG8_MMA(0, 1, At, B1); PG8_BAR; PG8_SCHED;
;             PG8_LDA(At, 0, 1); PG8_STAGE(PG8_SB(0, 0), b2, voffB); PG8_STAGE(PG8_SB(0, 1), b2 + hstepB, voffB); PG8_STAGE(PG8_SA(0, 0), a2, voffA);
;             PG8_WAIT_V(8); PG8_WAIT_L(0); PG8_BAR; PG8_MMA(1, 0, At, B0); PG8_MMA(1, 1, At, B1); PG8_BAR; PG8_SCHED;
.LBB0_835:
	s_mov_b32 s6, 0x10000
	s_mov_b32 s14, 0x14000
	v_add_u32_e32 v106, s6, v240
	v_add_u32_e32 v150, s14, v240
	ds_read_b128 v[74:77], v106
	ds_read_b128 v[86:89], v106 offset:1024
	ds_read_b128 v[98:101], v106 offset:2048
	ds_read_b128 v[106:109], v106 offset:3072
	ds_read_b128 v[122:125], v150
	ds_read_b128 v[126:129], v150 offset:1024
	ds_read_b128 v[142:145], v150 offset:2048
	ds_read_b128 v[150:153], v150 offset:3072
	ds_read_b128 v[154:157], v241
	ds_read_b128 v[166:169], v241 offset:1024
	ds_read_b128 v[170:173], v241 offset:2048
	ds_read_b128 v[174:177], v241 offset:3072
	ds_read_b128 v[178:181], v241 offset:4096
	ds_read_b128 v[182:185], v241 offset:5120
	ds_read_b128 v[186:189], v241 offset:6144
	ds_read_b128 v[200:203], v241 offset:7168
	s_add_u32 s2, s28, 0x4000
	s_addc_u32 s3, s29, 0
	s_cmpk_eq_i32 s72, 0x7c
	s_cselect_b32 s38, s43, s2
	s_cselect_b32 s39, s42, s3
	s_cselect_b32 s30, s51, s53
	s_cselect_b32 s31, s45, s71
	s_add_u32 s2, s38, 0x8000
	s_addc_u32 s3, s39, 0
	s_add_i32 m0, s60, 0xc000
	s_nop 0
	global_load_lds_dwordx4 v196, s[28:29]
	s_add_i32 m0, s60, 0xe000
	s_nop 0
	global_load_lds_dwordx4 v198, s[28:29]
	s_waitcnt vmcnt(8)
	s_waitcnt lgkmcnt(0)
	s_barrier
	s_setprio 1
	s_waitcnt lgkmcnt(0)
	v_mfma_f32_16x16x32_bf16 v[162:165], v[74:77], v[154:157], v[162:165]
	v_mfma_f32_16x16x32_bf16 v[158:161], v[98:101], v[154:157], v[158:161]
	v_mfma_f32_16x16x32_bf16 v[134:137], v[74:77], v[170:173], v[134:137]
	v_mfma_f32_16x16x32_bf16 v[130:133], v[98:101], v[170:173], v[130:133]
	v_mfma_f32_16x16x32_bf16 v[110:113], v[74:77], v[178:181], v[110:113]
	v_mfma_f32_16x16x32_bf16 v[102:105], v[98:101], v[178:181], v[102:105]
	v_mfma_f32_16x16x32_bf16 v[82:85], v[74:77], v[186:189], v[82:85]
	v_mfma_f32_16x16x32_bf16 v[78:81], v[98:101], v[186:189], v[78:81]
	v_mfma_f32_16x16x32_bf16 v[162:165], v[86:89], v[166:169], v[162:165]
	v_mfma_f32_16x16x32_bf16 v[158:161], v[106:109], v[166:169], v[158:161]
	v_mfma_f32_16x16x32_bf16 v[134:137], v[86:89], v[174:177], v[134:137]
	v_mfma_f32_16x16x32_bf16 v[130:133], v[106:109], v[174:177], v[130:133]
	v_mfma_f32_16x16x32_bf16 v[110:113], v[86:89], v[182:185], v[110:113]
	v_mfma_f32_16x16x32_bf16 v[102:105], v[106:109], v[182:185], v[102:105]
	v_mfma_f32_16x16x32_bf16 v[82:85], v[86:89], v[200:203], v[82:85]
	v_mfma_f32_16x16x32_bf16 v[78:81], v[106:109], v[200:203], v[78:81]
	s_setprio 0
	s_setprio 1
	v_mfma_f32_16x16x32_bf16 v[146:149], v[122:125], v[154:157], v[146:149]
	v_mfma_f32_16x16x32_bf16 v[138:141], v[142:145], v[154:157], v[138:141]
	v_mfma_f32_16x16x32_bf16 v[118:121], v[122:125], v[170:173], v[118:121]
	v_mfma_f32_16x16x32_bf16 v[114:117], v[142:145], v[170:173], v[114:117]
	v_mfma_f32_16x16x32_bf16 v[94:97], v[122:125], v[178:181], v[94:97]
	v_mfma_f32_16x16x32_bf16 v[90:93], v[142:145], v[178:181], v[90:93]
	v_mfma_f32_16x16x32_bf16 v[70:73], v[122:125], v[186:189], v[70:73]
	v_mfma_f32_16x16x32_bf16 v[66:69], v[142:145], v[186:189], v[66:69]
	v_mfma_f32_16x16x32_bf16 v[146:149], v[126:129], v[166:169], v[146:149]
	v_mfma_f32_16x16x32_bf16 v[138:141], v[150:153], v[166:169], v[138:141]
	v_mfma_f32_16x16x32_bf16 v[118:121], v[126:129], v[174:177], v[118:121]
	v_mfma_f32_16x16x32_bf16 v[114:117], v[150:153], v[174:177], v[114:117]
	v_mfma_f32_16x16x32_bf16 v[94:97], v[126:129], v[182:185], v[94:97]
	s_setprio 2
	s_barrier
	v_mfma_f32_16x16x32_bf16 v[90:93], v[150:153], v[182:185], v[90:93]
	v_mfma_f32_16x16x32_bf16 v[70:73], v[126:129], v[200:203], v[70:73]
	v_mfma_f32_16x16x32_bf16 v[66:69], v[150:153], v[200:203], v[66:69]
	s_setprio 0
	s_add_i32 s6, s6, s59
	v_lshl_add_u64 v[204:205], s[30:31], 0, v[0:1]
	s_mov_b32 m0, s6
	ds_read_b128 v[154:157], v241 offset:16384
	ds_read_b128 v[166:169], v241 offset:17408
	ds_read_b128 v[170:173], v241 offset:18432
	ds_read_b128 v[174:177], v241 offset:19456
	ds_read_b128 v[178:181], v241 offset:20480
	ds_read_b128 v[182:185], v241 offset:21504
	ds_read_b128 v[186:189], v241 offset:22528
	ds_read_b128 v[200:203], v241 offset:23552
	global_load_lds_dwordx4 v[204:205], off
	s_add_i32 m0, s6, 0x2000
	s_add_u32 s12, s30, 0x200000
	v_lshl_add_u64 v[206:207], s[30:31], 0, v[190:191]
	s_addc_u32 s13, s31, 0
	s_add_i32 s6, s14, s59
	global_load_lds_dwordx4 v[206:207], off
	s_mov_b32 m0, s6
	s_nop 0
	global_load_lds_dwordx4 v0, s[12:13]
	s_add_i32 m0, s6, 0x2000
	s_nop 0
	global_load_lds_dwordx4 v190, s[12:13]
	s_mov_b32 m0, s60
	s_nop 0
	global_load_lds_dwordx4 v194, s[38:39]
	s_mov_b32 m0, s61
	s_nop 0
	global_load_lds_dwordx4 v192, s[38:39]
	s_waitcnt vmcnt(8)
	s_waitcnt lgkmcnt(0)
	s_barrier
	s_setprio 1
	s_waitcnt lgkmcnt(0)
	v_mfma_f32_16x16x32_bf16 v[62:65], v[74:77], v[154:157], v[62:65]
	v_mfma_f32_16x16x32_bf16 v[58:61], v[98:101], v[154:157], v[58:61]
	v_mfma_f32_16x16x32_bf16 v[46:49], v[74:77], v[170:173], v[46:49]
	v_mfma_f32_16x16x32_bf16 v[42:45], v[98:101], v[170:173], v[42:45]
	v_mfma_f32_16x16x32_bf16 v[30:33], v[74:77], v[178:181], v[30:33]
	v_mfma_f32_16x16x32_bf16 v[26:29], v[98:101], v[178:181], v[26:29]
	v_mfma_f32_16x16x32_bf16 v[14:17], v[74:77], v[186:189], v[14:17]
	v_mfma_f32_16x16x32_bf16 v[10:13], v[98:101], v[186:189], v[10:13]
	v_mfma_f32_16x16x32_bf16 v[62:65], v[86:89], v[166:169], v[62:65]
	v_mfma_f32_16x16x32_bf16 v[58:61], v[106:109], v[166:169], v[58:61]
	v_mfma_f32_16x16x32_bf16 v[46:49], v[86:89], v[174:177], v[46:49]
	v_mfma_f32_16x16x32_bf16 v[42:45], v[106:109], v[174:177], v[42:45]
	v_mfma_f32_16x16x32_bf16 v[30:33], v[86:89], v[182:185], v[30:33]
	v_mfma_f32_16x16x32_bf16 v[26:29], v[106:109], v[182:185], v[26:29]
	v_mfma_f32_16x16x32_bf16 v[14:17], v[86:89], v[200:203], v[14:17]
	v_mfma_f32_16x16x32_bf16 v[10:13], v[106:109], v[200:203], v[10:13]
	s_setprio 0
	s_setprio 1
	v_mfma_f32_16x16x32_bf16 v[54:57], v[122:125], v[154:157], v[54:57]
	v_mfma_f32_16x16x32_bf16 v[50:53], v[142:145], v[154:157], v[50:53]
	v_mfma_f32_16x16x32_bf16 v[38:41], v[122:125], v[170:173], v[38:41]
	v_mfma_f32_16x16x32_bf16 v[34:37], v[142:145], v[170:173], v[34:37]
	v_mfma_f32_16x16x32_bf16 v[22:25], v[122:125], v[178:181], v[22:25]
	v_mfma_f32_16x16x32_bf16 v[18:21], v[142:145], v[178:181], v[18:21]
	v_mfma_f32_16x16x32_bf16 v[6:9], v[122:125], v[186:189], v[6:9]
	v_mfma_f32_16x16x32_bf16 v[2:5], v[142:145], v[186:189], v[2:5]
	v_mfma_f32_16x16x32_bf16 v[54:57], v[126:129], v[166:169], v[54:57]
	v_mfma_f32_16x16x32_bf16 v[50:53], v[150:153], v[166:169], v[50:53]
	v_mfma_f32_16x16x32_bf16 v[38:41], v[126:129], v[174:177], v[38:41]
	v_mfma_f32_16x16x32_bf16 v[34:37], v[150:153], v[174:177], v[34:37]
	v_mfma_f32_16x16x32_bf16 v[22:25], v[126:129], v[182:185], v[22:25]
	s_setprio 2
	s_barrier
; #define PG8_STAGE(bufoff, gbase, voff) do { _Pragma("unroll") for (int _i = 0; _i < 2; ++_i) \
;         __builtin_amdgcn_global_load_lds((const unsigned*)((const char*)(gbase) + (voff)[_i]), (LAS unsigned*)(lds + (bufoff) + ldsw + _i * 8192), 16, 0, 0); } while (0)
; #define PG8_LDA(dst, b, h) do { _Pragma("unroll") for (int m = 0; m < 4; ++m) _Pragma("unroll") for (int k = 0; k < 2; ++k) dst[m][k] = *(const LAS bf16x8*)(lds + PG8_SA(b, h) + aoff + m * 2048 + k * 1024); } while (0)
; #define PG8_LDB(dst, b, h) do { _Pragma("unroll") for (int n = 0; n < 2; ++n) _Pragma("unroll") for (int k = 0; k < 2; ++k) dst[n][k] = *(const LAS bf16x8*)(lds + PG8_SB(b, h) + boff + n * 2048 + k * 1024); } while (0)
; #define PG8_MMA(ai, bj, At, Bt) do { __builtin_amdgcn_s_setprio(1); _Pragma("unroll") for (int m = 0; m < 4; ++m) _Pragma("unroll") for (int n = 0; n < 2; ++n) _Pragma("unroll") for (int k = 0; k < 2; ++k) \
;         acc[ai][bj][m][n] = __builtin_amdgcn_mfma_f32_16x16x32_bf16(Bt[n][k], At[m][k], acc[ai][bj][m][n], 0, 0, 0); __builtin_amdgcn_s_setprio(0); } while (0)
; #define PG8_WAIT_V(n) asm volatile("s_waitcnt vmcnt(" #n ")" ::: "memory")
; #define PG8_WAIT_L(n) asm volatile("s_waitcnt lgkmcnt(" #n ")" ::: "memory")
; #define PG8_BAR __builtin_amdgcn_s_barrier()
; #define PG8_SCHED __builtin_amdgcn_sched_barrier(0)
; template <class Epi>
; __device__ __forceinline__ void gemm_phase(LAS unsigned char* lds, const Gemm g, const TileOrder& S, const Epi& E) {
;     ...
;             PG8_WAIT_V(8); PG8_WAIT_L(0); PG8_BAR; PG8_MMA(1, 0, At, B0); PG8_MMA(1, 1, At, B1); PG8_BAR; PG8_SCHED;
;             PG8_LDB(B0, 1, 0); PG8_LDB(B1, 1, 1); PG8_SCHED; PG8_LDA(At, 1, 0); PG8_STAGE(PG8_SA(0, 1), a2 + hstepA, voffA);
;             PG8_WAIT_V(8); PG8_WAIT_L(0); PG8_BAR; PG8_MMA(0, 0, At, B0); PG8_MMA(0, 1, At, B1); PG8_BAR; PG8_SCHED;
	v_mfma_f32_16x16x32_bf16 v[18:21], v[150:153], v[182:185], v[18:21]
	v_mfma_f32_16x16x32_bf16 v[6:9], v[126:129], v[200:203], v[6:9]
	v_mfma_f32_16x16x32_bf16 v[2:5], v[150:153], v[200:203], v[2:5]
	s_setprio 0
	s_add_i32 s6, 0, 0x18000
	s_add_i32 s14, 0, 0x1c000
	v_add_u32_e32 v106, s6, v240
	v_add_u32_e32 v150, s14, v240
	ds_read_b128 v[74:77], v106
	ds_read_b128 v[86:89], v106 offset:1024
	ds_read_b128 v[98:101], v106 offset:2048
	ds_read_b128 v[106:109], v106 offset:3072
	ds_read_b128 v[122:125], v150
	ds_read_b128 v[126:129], v150 offset:1024
	ds_read_b128 v[142:145], v150 offset:2048
	ds_read_b128 v[150:153], v150 offset:3072
	s_add_u32 s12, s38, 0x4000
	s_addc_u32 s13, s39, 0
	s_mov_b32 m0, s62
	ds_read_b128 v[154:157], v241 offset:32768
	ds_read_b128 v[166:169], v241 offset:33792
	ds_read_b128 v[170:173], v241 offset:34816
	ds_read_b128 v[174:177], v241 offset:35840
	ds_read_b128 v[178:181], v241 offset:36864
	ds_read_b128 v[182:185], v241 offset:37888
	ds_read_b128 v[186:189], v241 offset:38912
	ds_read_b128 v[200:203], v241 offset:39936
	global_load_lds_dwordx4 v194, s[12:13]
	s_mov_b32 m0, s63
	s_nop 0
	global_load_lds_dwordx4 v192, s[12:13]
	s_waitcnt vmcnt(8)
	s_waitcnt lgkmcnt(0)
	s_barrier
	s_setprio 1
	s_waitcnt lgkmcnt(0)
	v_mfma_f32_16x16x32_bf16 v[162:165], v[74:77], v[154:157], v[162:165]
	v_mfma_f32_16x16x32_bf16 v[158:161], v[98:101], v[154:157], v[158:161]
	v_mfma_f32_16x16x32_bf16 v[134:137], v[74:77], v[170:173], v[134:137]
	v_mfma_f32_16x16x32_bf16 v[130:133], v[98:101], v[170:173], v[130:133]
	v_mfma_f32_16x16x32_bf16 v[110:113], v[74:77], v[178:181], v[110:113]
	v_mfma_f32_16x16x32_bf16 v[102:105], v[98:101], v[178:181], v[102:105]
	v_mfma_f32_16x16x32_bf16 v[82:85], v[74:77], v[186:189], v[82:85]
	v_mfma_f32_16x16x32_bf16 v[78:81], v[98:101], v[186:189], v[78:81]
	v_mfma_f32_16x16x32_bf16 v[162:165], v[86:89], v[166:169], v[162:165]
	v_mfma_f32_16x16x32_bf16 v[158:161], v[106:109], v[166:169], v[158:161]
	v_mfma_f32_16x16x32_bf16 v[134:137], v[86:89], v[174:177], v[134:137]
	v_mfma_f32_16x16x32_bf16 v[130:133], v[106:109], v[174:177], v[130:133]
	v_mfma_f32_16x16x32_bf16 v[110:113], v[86:89], v[182:185], v[110:113]
	v_mfma_f32_16x16x32_bf16 v[102:105], v[106:109], v[182:185], v[102:105]
	v_mfma_f32_16x16x32_bf16 v[82:85], v[86:89], v[200:203], v[82:85]
	v_mfma_f32_16x16x32_bf16 v[78:81], v[106:109], v[200:203], v[78:81]
	s_setprio 0
	s_setprio 1
	v_mfma_f32_16x16x32_bf16 v[146:149], v[122:125], v[154:157], v[146:149]
	v_mfma_f32_16x16x32_bf16 v[138:141], v[142:145], v[154:157], v[138:141]
	v_mfma_f32_16x16x32_bf16 v[118:121], v[122:125], v[170:173], v[118:121]
	v_mfma_f32_16x16x32_bf16 v[114:117], v[142:145], v[170:173], v[114:117]
	v_mfma_f32_16x16x32_bf16 v[94:97], v[122:125], v[178:181], v[94:97]
	v_mfma_f32_16x16x32_bf16 v[90:93], v[142:145], v[178:181], v[90:93]
	v_mfma_f32_16x16x32_bf16 v[70:73], v[122:125], v[186:189], v[70:73]
	v_mfma_f32_16x16x32_bf16 v[66:69], v[142:145], v[186:189], v[66:69]
	v_mfma_f32_16x16x32_bf16 v[146:149], v[126:129], v[166:169], v[146:149]
	v_mfma_f32_16x16x32_bf16 v[138:141], v[150:153], v[166:169], v[138:141]
	v_mfma_f32_16x16x32_bf16 v[118:121], v[126:129], v[174:177], v[118:121]
	v_mfma_f32_16x16x32_bf16 v[114:117], v[150:153], v[174:177], v[114:117]
	v_mfma_f32_16x16x32_bf16 v[94:97], v[126:129], v[182:185], v[94:97]
	s_setprio 2
	s_barrier
; #define PG8_STAGE(bufoff, gbase, voff) do { _Pragma("unroll") for (int _i = 0; _i < 2; ++_i) \
;         __builtin_amdgcn_global_load_lds((const unsigned*)((const char*)(gbase) + (voff)[_i]), (LAS unsigned*)(lds + (bufoff) + ldsw + _i * 8192), 16, 0, 0); } while (0)
; #define PG8_LDA(dst, b, h) do { _Pragma("unroll") for (int m = 0; m < 4; ++m) _Pragma("unroll") for (int k = 0; k < 2; ++k) dst[m][k] = *(const LAS bf16x8*)(lds + PG8_SA(b, h) + aoff + m * 2048 + k * 1024); } while (0)
; #define PG8_MMA(ai, bj, At, Bt) do { __builtin_amdgcn_s_setprio(1); _Pragma("unroll") for (int m = 0; m < 4; ++m) _Pragma("unroll") for (int n = 0; n < 2; ++n) _Pragma("unroll") for (int k = 0; k < 2; ++k) \
;         acc[ai][bj][m][n] = __builtin_amdgcn_mfma_f32_16x16x32_bf16(Bt[n][k], At[m][k], acc[ai][bj][m][n], 0, 0, 0); __builtin_amdgcn_s_setprio(0); } while (0)
; #define PG8_WAIT_V(n) asm volatile("s_waitcnt vmcnt(" #n ")" ::: "memory")
; #define PG8_WAIT_L(n) asm volatile("s_waitcnt lgkmcnt(" #n ")" ::: "memory")
; #define PG8_BAR __builtin_amdgcn_s_barrier()
; #define PG8_SCHED __builtin_amdgcn_sched_barrier(0)
; template <class Epi>
; __device__ __forceinline__ void gemm_phase(LAS unsigned char* lds, const Gemm g, const TileOrder& S, const Epi& E) {
;     ...
;             PG8_WAIT_V(8); PG8_WAIT_L(0); PG8_BAR; PG8_MMA(0, 0, At, B0); PG8_MMA(0, 1, At, B1); PG8_BAR; PG8_SCHED;
;             PG8_LDA(At, 1, 1); PG8_STAGE(PG8_SB(1, 0), b3, voffB); PG8_STAGE(PG8_SB(1, 1), b3 + hstepB, voffB); PG8_STAGE(PG8_SA(1, 0), a3, voffA);
;             PG8_WAIT_V(8); PG8_WAIT_L(0); PG8_BAR; PG8_MMA(1, 0, At, B0); PG8_MMA(1, 1, At, B1); PG8_BAR; PG8_SCHED;
;         }
;         if (wr == 0) PG8_BAR;
	v_mfma_f32_16x16x32_bf16 v[90:93], v[150:153], v[182:185], v[90:93]
	v_mfma_f32_16x16x32_bf16 v[70:73], v[126:129], v[200:203], v[70:73]
	v_mfma_f32_16x16x32_bf16 v[66:69], v[150:153], v[200:203], v[66:69]
	s_setprio 0
	s_add_i32 s6, s6, s59
	v_lshl_add_u64 v[204:205], v[204:205], 0, s[34:35]
	s_mov_b32 m0, s6
	ds_read_b128 v[154:157], v241 offset:49152
	ds_read_b128 v[166:169], v241 offset:50176
	ds_read_b128 v[170:173], v241 offset:51200
	ds_read_b128 v[174:177], v241 offset:52224
	ds_read_b128 v[178:181], v241 offset:53248
	ds_read_b128 v[182:185], v241 offset:54272
	ds_read_b128 v[186:189], v241 offset:55296
	ds_read_b128 v[200:203], v241 offset:56320
	global_load_lds_dwordx4 v[204:205], off
	s_add_i32 m0, s6, 0x2000
	s_add_u32 s12, s30, 0x200080
	v_lshl_add_u64 v[204:205], v[206:207], 0, s[34:35]
	s_addc_u32 s13, s31, 0
	s_add_i32 s6, s14, s59
	global_load_lds_dwordx4 v[204:205], off
	s_mov_b32 m0, s6
	s_nop 0
	global_load_lds_dwordx4 v0, s[12:13]
	s_add_i32 m0, s6, 0x2000
	s_nop 0
	global_load_lds_dwordx4 v190, s[12:13]
	s_mov_b32 m0, s69
	s_nop 0
	global_load_lds_dwordx4 v194, s[2:3]
	s_mov_b32 m0, s70
	s_nop 0
	global_load_lds_dwordx4 v192, s[2:3]
	s_waitcnt vmcnt(8)
	s_waitcnt lgkmcnt(0)
	s_barrier
	s_setprio 1
	s_waitcnt lgkmcnt(0)
	v_mfma_f32_16x16x32_bf16 v[62:65], v[74:77], v[154:157], v[62:65]
	v_mfma_f32_16x16x32_bf16 v[58:61], v[98:101], v[154:157], v[58:61]
	v_mfma_f32_16x16x32_bf16 v[46:49], v[74:77], v[170:173], v[46:49]
	v_mfma_f32_16x16x32_bf16 v[42:45], v[98:101], v[170:173], v[42:45]
	v_mfma_f32_16x16x32_bf16 v[30:33], v[74:77], v[178:181], v[30:33]
	v_mfma_f32_16x16x32_bf16 v[26:29], v[98:101], v[178:181], v[26:29]
	v_mfma_f32_16x16x32_bf16 v[14:17], v[74:77], v[186:189], v[14:17]
	v_mfma_f32_16x16x32_bf16 v[10:13], v[98:101], v[186:189], v[10:13]
	v_mfma_f32_16x16x32_bf16 v[62:65], v[86:89], v[166:169], v[62:65]
	v_mfma_f32_16x16x32_bf16 v[58:61], v[106:109], v[166:169], v[58:61]
	v_mfma_f32_16x16x32_bf16 v[46:49], v[86:89], v[174:177], v[46:49]
	v_mfma_f32_16x16x32_bf16 v[42:45], v[106:109], v[174:177], v[42:45]
	v_mfma_f32_16x16x32_bf16 v[30:33], v[86:89], v[182:185], v[30:33]
	v_mfma_f32_16x16x32_bf16 v[26:29], v[106:109], v[182:185], v[26:29]
	v_mfma_f32_16x16x32_bf16 v[14:17], v[86:89], v[200:203], v[14:17]
	v_mfma_f32_16x16x32_bf16 v[10:13], v[106:109], v[200:203], v[10:13]
	s_setprio 0
	s_setprio 1
	v_mfma_f32_16x16x32_bf16 v[54:57], v[122:125], v[154:157], v[54:57]
	v_mfma_f32_16x16x32_bf16 v[50:53], v[142:145], v[154:157], v[50:53]
	v_mfma_f32_16x16x32_bf16 v[38:41], v[122:125], v[170:173], v[38:41]
	v_mfma_f32_16x16x32_bf16 v[34:37], v[142:145], v[170:173], v[34:37]
	v_mfma_f32_16x16x32_bf16 v[22:25], v[122:125], v[178:181], v[22:25]
	v_mfma_f32_16x16x32_bf16 v[18:21], v[142:145], v[178:181], v[18:21]
	v_mfma_f32_16x16x32_bf16 v[6:9], v[122:125], v[186:189], v[6:9]
	v_mfma_f32_16x16x32_bf16 v[2:5], v[142:145], v[186:189], v[2:5]
	v_mfma_f32_16x16x32_bf16 v[54:57], v[126:129], v[166:169], v[54:57]
	v_mfma_f32_16x16x32_bf16 v[50:53], v[150:153], v[166:169], v[50:53]
	v_mfma_f32_16x16x32_bf16 v[38:41], v[126:129], v[174:177], v[38:41]
	v_mfma_f32_16x16x32_bf16 v[34:37], v[150:153], v[174:177], v[34:37]
	v_mfma_f32_16x16x32_bf16 v[22:25], v[126:129], v[182:185], v[22:25]
	s_setprio 2
	s_barrier
	v_mfma_f32_16x16x32_bf16 v[18:21], v[150:153], v[182:185], v[18:21]
	v_mfma_f32_16x16x32_bf16 v[6:9], v[126:129], v[200:203], v[6:9]
	v_mfma_f32_16x16x32_bf16 v[2:5], v[150:153], v[200:203], v[2:5]
	s_setprio 0
	s_add_i32 s72, s72, 2
	s_add_u32 s53, s53, 0x100
	s_addc_u32 s71, s71, 0
	s_add_u32 s28, s28, 0x10000
	s_addc_u32 s29, s29, 0
	s_cmpk_gt_u32 s72, 0x7d
	s_cbranch_scc0 .LBB0_835
	s_and_b64 vcc, exec, s[46:47]
	s_cbranch_vccz .LBB0_838
	s_barrier
